# K-loop load segments (7 phases): four fragment ds_reads whose registers the tail MFMAs do not use are issued right after the early barrier, under the tail MFMAs
# baseline (speedup 1.0000x reference)
.LBB0_322:
	s_ashr_i32 s43, s42, 31
	s_lshl_b64 s[46:47], s[42:43], 19
	s_add_u32 s46, s12, s46
	s_addc_u32 s47, s13, s47
	s_and_b64 s[48:49], s[4:5], exec
	s_cselect_b32 s18, s47, s7
	s_cselect_b32 s43, s46, s6
	s_ashr_i32 s45, s44, 31
	s_lshl_b64 s[48:49], s[44:45], 19
	s_add_u32 s48, s59, s48
	s_addc_u32 s49, s60, s49
	s_and_b64 s[50:51], s[4:5], exec
	s_cselect_b32 s45, s49, s9
	s_cselect_b32 s55, s48, s8
	s_add_u32 s6, s6, 0x40080
	s_addc_u32 s7, s7, 0
	s_add_u32 s56, s8, 0x100
	s_addc_u32 s57, s9, 0
	s_mov_b32 s78, -2
	ds_read_b128 v[96:99], v209
	ds_read_b128 v[100:103], v209 offset:1024
	ds_read_b128 v[120:123], v209 offset:2048
	ds_read_b128 v[124:127], v209 offset:3072
	ds_read_b128 v[144:147], v210
	ds_read_b128 v[148:151], v210 offset:1024
	ds_read_b128 v[152:155], v210 offset:2048
	ds_read_b128 v[156:159], v210 offset:3072
	s_add_u32 s8, s6, 0xfffc0080
	s_addc_u32 s9, s7, -1
	s_cmp_eq_u32 s78, 12
	s_cselect_b32 s51, s18, s9
	s_cselect_b32 s50, s43, s8
	s_cselect_b32 s9, s45, s57
	s_cselect_b32 s8, s55, s56
	v_lshl_add_u64 v[206:207], s[6:7], 0, v[170:171]
	s_add_i32 m0, s17, 0xc000
	ds_read_b128 v[178:181], v211
	ds_read_b128 v[182:185], v211 offset:1024
	ds_read_b128 v[186:189], v211 offset:2048
	ds_read_b128 v[190:193], v211 offset:3072
	ds_read_b128 v[194:197], v211 offset:4096
	ds_read_b128 v[198:201], v211 offset:5120
	ds_read_b128 v[202:205], v211 offset:6144
	ds_read_b128 v[218:221], v211 offset:7168
	global_load_lds_dwordx4 v[206:207], off
	s_add_i32 m0, s17, 0xe000
	v_lshl_add_u64 v[206:207], s[6:7], 0, v[172:173]
	global_load_lds_dwordx4 v[206:207], off
	s_waitcnt vmcnt(8) lgkmcnt(0)
	s_barrier
	s_setprio 1
	v_mfma_f32_16x16x32_bf16 v[140:143], v[96:99], v[178:181], 0
	v_mfma_f32_16x16x32_bf16 v[140:143], v[100:103], v[182:185], v[140:143]
	v_mfma_f32_16x16x32_bf16 v[116:119], v[100:103], v[190:193], 0
	v_mfma_f32_16x16x32_bf16 v[116:119], v[96:99], v[186:189], v[116:119]
	v_mfma_f32_16x16x32_bf16 v[92:95], v[96:99], v[194:197], 0
	v_mfma_f32_16x16x32_bf16 v[92:95], v[100:103], v[198:201], v[92:95]
	v_mfma_f32_16x16x32_bf16 v[76:79], v[100:103], v[218:221], 0
	v_mfma_f32_16x16x32_bf16 v[76:79], v[96:99], v[202:205], v[76:79]
	v_mfma_f32_16x16x32_bf16 v[136:139], v[120:123], v[178:181], 0
	v_mfma_f32_16x16x32_bf16 v[136:139], v[124:127], v[182:185], v[136:139]
	v_mfma_f32_16x16x32_bf16 v[112:115], v[124:127], v[190:193], 0
	v_mfma_f32_16x16x32_bf16 v[112:115], v[120:123], v[186:189], v[112:115]
	v_mfma_f32_16x16x32_bf16 v[88:91], v[120:123], v[194:197], 0
	v_mfma_f32_16x16x32_bf16 v[88:91], v[124:127], v[198:201], v[88:91]
	v_mfma_f32_16x16x32_bf16 v[72:75], v[124:127], v[218:221], 0
	v_mfma_f32_16x16x32_bf16 v[72:75], v[120:123], v[202:205], v[72:75]
	v_mfma_f32_16x16x32_bf16 v[132:135], v[144:147], v[178:181], 0
	v_mfma_f32_16x16x32_bf16 v[132:135], v[148:151], v[182:185], v[132:135]
	v_mfma_f32_16x16x32_bf16 v[108:111], v[148:151], v[190:193], 0
	v_mfma_f32_16x16x32_bf16 v[108:111], v[144:147], v[186:189], v[108:111]
	v_mfma_f32_16x16x32_bf16 v[84:87], v[144:147], v[194:197], 0
	v_mfma_f32_16x16x32_bf16 v[84:87], v[148:151], v[198:201], v[84:87]
	v_mfma_f32_16x16x32_bf16 v[68:71], v[148:151], v[218:221], 0
	v_mfma_f32_16x16x32_bf16 v[68:71], v[144:147], v[202:205], v[68:71]
	v_mfma_f32_16x16x32_bf16 v[128:131], v[152:155], v[178:181], 0
	v_mfma_f32_16x16x32_bf16 v[128:131], v[156:159], v[182:185], v[128:131]
	v_mfma_f32_16x16x32_bf16 v[104:107], v[156:159], v[190:193], 0
	v_mfma_f32_16x16x32_bf16 v[104:107], v[152:155], v[186:189], v[104:107]
	s_setprio 2
	s_barrier
	ds_read_b128 v[178:181], v211 offset:16384
	ds_read_b128 v[182:185], v211 offset:17408
	ds_read_b128 v[186:189], v211 offset:18432
	ds_read_b128 v[190:193], v211 offset:19456
	v_mfma_f32_16x16x32_bf16 v[80:83], v[152:155], v[194:197], 0
	v_mfma_f32_16x16x32_bf16 v[80:83], v[156:159], v[198:201], v[80:83]
	v_mfma_f32_16x16x32_bf16 v[64:67], v[156:159], v[218:221], 0
	v_mfma_f32_16x16x32_bf16 v[64:67], v[152:155], v[202:205], v[64:67]
	s_setprio 2
	s_add_i32 s79, s73, s61
	v_lshl_add_u64 v[206:207], s[8:9], 0, v[162:163]
	s_mov_b32 m0, s79
	ds_read_b128 v[194:197], v211 offset:20480
	ds_read_b128 v[198:201], v211 offset:21504
	ds_read_b128 v[202:205], v211 offset:22528
	ds_read_b128 v[218:221], v211 offset:23552
	global_load_lds_dwordx4 v[206:207], off
	s_add_i32 m0, s79, 0x2000
	s_add_u32 s80, s8, 0x40000
	v_lshl_add_u64 v[222:223], s[8:9], 0, v[166:167]
	s_addc_u32 s81, s9, 0
	s_add_i32 s79, s74, s61
	global_load_lds_dwordx4 v[222:223], off
	v_lshl_add_u64 v[224:225], s[80:81], 0, v[162:163]
	s_mov_b32 m0, s79
	v_lshl_add_u64 v[226:227], s[50:51], 0, v[164:165]
	global_load_lds_dwordx4 v[224:225], off
	s_add_i32 m0, s79, 0x2000
	v_lshl_add_u64 v[224:225], s[80:81], 0, v[166:167]
	global_load_lds_dwordx4 v[224:225], off
	s_mov_b32 m0, s17
	v_lshl_add_u64 v[224:225], s[50:51], 0, v[160:161]
	global_load_lds_dwordx4 v[224:225], off
	s_mov_b32 m0, s62
	s_nop 0
	global_load_lds_dwordx4 v[226:227], off
	s_waitcnt vmcnt(8) lgkmcnt(0)
	s_barrier
	s_setprio 1
	v_mfma_f32_16x16x32_bf16 v[60:63], v[96:99], v[178:181], 0
	v_mfma_f32_16x16x32_bf16 v[60:63], v[100:103], v[182:185], v[60:63]
	v_mfma_f32_16x16x32_bf16 v[44:47], v[100:103], v[190:193], 0
	v_mfma_f32_16x16x32_bf16 v[44:47], v[96:99], v[186:189], v[44:47]
	v_mfma_f32_16x16x32_bf16 v[28:31], v[96:99], v[194:197], 0
	v_mfma_f32_16x16x32_bf16 v[28:31], v[100:103], v[198:201], v[28:31]
	v_mfma_f32_16x16x32_bf16 v[12:15], v[100:103], v[218:221], 0
	v_mfma_f32_16x16x32_bf16 v[12:15], v[96:99], v[202:205], v[12:15]
	v_mfma_f32_16x16x32_bf16 v[56:59], v[120:123], v[178:181], 0
	v_mfma_f32_16x16x32_bf16 v[56:59], v[124:127], v[182:185], v[56:59]
	v_mfma_f32_16x16x32_bf16 v[40:43], v[124:127], v[190:193], 0
	v_mfma_f32_16x16x32_bf16 v[40:43], v[120:123], v[186:189], v[40:43]
	v_mfma_f32_16x16x32_bf16 v[24:27], v[120:123], v[194:197], 0
	v_mfma_f32_16x16x32_bf16 v[24:27], v[124:127], v[198:201], v[24:27]
	v_mfma_f32_16x16x32_bf16 v[8:11], v[124:127], v[218:221], 0
	v_mfma_f32_16x16x32_bf16 v[8:11], v[120:123], v[202:205], v[8:11]
	v_mfma_f32_16x16x32_bf16 v[52:55], v[144:147], v[178:181], 0
	v_mfma_f32_16x16x32_bf16 v[52:55], v[148:151], v[182:185], v[52:55]
	v_mfma_f32_16x16x32_bf16 v[36:39], v[148:151], v[190:193], 0
	v_mfma_f32_16x16x32_bf16 v[36:39], v[144:147], v[186:189], v[36:39]
	v_mfma_f32_16x16x32_bf16 v[20:23], v[144:147], v[194:197], 0
	v_mfma_f32_16x16x32_bf16 v[20:23], v[148:151], v[198:201], v[20:23]
	v_mfma_f32_16x16x32_bf16 v[4:7], v[148:151], v[218:221], 0
	v_mfma_f32_16x16x32_bf16 v[4:7], v[144:147], v[202:205], v[4:7]
	v_mfma_f32_16x16x32_bf16 v[48:51], v[152:155], v[178:181], 0
	v_mfma_f32_16x16x32_bf16 v[48:51], v[156:159], v[182:185], v[48:51]
	v_mfma_f32_16x16x32_bf16 v[32:35], v[156:159], v[190:193], 0
	v_mfma_f32_16x16x32_bf16 v[32:35], v[152:155], v[186:189], v[32:35]
	s_setprio 2
	s_barrier
	ds_read_b128 v[178:181], v211 offset:32768
	ds_read_b128 v[182:185], v211 offset:33792
	ds_read_b128 v[186:189], v211 offset:34816
	ds_read_b128 v[190:193], v211 offset:35840
	v_mfma_f32_16x16x32_bf16 v[16:19], v[152:155], v[194:197], 0
	v_mfma_f32_16x16x32_bf16 v[16:19], v[156:159], v[198:201], v[16:19]
	v_mfma_f32_16x16x32_bf16 v[0:3], v[156:159], v[218:221], 0
	v_mfma_f32_16x16x32_bf16 v[0:3], v[152:155], v[202:205], v[0:3]
	s_setprio 0
	s_add_i32 s79, 0, 0x18000
	s_add_i32 s80, 0, 0x1c000
	v_add_u32_e32 v124, s79, v208
	v_add_u32_e32 v156, s80, v208
	ds_read_b128 v[96:99], v124
	ds_read_b128 v[100:103], v124 offset:1024
	ds_read_b128 v[120:123], v124 offset:2048
	ds_read_b128 v[124:127], v124 offset:3072
	ds_read_b128 v[144:147], v156
	ds_read_b128 v[148:151], v156 offset:1024
	ds_read_b128 v[152:155], v156 offset:2048
	ds_read_b128 v[156:159], v156 offset:3072
	s_add_u32 s50, s50, 0x40000
	s_addc_u32 s51, s51, 0
	s_mov_b32 m0, s63
	v_lshl_add_u64 v[228:229], s[50:51], 0, v[160:161]
	ds_read_b128 v[194:197], v211 offset:36864
	ds_read_b128 v[198:201], v211 offset:37888
	ds_read_b128 v[202:205], v211 offset:38912
	ds_read_b128 v[218:221], v211 offset:39936
	global_load_lds_dwordx4 v[228:229], off
	s_mov_b32 m0, s64
	v_lshl_add_u64 v[228:229], s[50:51], 0, v[164:165]
	global_load_lds_dwordx4 v[228:229], off
	s_waitcnt vmcnt(8) lgkmcnt(0)
	s_barrier
	s_setprio 1
	v_mfma_f32_16x16x32_bf16 v[140:143], v[96:99], v[178:181], v[140:143]
	v_mfma_f32_16x16x32_bf16 v[140:143], v[100:103], v[182:185], v[140:143]
	v_mfma_f32_16x16x32_bf16 v[116:119], v[100:103], v[190:193], v[116:119]
	v_mfma_f32_16x16x32_bf16 v[116:119], v[96:99], v[186:189], v[116:119]
	v_mfma_f32_16x16x32_bf16 v[92:95], v[96:99], v[194:197], v[92:95]
	v_mfma_f32_16x16x32_bf16 v[92:95], v[100:103], v[198:201], v[92:95]
	v_mfma_f32_16x16x32_bf16 v[76:79], v[100:103], v[218:221], v[76:79]
	v_mfma_f32_16x16x32_bf16 v[76:79], v[96:99], v[202:205], v[76:79]
	v_mfma_f32_16x16x32_bf16 v[136:139], v[120:123], v[178:181], v[136:139]
	v_mfma_f32_16x16x32_bf16 v[136:139], v[124:127], v[182:185], v[136:139]
	v_mfma_f32_16x16x32_bf16 v[112:115], v[124:127], v[190:193], v[112:115]
	v_mfma_f32_16x16x32_bf16 v[112:115], v[120:123], v[186:189], v[112:115]
	v_mfma_f32_16x16x32_bf16 v[88:91], v[120:123], v[194:197], v[88:91]
	v_mfma_f32_16x16x32_bf16 v[88:91], v[124:127], v[198:201], v[88:91]
	v_mfma_f32_16x16x32_bf16 v[72:75], v[124:127], v[218:221], v[72:75]
	v_mfma_f32_16x16x32_bf16 v[72:75], v[120:123], v[202:205], v[72:75]
	v_mfma_f32_16x16x32_bf16 v[132:135], v[144:147], v[178:181], v[132:135]
	v_mfma_f32_16x16x32_bf16 v[132:135], v[148:151], v[182:185], v[132:135]
	v_mfma_f32_16x16x32_bf16 v[108:111], v[148:151], v[190:193], v[108:111]
	v_mfma_f32_16x16x32_bf16 v[108:111], v[144:147], v[186:189], v[108:111]
	v_mfma_f32_16x16x32_bf16 v[84:87], v[144:147], v[194:197], v[84:87]
	v_mfma_f32_16x16x32_bf16 v[84:87], v[148:151], v[198:201], v[84:87]
	v_mfma_f32_16x16x32_bf16 v[68:71], v[148:151], v[218:221], v[68:71]
	v_mfma_f32_16x16x32_bf16 v[68:71], v[144:147], v[202:205], v[68:71]
	v_mfma_f32_16x16x32_bf16 v[128:131], v[152:155], v[178:181], v[128:131]
	v_mfma_f32_16x16x32_bf16 v[128:131], v[156:159], v[182:185], v[128:131]
	v_mfma_f32_16x16x32_bf16 v[104:107], v[156:159], v[190:193], v[104:107]
	v_mfma_f32_16x16x32_bf16 v[104:107], v[152:155], v[186:189], v[104:107]
	s_setprio 2
	s_barrier
	ds_read_b128 v[178:181], v211 offset:49152
	ds_read_b128 v[182:185], v211 offset:50176
	ds_read_b128 v[186:189], v211 offset:51200
	ds_read_b128 v[190:193], v211 offset:52224
	v_mfma_f32_16x16x32_bf16 v[80:83], v[152:155], v[194:197], v[80:83]
	v_mfma_f32_16x16x32_bf16 v[80:83], v[156:159], v[198:201], v[80:83]
	v_mfma_f32_16x16x32_bf16 v[64:67], v[156:159], v[218:221], v[64:67]
	v_mfma_f32_16x16x32_bf16 v[64:67], v[152:155], v[202:205], v[64:67]
	s_setprio 2
	s_add_i32 s50, s79, s61
	v_lshl_add_u64 v[206:207], v[206:207], 0, s[36:37]
	s_mov_b32 m0, s50
	ds_read_b128 v[194:197], v211 offset:53248
	ds_read_b128 v[198:201], v211 offset:54272
	ds_read_b128 v[202:205], v211 offset:55296
	ds_read_b128 v[218:221], v211 offset:56320
	global_load_lds_dwordx4 v[206:207], off
	s_add_i32 m0, s50, 0x2000
	s_add_u32 s8, s8, 0x40080
	v_lshl_add_u64 v[206:207], v[222:223], 0, s[36:37]
	s_addc_u32 s9, s9, 0
	s_add_i32 s50, s80, s61
	global_load_lds_dwordx4 v[206:207], off
	s_mov_b32 m0, s50
	v_lshl_add_u64 v[206:207], s[8:9], 0, v[162:163]
	global_load_lds_dwordx4 v[206:207], off
	s_add_i32 m0, s50, 0x2000
	v_lshl_add_u64 v[206:207], s[8:9], 0, v[166:167]
	global_load_lds_dwordx4 v[206:207], off
	s_mov_b32 m0, s68
	v_lshl_add_u64 v[206:207], v[224:225], 0, s[36:37]
	global_load_lds_dwordx4 v[206:207], off
	s_mov_b32 m0, s69
	v_lshl_add_u64 v[206:207], v[226:227], 0, s[36:37]
	global_load_lds_dwordx4 v[206:207], off
	s_waitcnt vmcnt(8) lgkmcnt(0)
	s_barrier
	s_setprio 1
	v_mfma_f32_16x16x32_bf16 v[60:63], v[96:99], v[178:181], v[60:63]
	v_mfma_f32_16x16x32_bf16 v[60:63], v[100:103], v[182:185], v[60:63]
	v_mfma_f32_16x16x32_bf16 v[44:47], v[100:103], v[190:193], v[44:47]
	v_mfma_f32_16x16x32_bf16 v[44:47], v[96:99], v[186:189], v[44:47]
	v_mfma_f32_16x16x32_bf16 v[28:31], v[96:99], v[194:197], v[28:31]
	v_mfma_f32_16x16x32_bf16 v[28:31], v[100:103], v[198:201], v[28:31]
	v_mfma_f32_16x16x32_bf16 v[12:15], v[100:103], v[218:221], v[12:15]
	v_mfma_f32_16x16x32_bf16 v[12:15], v[96:99], v[202:205], v[12:15]
	v_mfma_f32_16x16x32_bf16 v[56:59], v[120:123], v[178:181], v[56:59]
	v_mfma_f32_16x16x32_bf16 v[56:59], v[124:127], v[182:185], v[56:59]
	v_mfma_f32_16x16x32_bf16 v[40:43], v[124:127], v[190:193], v[40:43]
	v_mfma_f32_16x16x32_bf16 v[40:43], v[120:123], v[186:189], v[40:43]
	v_mfma_f32_16x16x32_bf16 v[24:27], v[120:123], v[194:197], v[24:27]
	v_mfma_f32_16x16x32_bf16 v[24:27], v[124:127], v[198:201], v[24:27]
	v_mfma_f32_16x16x32_bf16 v[8:11], v[124:127], v[218:221], v[8:11]
	v_mfma_f32_16x16x32_bf16 v[8:11], v[120:123], v[202:205], v[8:11]
	v_mfma_f32_16x16x32_bf16 v[52:55], v[144:147], v[178:181], v[52:55]
	v_mfma_f32_16x16x32_bf16 v[52:55], v[148:151], v[182:185], v[52:55]
	v_mfma_f32_16x16x32_bf16 v[36:39], v[148:151], v[190:193], v[36:39]
	v_mfma_f32_16x16x32_bf16 v[36:39], v[144:147], v[186:189], v[36:39]
	v_mfma_f32_16x16x32_bf16 v[20:23], v[144:147], v[194:197], v[20:23]
	v_mfma_f32_16x16x32_bf16 v[20:23], v[148:151], v[198:201], v[20:23]
	v_mfma_f32_16x16x32_bf16 v[4:7], v[148:151], v[218:221], v[4:7]
	v_mfma_f32_16x16x32_bf16 v[4:7], v[144:147], v[202:205], v[4:7]
	v_mfma_f32_16x16x32_bf16 v[48:51], v[152:155], v[178:181], v[48:51]
	v_mfma_f32_16x16x32_bf16 v[48:51], v[156:159], v[182:185], v[48:51]
	v_mfma_f32_16x16x32_bf16 v[32:35], v[156:159], v[190:193], v[32:35]
	v_mfma_f32_16x16x32_bf16 v[32:35], v[152:155], v[186:189], v[32:35]
	s_setprio 2
	s_barrier
	v_mfma_f32_16x16x32_bf16 v[16:19], v[152:155], v[194:197], v[16:19]
	v_mfma_f32_16x16x32_bf16 v[16:19], v[156:159], v[198:201], v[16:19]
	v_mfma_f32_16x16x32_bf16 v[0:3], v[156:159], v[218:221], v[0:3]
	v_mfma_f32_16x16x32_bf16 v[0:3], v[152:155], v[202:205], v[0:3]
	s_setprio 0
	s_add_i32 s78, s78, 2
	s_add_u32 s6, s6, 0x100
	s_addc_u32 s7, s7, 0
	s_add_u32 s56, s56, 0x100
	s_addc_u32 s57, s57, 0
	s_cmp_gt_u32 s78, 13
.LBB0_323:
	ds_read_b128 v[96:99], v209
	ds_read_b128 v[100:103], v209 offset:1024
	ds_read_b128 v[120:123], v209 offset:2048
	ds_read_b128 v[124:127], v209 offset:3072
	ds_read_b128 v[144:147], v210
	ds_read_b128 v[148:151], v210 offset:1024
	ds_read_b128 v[152:155], v210 offset:2048
	ds_read_b128 v[156:159], v210 offset:3072
	s_add_u32 s8, s6, 0xfffc0080
	s_addc_u32 s9, s7, -1
	s_cmp_eq_u32 s78, 12
	s_cselect_b32 s51, s18, s9
	s_cselect_b32 s50, s43, s8
	s_cselect_b32 s9, s45, s57
	s_cselect_b32 s8, s55, s56
	v_lshl_add_u64 v[206:207], s[6:7], 0, v[170:171]
	s_add_i32 m0, s17, 0xc000
	ds_read_b128 v[178:181], v211
	ds_read_b128 v[182:185], v211 offset:1024
	ds_read_b128 v[186:189], v211 offset:2048
	ds_read_b128 v[190:193], v211 offset:3072
	ds_read_b128 v[194:197], v211 offset:4096
	ds_read_b128 v[198:201], v211 offset:5120
	ds_read_b128 v[202:205], v211 offset:6144
	ds_read_b128 v[218:221], v211 offset:7168
	global_load_lds_dwordx4 v[206:207], off
	s_add_i32 m0, s17, 0xe000
	v_lshl_add_u64 v[206:207], s[6:7], 0, v[172:173]
	global_load_lds_dwordx4 v[206:207], off
	s_waitcnt vmcnt(8) lgkmcnt(0)
	s_barrier
	s_setprio 1
	v_mfma_f32_16x16x32_bf16 v[140:143], v[96:99], v[178:181], v[140:143]
	v_mfma_f32_16x16x32_bf16 v[140:143], v[100:103], v[182:185], v[140:143]
	v_mfma_f32_16x16x32_bf16 v[116:119], v[100:103], v[190:193], v[116:119]
	v_mfma_f32_16x16x32_bf16 v[116:119], v[96:99], v[186:189], v[116:119]
	v_mfma_f32_16x16x32_bf16 v[92:95], v[96:99], v[194:197], v[92:95]
	v_mfma_f32_16x16x32_bf16 v[92:95], v[100:103], v[198:201], v[92:95]
	v_mfma_f32_16x16x32_bf16 v[76:79], v[100:103], v[218:221], v[76:79]
	v_mfma_f32_16x16x32_bf16 v[76:79], v[96:99], v[202:205], v[76:79]
	v_mfma_f32_16x16x32_bf16 v[136:139], v[120:123], v[178:181], v[136:139]
	v_mfma_f32_16x16x32_bf16 v[136:139], v[124:127], v[182:185], v[136:139]
	v_mfma_f32_16x16x32_bf16 v[112:115], v[124:127], v[190:193], v[112:115]
	v_mfma_f32_16x16x32_bf16 v[112:115], v[120:123], v[186:189], v[112:115]
	v_mfma_f32_16x16x32_bf16 v[88:91], v[120:123], v[194:197], v[88:91]
	v_mfma_f32_16x16x32_bf16 v[88:91], v[124:127], v[198:201], v[88:91]
	v_mfma_f32_16x16x32_bf16 v[72:75], v[124:127], v[218:221], v[72:75]
	v_mfma_f32_16x16x32_bf16 v[72:75], v[120:123], v[202:205], v[72:75]
	v_mfma_f32_16x16x32_bf16 v[132:135], v[144:147], v[178:181], v[132:135]
	v_mfma_f32_16x16x32_bf16 v[132:135], v[148:151], v[182:185], v[132:135]
	v_mfma_f32_16x16x32_bf16 v[108:111], v[148:151], v[190:193], v[108:111]
	v_mfma_f32_16x16x32_bf16 v[108:111], v[144:147], v[186:189], v[108:111]
	v_mfma_f32_16x16x32_bf16 v[84:87], v[144:147], v[194:197], v[84:87]
	v_mfma_f32_16x16x32_bf16 v[84:87], v[148:151], v[198:201], v[84:87]
	v_mfma_f32_16x16x32_bf16 v[68:71], v[148:151], v[218:221], v[68:71]
	v_mfma_f32_16x16x32_bf16 v[68:71], v[144:147], v[202:205], v[68:71]
	v_mfma_f32_16x16x32_bf16 v[128:131], v[152:155], v[178:181], v[128:131]
	v_mfma_f32_16x16x32_bf16 v[128:131], v[156:159], v[182:185], v[128:131]
	v_mfma_f32_16x16x32_bf16 v[104:107], v[156:159], v[190:193], v[104:107]
	v_mfma_f32_16x16x32_bf16 v[104:107], v[152:155], v[186:189], v[104:107]
	s_setprio 2
	s_barrier
	ds_read_b128 v[178:181], v211 offset:16384
	ds_read_b128 v[182:185], v211 offset:17408
	ds_read_b128 v[186:189], v211 offset:18432
	ds_read_b128 v[190:193], v211 offset:19456
	v_mfma_f32_16x16x32_bf16 v[80:83], v[152:155], v[194:197], v[80:83]
	v_mfma_f32_16x16x32_bf16 v[80:83], v[156:159], v[198:201], v[80:83]
	v_mfma_f32_16x16x32_bf16 v[64:67], v[156:159], v[218:221], v[64:67]
	v_mfma_f32_16x16x32_bf16 v[64:67], v[152:155], v[202:205], v[64:67]
	s_setprio 2
	s_add_i32 s79, s73, s61
	v_lshl_add_u64 v[206:207], s[8:9], 0, v[162:163]
	s_mov_b32 m0, s79
	ds_read_b128 v[194:197], v211 offset:20480
	ds_read_b128 v[198:201], v211 offset:21504
	ds_read_b128 v[202:205], v211 offset:22528
	ds_read_b128 v[218:221], v211 offset:23552
	global_load_lds_dwordx4 v[206:207], off
	s_add_i32 m0, s79, 0x2000
	s_add_u32 s80, s8, 0x40000
	v_lshl_add_u64 v[222:223], s[8:9], 0, v[166:167]
	s_addc_u32 s81, s9, 0
	s_add_i32 s79, s74, s61
	global_load_lds_dwordx4 v[222:223], off
	v_lshl_add_u64 v[224:225], s[80:81], 0, v[162:163]
	s_mov_b32 m0, s79
	v_lshl_add_u64 v[226:227], s[50:51], 0, v[164:165]
	global_load_lds_dwordx4 v[224:225], off
	s_add_i32 m0, s79, 0x2000
	v_lshl_add_u64 v[224:225], s[80:81], 0, v[166:167]
	global_load_lds_dwordx4 v[224:225], off
	s_mov_b32 m0, s17
	v_lshl_add_u64 v[224:225], s[50:51], 0, v[160:161]
	global_load_lds_dwordx4 v[224:225], off
	s_mov_b32 m0, s62
	s_nop 0
	global_load_lds_dwordx4 v[226:227], off
	s_waitcnt vmcnt(8) lgkmcnt(0)
	s_barrier
	s_setprio 1
	v_mfma_f32_16x16x32_bf16 v[60:63], v[96:99], v[178:181], v[60:63]
	v_mfma_f32_16x16x32_bf16 v[60:63], v[100:103], v[182:185], v[60:63]
	v_mfma_f32_16x16x32_bf16 v[44:47], v[100:103], v[190:193], v[44:47]
	v_mfma_f32_16x16x32_bf16 v[44:47], v[96:99], v[186:189], v[44:47]
	v_mfma_f32_16x16x32_bf16 v[28:31], v[96:99], v[194:197], v[28:31]
	v_mfma_f32_16x16x32_bf16 v[28:31], v[100:103], v[198:201], v[28:31]
	v_mfma_f32_16x16x32_bf16 v[12:15], v[100:103], v[218:221], v[12:15]
	v_mfma_f32_16x16x32_bf16 v[12:15], v[96:99], v[202:205], v[12:15]
	v_mfma_f32_16x16x32_bf16 v[56:59], v[120:123], v[178:181], v[56:59]
	v_mfma_f32_16x16x32_bf16 v[56:59], v[124:127], v[182:185], v[56:59]
	v_mfma_f32_16x16x32_bf16 v[40:43], v[124:127], v[190:193], v[40:43]
	v_mfma_f32_16x16x32_bf16 v[40:43], v[120:123], v[186:189], v[40:43]
	v_mfma_f32_16x16x32_bf16 v[24:27], v[120:123], v[194:197], v[24:27]
	v_mfma_f32_16x16x32_bf16 v[24:27], v[124:127], v[198:201], v[24:27]
	v_mfma_f32_16x16x32_bf16 v[8:11], v[124:127], v[218:221], v[8:11]
	v_mfma_f32_16x16x32_bf16 v[8:11], v[120:123], v[202:205], v[8:11]
	v_mfma_f32_16x16x32_bf16 v[52:55], v[144:147], v[178:181], v[52:55]
	v_mfma_f32_16x16x32_bf16 v[52:55], v[148:151], v[182:185], v[52:55]
	v_mfma_f32_16x16x32_bf16 v[36:39], v[148:151], v[190:193], v[36:39]
	v_mfma_f32_16x16x32_bf16 v[36:39], v[144:147], v[186:189], v[36:39]
	v_mfma_f32_16x16x32_bf16 v[20:23], v[144:147], v[194:197], v[20:23]
	v_mfma_f32_16x16x32_bf16 v[20:23], v[148:151], v[198:201], v[20:23]
	v_mfma_f32_16x16x32_bf16 v[4:7], v[148:151], v[218:221], v[4:7]
	v_mfma_f32_16x16x32_bf16 v[4:7], v[144:147], v[202:205], v[4:7]
	v_mfma_f32_16x16x32_bf16 v[48:51], v[152:155], v[178:181], v[48:51]
	v_mfma_f32_16x16x32_bf16 v[48:51], v[156:159], v[182:185], v[48:51]
	v_mfma_f32_16x16x32_bf16 v[32:35], v[156:159], v[190:193], v[32:35]
	v_mfma_f32_16x16x32_bf16 v[32:35], v[152:155], v[186:189], v[32:35]
	s_setprio 2
	s_barrier
	ds_read_b128 v[178:181], v211 offset:32768
	ds_read_b128 v[182:185], v211 offset:33792
	ds_read_b128 v[186:189], v211 offset:34816
	ds_read_b128 v[190:193], v211 offset:35840
	v_mfma_f32_16x16x32_bf16 v[16:19], v[152:155], v[194:197], v[16:19]
	v_mfma_f32_16x16x32_bf16 v[16:19], v[156:159], v[198:201], v[16:19]
	v_mfma_f32_16x16x32_bf16 v[0:3], v[156:159], v[218:221], v[0:3]
	v_mfma_f32_16x16x32_bf16 v[0:3], v[152:155], v[202:205], v[0:3]
	s_setprio 0
	s_add_i32 s79, 0, 0x18000
	s_add_i32 s80, 0, 0x1c000
	v_add_u32_e32 v124, s79, v208
	v_add_u32_e32 v156, s80, v208
	ds_read_b128 v[96:99], v124
	ds_read_b128 v[100:103], v124 offset:1024
	ds_read_b128 v[120:123], v124 offset:2048
	ds_read_b128 v[124:127], v124 offset:3072
	ds_read_b128 v[144:147], v156
	ds_read_b128 v[148:151], v156 offset:1024
	ds_read_b128 v[152:155], v156 offset:2048
	ds_read_b128 v[156:159], v156 offset:3072
	s_add_u32 s50, s50, 0x40000
	s_addc_u32 s51, s51, 0
	s_mov_b32 m0, s63
	v_lshl_add_u64 v[228:229], s[50:51], 0, v[160:161]
	ds_read_b128 v[194:197], v211 offset:36864
	ds_read_b128 v[198:201], v211 offset:37888
	ds_read_b128 v[202:205], v211 offset:38912
	ds_read_b128 v[218:221], v211 offset:39936
	global_load_lds_dwordx4 v[228:229], off
	s_mov_b32 m0, s64
	v_lshl_add_u64 v[228:229], s[50:51], 0, v[164:165]
	global_load_lds_dwordx4 v[228:229], off
	s_waitcnt vmcnt(8) lgkmcnt(0)
	s_barrier
	s_setprio 1
	v_mfma_f32_16x16x32_bf16 v[140:143], v[96:99], v[178:181], v[140:143]
	v_mfma_f32_16x16x32_bf16 v[140:143], v[100:103], v[182:185], v[140:143]
	v_mfma_f32_16x16x32_bf16 v[116:119], v[100:103], v[190:193], v[116:119]
	v_mfma_f32_16x16x32_bf16 v[116:119], v[96:99], v[186:189], v[116:119]
	v_mfma_f32_16x16x32_bf16 v[92:95], v[96:99], v[194:197], v[92:95]
	v_mfma_f32_16x16x32_bf16 v[92:95], v[100:103], v[198:201], v[92:95]
	v_mfma_f32_16x16x32_bf16 v[76:79], v[100:103], v[218:221], v[76:79]
	v_mfma_f32_16x16x32_bf16 v[76:79], v[96:99], v[202:205], v[76:79]
	v_mfma_f32_16x16x32_bf16 v[136:139], v[120:123], v[178:181], v[136:139]
	v_mfma_f32_16x16x32_bf16 v[136:139], v[124:127], v[182:185], v[136:139]
	v_mfma_f32_16x16x32_bf16 v[112:115], v[124:127], v[190:193], v[112:115]
	v_mfma_f32_16x16x32_bf16 v[112:115], v[120:123], v[186:189], v[112:115]
	v_mfma_f32_16x16x32_bf16 v[88:91], v[120:123], v[194:197], v[88:91]
	v_mfma_f32_16x16x32_bf16 v[88:91], v[124:127], v[198:201], v[88:91]
	v_mfma_f32_16x16x32_bf16 v[72:75], v[124:127], v[218:221], v[72:75]
	v_mfma_f32_16x16x32_bf16 v[72:75], v[120:123], v[202:205], v[72:75]
	v_mfma_f32_16x16x32_bf16 v[132:135], v[144:147], v[178:181], v[132:135]
	v_mfma_f32_16x16x32_bf16 v[132:135], v[148:151], v[182:185], v[132:135]
	v_mfma_f32_16x16x32_bf16 v[108:111], v[148:151], v[190:193], v[108:111]
	v_mfma_f32_16x16x32_bf16 v[108:111], v[144:147], v[186:189], v[108:111]
	v_mfma_f32_16x16x32_bf16 v[84:87], v[144:147], v[194:197], v[84:87]
	v_mfma_f32_16x16x32_bf16 v[84:87], v[148:151], v[198:201], v[84:87]
	v_mfma_f32_16x16x32_bf16 v[68:71], v[148:151], v[218:221], v[68:71]
	v_mfma_f32_16x16x32_bf16 v[68:71], v[144:147], v[202:205], v[68:71]
	v_mfma_f32_16x16x32_bf16 v[128:131], v[152:155], v[178:181], v[128:131]
	v_mfma_f32_16x16x32_bf16 v[128:131], v[156:159], v[182:185], v[128:131]
	v_mfma_f32_16x16x32_bf16 v[104:107], v[156:159], v[190:193], v[104:107]
	v_mfma_f32_16x16x32_bf16 v[104:107], v[152:155], v[186:189], v[104:107]
	s_setprio 2
	s_barrier
	ds_read_b128 v[178:181], v211 offset:49152
	ds_read_b128 v[182:185], v211 offset:50176
	ds_read_b128 v[186:189], v211 offset:51200
	ds_read_b128 v[190:193], v211 offset:52224
	v_mfma_f32_16x16x32_bf16 v[80:83], v[152:155], v[194:197], v[80:83]
	v_mfma_f32_16x16x32_bf16 v[80:83], v[156:159], v[198:201], v[80:83]
	v_mfma_f32_16x16x32_bf16 v[64:67], v[156:159], v[218:221], v[64:67]
	v_mfma_f32_16x16x32_bf16 v[64:67], v[152:155], v[202:205], v[64:67]
	s_setprio 2
	s_add_i32 s50, s79, s61
	v_lshl_add_u64 v[206:207], v[206:207], 0, s[36:37]
	s_mov_b32 m0, s50
	ds_read_b128 v[194:197], v211 offset:53248
	ds_read_b128 v[198:201], v211 offset:54272
	ds_read_b128 v[202:205], v211 offset:55296
	ds_read_b128 v[218:221], v211 offset:56320
	global_load_lds_dwordx4 v[206:207], off
	s_add_i32 m0, s50, 0x2000
	s_add_u32 s8, s8, 0x40080
	v_lshl_add_u64 v[206:207], v[222:223], 0, s[36:37]
	s_addc_u32 s9, s9, 0
	s_add_i32 s50, s80, s61
	global_load_lds_dwordx4 v[206:207], off
	s_mov_b32 m0, s50
	v_lshl_add_u64 v[206:207], s[8:9], 0, v[162:163]
	global_load_lds_dwordx4 v[206:207], off
	s_add_i32 m0, s50, 0x2000
	v_lshl_add_u64 v[206:207], s[8:9], 0, v[166:167]
	global_load_lds_dwordx4 v[206:207], off
	s_mov_b32 m0, s68
	v_lshl_add_u64 v[206:207], v[224:225], 0, s[36:37]
	global_load_lds_dwordx4 v[206:207], off
	s_mov_b32 m0, s69
	v_lshl_add_u64 v[206:207], v[226:227], 0, s[36:37]
	global_load_lds_dwordx4 v[206:207], off
	s_waitcnt vmcnt(8) lgkmcnt(0)
	s_barrier
	s_setprio 1
	v_mfma_f32_16x16x32_bf16 v[60:63], v[96:99], v[178:181], v[60:63]
	v_mfma_f32_16x16x32_bf16 v[60:63], v[100:103], v[182:185], v[60:63]
	v_mfma_f32_16x16x32_bf16 v[44:47], v[100:103], v[190:193], v[44:47]
	v_mfma_f32_16x16x32_bf16 v[44:47], v[96:99], v[186:189], v[44:47]
	v_mfma_f32_16x16x32_bf16 v[28:31], v[96:99], v[194:197], v[28:31]
	v_mfma_f32_16x16x32_bf16 v[28:31], v[100:103], v[198:201], v[28:31]
	v_mfma_f32_16x16x32_bf16 v[12:15], v[100:103], v[218:221], v[12:15]
	v_mfma_f32_16x16x32_bf16 v[12:15], v[96:99], v[202:205], v[12:15]
	v_mfma_f32_16x16x32_bf16 v[56:59], v[120:123], v[178:181], v[56:59]
	v_mfma_f32_16x16x32_bf16 v[56:59], v[124:127], v[182:185], v[56:59]
	v_mfma_f32_16x16x32_bf16 v[40:43], v[124:127], v[190:193], v[40:43]
	v_mfma_f32_16x16x32_bf16 v[40:43], v[120:123], v[186:189], v[40:43]
	v_mfma_f32_16x16x32_bf16 v[24:27], v[120:123], v[194:197], v[24:27]
	v_mfma_f32_16x16x32_bf16 v[24:27], v[124:127], v[198:201], v[24:27]
	v_mfma_f32_16x16x32_bf16 v[8:11], v[124:127], v[218:221], v[8:11]
	v_mfma_f32_16x16x32_bf16 v[8:11], v[120:123], v[202:205], v[8:11]
	v_mfma_f32_16x16x32_bf16 v[52:55], v[144:147], v[178:181], v[52:55]
	v_mfma_f32_16x16x32_bf16 v[52:55], v[148:151], v[182:185], v[52:55]
	v_mfma_f32_16x16x32_bf16 v[36:39], v[148:151], v[190:193], v[36:39]
	v_mfma_f32_16x16x32_bf16 v[36:39], v[144:147], v[186:189], v[36:39]
	v_mfma_f32_16x16x32_bf16 v[20:23], v[144:147], v[194:197], v[20:23]
	v_mfma_f32_16x16x32_bf16 v[20:23], v[148:151], v[198:201], v[20:23]
	v_mfma_f32_16x16x32_bf16 v[4:7], v[148:151], v[218:221], v[4:7]
	v_mfma_f32_16x16x32_bf16 v[4:7], v[144:147], v[202:205], v[4:7]
	v_mfma_f32_16x16x32_bf16 v[48:51], v[152:155], v[178:181], v[48:51]
	v_mfma_f32_16x16x32_bf16 v[48:51], v[156:159], v[182:185], v[48:51]
	v_mfma_f32_16x16x32_bf16 v[32:35], v[156:159], v[190:193], v[32:35]
	v_mfma_f32_16x16x32_bf16 v[32:35], v[152:155], v[186:189], v[32:35]
	s_setprio 2
	s_barrier
	v_mfma_f32_16x16x32_bf16 v[16:19], v[152:155], v[194:197], v[16:19]
	v_mfma_f32_16x16x32_bf16 v[16:19], v[156:159], v[198:201], v[16:19]
	v_mfma_f32_16x16x32_bf16 v[0:3], v[156:159], v[218:221], v[0:3]
	v_mfma_f32_16x16x32_bf16 v[0:3], v[152:155], v[202:205], v[0:3]
	s_setprio 0
	s_add_i32 s78, s78, 2
	s_add_u32 s6, s6, 0x100
	s_addc_u32 s7, s7, 0
	s_add_u32 s56, s56, 0x100
	s_addc_u32 s57, s57, 0
	s_cmp_gt_u32 s78, 13
	s_cbranch_scc0 .LBB0_323

.LBB0_783:
	s_ashr_i32 s23, s22, 31
	s_lshl_b64 s[26:27], s[22:23], 19
	s_add_u32 s26, s43, s26
	s_addc_u32 s27, s44, s27
	s_and_b64 s[28:29], s[4:5], exec
	s_cselect_b32 s23, s27, s37
	s_cselect_b32 s31, s26, s36
	s_ashr_i32 s25, s24, 31
	s_lshl_b64 s[28:29], s[24:25], 19
	s_add_u32 s28, s45, s28
	s_addc_u32 s29, s46, s29
	s_and_b64 s[40:41], s[4:5], exec
	s_cselect_b32 s25, s29, s39
	s_cselect_b32 s62, s28, s38
	s_add_u32 s36, s36, 0x40080
	s_addc_u32 s37, s37, 0
	s_add_u32 s63, s38, 0x100
	s_addc_u32 s64, s39, 0
	s_mov_b32 s65, -2
	ds_read_b128 v[144:147], v163
	ds_read_b128 v[148:151], v163 offset:1024
	ds_read_b128 v[152:155], v163 offset:2048
	ds_read_b128 v[156:159], v163 offset:3072
	ds_read_b128 v[168:171], v164
	ds_read_b128 v[172:175], v164 offset:1024
	ds_read_b128 v[176:179], v164 offset:2048
	ds_read_b128 v[180:183], v164 offset:3072
	s_add_u32 s38, s36, 0xfffc0080
	s_addc_u32 s39, s37, -1
	s_cmp_eq_u32 s65, 12
	s_cselect_b32 s41, s23, s39
	s_cselect_b32 s40, s31, s38
	s_cselect_b32 s39, s25, s64
	s_cselect_b32 s38, s62, s63
	v_lshl_add_u64 v[160:161], s[36:37], 0, v[136:137]
	s_add_i32 m0, s50, 0xc000
	ds_read_b128 v[184:187], v165
	ds_read_b128 v[188:191], v165 offset:1024
	ds_read_b128 v[192:195], v165 offset:2048
	ds_read_b128 v[196:199], v165 offset:3072
	ds_read_b128 v[200:203], v165 offset:4096
	ds_read_b128 v[204:207], v165 offset:5120
	ds_read_b128 v[208:211], v165 offset:6144
	ds_read_b128 v[212:215], v165 offset:7168
	global_load_lds_dwordx4 v[160:161], off
	s_add_i32 m0, s50, 0xe000
	v_lshl_add_u64 v[160:161], s[36:37], 0, v[138:139]
	global_load_lds_dwordx4 v[160:161], off
	s_waitcnt vmcnt(8) lgkmcnt(0)
	s_barrier
	s_setprio 1
	v_mfma_f32_16x16x32_bf16 v[124:127], v[144:147], v[184:187], 0
	v_mfma_f32_16x16x32_bf16 v[124:127], v[148:151], v[188:191], v[124:127]
	v_mfma_f32_16x16x32_bf16 v[108:111], v[148:151], v[196:199], 0
	v_mfma_f32_16x16x32_bf16 v[108:111], v[144:147], v[192:195], v[108:111]
	v_mfma_f32_16x16x32_bf16 v[92:95], v[144:147], v[200:203], 0
	v_mfma_f32_16x16x32_bf16 v[92:95], v[148:151], v[204:207], v[92:95]
	v_mfma_f32_16x16x32_bf16 v[76:79], v[148:151], v[212:215], 0
	v_mfma_f32_16x16x32_bf16 v[76:79], v[144:147], v[208:211], v[76:79]
	v_mfma_f32_16x16x32_bf16 v[120:123], v[152:155], v[184:187], 0
	v_mfma_f32_16x16x32_bf16 v[120:123], v[156:159], v[188:191], v[120:123]
	v_mfma_f32_16x16x32_bf16 v[104:107], v[156:159], v[196:199], 0
	v_mfma_f32_16x16x32_bf16 v[104:107], v[152:155], v[192:195], v[104:107]
	v_mfma_f32_16x16x32_bf16 v[88:91], v[152:155], v[200:203], 0
	v_mfma_f32_16x16x32_bf16 v[88:91], v[156:159], v[204:207], v[88:91]
	v_mfma_f32_16x16x32_bf16 v[72:75], v[156:159], v[212:215], 0
	v_mfma_f32_16x16x32_bf16 v[72:75], v[152:155], v[208:211], v[72:75]
	v_mfma_f32_16x16x32_bf16 v[116:119], v[168:171], v[184:187], 0
	v_mfma_f32_16x16x32_bf16 v[116:119], v[172:175], v[188:191], v[116:119]
	v_mfma_f32_16x16x32_bf16 v[100:103], v[172:175], v[196:199], 0
	v_mfma_f32_16x16x32_bf16 v[100:103], v[168:171], v[192:195], v[100:103]
	v_mfma_f32_16x16x32_bf16 v[84:87], v[168:171], v[200:203], 0
	v_mfma_f32_16x16x32_bf16 v[84:87], v[172:175], v[204:207], v[84:87]
	v_mfma_f32_16x16x32_bf16 v[68:71], v[172:175], v[212:215], 0
	v_mfma_f32_16x16x32_bf16 v[68:71], v[168:171], v[208:211], v[68:71]
	v_mfma_f32_16x16x32_bf16 v[112:115], v[176:179], v[184:187], 0
	v_mfma_f32_16x16x32_bf16 v[112:115], v[180:183], v[188:191], v[112:115]
	v_mfma_f32_16x16x32_bf16 v[96:99], v[180:183], v[196:199], 0
	v_mfma_f32_16x16x32_bf16 v[96:99], v[176:179], v[192:195], v[96:99]
	s_setprio 2
	s_barrier
	ds_read_b128 v[184:187], v165 offset:16384
	ds_read_b128 v[188:191], v165 offset:17408
	ds_read_b128 v[192:195], v165 offset:18432
	ds_read_b128 v[196:199], v165 offset:19456
	v_mfma_f32_16x16x32_bf16 v[80:83], v[176:179], v[200:203], 0
	v_mfma_f32_16x16x32_bf16 v[80:83], v[180:183], v[204:207], v[80:83]
	v_mfma_f32_16x16x32_bf16 v[64:67], v[180:183], v[212:215], 0
	v_mfma_f32_16x16x32_bf16 v[64:67], v[176:179], v[208:211], v[64:67]
	s_setprio 2
	s_add_i32 s66, s59, s47
	v_lshl_add_u64 v[160:161], s[38:39], 0, v[132:133]
	s_mov_b32 m0, s66
	ds_read_b128 v[200:203], v165 offset:20480
	ds_read_b128 v[204:207], v165 offset:21504
	ds_read_b128 v[208:211], v165 offset:22528
	ds_read_b128 v[212:215], v165 offset:23552
	global_load_lds_dwordx4 v[160:161], off
	s_add_i32 m0, s66, 0x2000
	s_add_u32 s66, s38, 0x40000
	v_lshl_add_u64 v[216:217], s[38:39], 0, v[128:129]
	s_addc_u32 s67, s39, 0
	s_add_i32 s68, s60, s47
	global_load_lds_dwordx4 v[216:217], off
	v_lshl_add_u64 v[218:219], s[66:67], 0, v[132:133]
	s_mov_b32 m0, s68
	v_lshl_add_u64 v[220:221], s[40:41], 0, v[130:131]
	global_load_lds_dwordx4 v[218:219], off
	s_add_i32 m0, s68, 0x2000
	v_lshl_add_u64 v[218:219], s[66:67], 0, v[128:129]
	global_load_lds_dwordx4 v[218:219], off
	s_mov_b32 m0, s50
	v_lshl_add_u64 v[218:219], s[40:41], 0, v[134:135]
	global_load_lds_dwordx4 v[218:219], off
	s_mov_b32 m0, s51
	s_nop 0
	global_load_lds_dwordx4 v[220:221], off
	s_waitcnt vmcnt(8) lgkmcnt(0)
	s_barrier
	s_setprio 1
	v_mfma_f32_16x16x32_bf16 v[60:63], v[144:147], v[184:187], 0
	v_mfma_f32_16x16x32_bf16 v[60:63], v[148:151], v[188:191], v[60:63]
	v_mfma_f32_16x16x32_bf16 v[44:47], v[148:151], v[196:199], 0
	v_mfma_f32_16x16x32_bf16 v[44:47], v[144:147], v[192:195], v[44:47]
	v_mfma_f32_16x16x32_bf16 v[28:31], v[144:147], v[200:203], 0
	v_mfma_f32_16x16x32_bf16 v[28:31], v[148:151], v[204:207], v[28:31]
	v_mfma_f32_16x16x32_bf16 v[12:15], v[148:151], v[212:215], 0
	v_mfma_f32_16x16x32_bf16 v[12:15], v[144:147], v[208:211], v[12:15]
	v_mfma_f32_16x16x32_bf16 v[56:59], v[152:155], v[184:187], 0
	v_mfma_f32_16x16x32_bf16 v[56:59], v[156:159], v[188:191], v[56:59]
	v_mfma_f32_16x16x32_bf16 v[40:43], v[156:159], v[196:199], 0
	v_mfma_f32_16x16x32_bf16 v[40:43], v[152:155], v[192:195], v[40:43]
	v_mfma_f32_16x16x32_bf16 v[24:27], v[152:155], v[200:203], 0
	v_mfma_f32_16x16x32_bf16 v[24:27], v[156:159], v[204:207], v[24:27]
	v_mfma_f32_16x16x32_bf16 v[8:11], v[156:159], v[212:215], 0
	v_mfma_f32_16x16x32_bf16 v[8:11], v[152:155], v[208:211], v[8:11]
	v_mfma_f32_16x16x32_bf16 v[52:55], v[168:171], v[184:187], 0
	v_mfma_f32_16x16x32_bf16 v[52:55], v[172:175], v[188:191], v[52:55]
	v_mfma_f32_16x16x32_bf16 v[36:39], v[172:175], v[196:199], 0
	v_mfma_f32_16x16x32_bf16 v[36:39], v[168:171], v[192:195], v[36:39]
	v_mfma_f32_16x16x32_bf16 v[20:23], v[168:171], v[200:203], 0
	v_mfma_f32_16x16x32_bf16 v[20:23], v[172:175], v[204:207], v[20:23]
	v_mfma_f32_16x16x32_bf16 v[4:7], v[172:175], v[212:215], 0
	v_mfma_f32_16x16x32_bf16 v[4:7], v[168:171], v[208:211], v[4:7]
	v_mfma_f32_16x16x32_bf16 v[48:51], v[176:179], v[184:187], 0
	v_mfma_f32_16x16x32_bf16 v[48:51], v[180:183], v[188:191], v[48:51]
	v_mfma_f32_16x16x32_bf16 v[32:35], v[180:183], v[196:199], 0
	v_mfma_f32_16x16x32_bf16 v[32:35], v[176:179], v[192:195], v[32:35]
	s_setprio 2
	s_barrier
	ds_read_b128 v[184:187], v165 offset:32768
	ds_read_b128 v[188:191], v165 offset:33792
	ds_read_b128 v[192:195], v165 offset:34816
	ds_read_b128 v[196:199], v165 offset:35840
	v_mfma_f32_16x16x32_bf16 v[16:19], v[176:179], v[200:203], 0
	v_mfma_f32_16x16x32_bf16 v[16:19], v[180:183], v[204:207], v[16:19]
	v_mfma_f32_16x16x32_bf16 v[0:3], v[180:183], v[212:215], 0
	v_mfma_f32_16x16x32_bf16 v[0:3], v[176:179], v[208:211], v[0:3]
	s_setprio 0
	s_add_i32 s66, 0, 0x18000
	s_add_i32 s67, 0, 0x1c000
	v_add_u32_e32 v156, s66, v162
	v_add_u32_e32 v167, s67, v162
	ds_read_b128 v[144:147], v156
	ds_read_b128 v[148:151], v156 offset:1024
	ds_read_b128 v[152:155], v156 offset:2048
	ds_read_b128 v[156:159], v156 offset:3072
	ds_read_b128 v[168:171], v167
	ds_read_b128 v[172:175], v167 offset:1024
	ds_read_b128 v[176:179], v167 offset:2048
	ds_read_b128 v[180:183], v167 offset:3072
	s_add_u32 s40, s40, 0x40000
	s_addc_u32 s41, s41, 0
	s_mov_b32 m0, s54
	v_lshl_add_u64 v[222:223], s[40:41], 0, v[134:135]
	ds_read_b128 v[200:203], v165 offset:36864
	ds_read_b128 v[204:207], v165 offset:37888
	ds_read_b128 v[208:211], v165 offset:38912
	ds_read_b128 v[212:215], v165 offset:39936
	global_load_lds_dwordx4 v[222:223], off
	s_mov_b32 m0, s55
	v_lshl_add_u64 v[222:223], s[40:41], 0, v[130:131]
	global_load_lds_dwordx4 v[222:223], off
	s_waitcnt vmcnt(8) lgkmcnt(0)
	s_barrier
	s_setprio 1
	v_mfma_f32_16x16x32_bf16 v[124:127], v[144:147], v[184:187], v[124:127]
	v_mfma_f32_16x16x32_bf16 v[124:127], v[148:151], v[188:191], v[124:127]
	v_mfma_f32_16x16x32_bf16 v[108:111], v[148:151], v[196:199], v[108:111]
	v_mfma_f32_16x16x32_bf16 v[108:111], v[144:147], v[192:195], v[108:111]
	v_mfma_f32_16x16x32_bf16 v[92:95], v[144:147], v[200:203], v[92:95]
	v_mfma_f32_16x16x32_bf16 v[92:95], v[148:151], v[204:207], v[92:95]
	v_mfma_f32_16x16x32_bf16 v[76:79], v[148:151], v[212:215], v[76:79]
	v_mfma_f32_16x16x32_bf16 v[76:79], v[144:147], v[208:211], v[76:79]
	v_mfma_f32_16x16x32_bf16 v[120:123], v[152:155], v[184:187], v[120:123]
	v_mfma_f32_16x16x32_bf16 v[120:123], v[156:159], v[188:191], v[120:123]
	v_mfma_f32_16x16x32_bf16 v[104:107], v[156:159], v[196:199], v[104:107]
	v_mfma_f32_16x16x32_bf16 v[104:107], v[152:155], v[192:195], v[104:107]
	v_mfma_f32_16x16x32_bf16 v[88:91], v[152:155], v[200:203], v[88:91]
	v_mfma_f32_16x16x32_bf16 v[88:91], v[156:159], v[204:207], v[88:91]
	v_mfma_f32_16x16x32_bf16 v[72:75], v[156:159], v[212:215], v[72:75]
	v_mfma_f32_16x16x32_bf16 v[72:75], v[152:155], v[208:211], v[72:75]
	v_mfma_f32_16x16x32_bf16 v[116:119], v[168:171], v[184:187], v[116:119]
	v_mfma_f32_16x16x32_bf16 v[116:119], v[172:175], v[188:191], v[116:119]
	v_mfma_f32_16x16x32_bf16 v[100:103], v[172:175], v[196:199], v[100:103]
	v_mfma_f32_16x16x32_bf16 v[100:103], v[168:171], v[192:195], v[100:103]
	v_mfma_f32_16x16x32_bf16 v[84:87], v[168:171], v[200:203], v[84:87]
	v_mfma_f32_16x16x32_bf16 v[84:87], v[172:175], v[204:207], v[84:87]
	v_mfma_f32_16x16x32_bf16 v[68:71], v[172:175], v[212:215], v[68:71]
	v_mfma_f32_16x16x32_bf16 v[68:71], v[168:171], v[208:211], v[68:71]
	v_mfma_f32_16x16x32_bf16 v[112:115], v[176:179], v[184:187], v[112:115]
	v_mfma_f32_16x16x32_bf16 v[112:115], v[180:183], v[188:191], v[112:115]
	v_mfma_f32_16x16x32_bf16 v[96:99], v[180:183], v[196:199], v[96:99]
	v_mfma_f32_16x16x32_bf16 v[96:99], v[176:179], v[192:195], v[96:99]
	s_setprio 2
	s_barrier
	ds_read_b128 v[184:187], v165 offset:49152
	ds_read_b128 v[188:191], v165 offset:50176
	ds_read_b128 v[192:195], v165 offset:51200
	ds_read_b128 v[196:199], v165 offset:52224
	v_mfma_f32_16x16x32_bf16 v[80:83], v[176:179], v[200:203], v[80:83]
	v_mfma_f32_16x16x32_bf16 v[80:83], v[180:183], v[204:207], v[80:83]
	v_mfma_f32_16x16x32_bf16 v[64:67], v[180:183], v[212:215], v[64:67]
	v_mfma_f32_16x16x32_bf16 v[64:67], v[176:179], v[208:211], v[64:67]
	s_setprio 2
	s_add_i32 s40, s66, s47
	v_lshl_add_u64 v[160:161], v[160:161], 0, s[16:17]
	s_mov_b32 m0, s40
	ds_read_b128 v[200:203], v165 offset:53248
	ds_read_b128 v[204:207], v165 offset:54272
	ds_read_b128 v[208:211], v165 offset:55296
	ds_read_b128 v[212:215], v165 offset:56320
	global_load_lds_dwordx4 v[160:161], off
	s_add_i32 m0, s40, 0x2000
	s_add_u32 s38, s38, 0x40080
	v_lshl_add_u64 v[160:161], v[216:217], 0, s[16:17]
	s_addc_u32 s39, s39, 0
	s_add_i32 s40, s67, s47
	global_load_lds_dwordx4 v[160:161], off
	s_mov_b32 m0, s40
	v_lshl_add_u64 v[160:161], s[38:39], 0, v[132:133]
	global_load_lds_dwordx4 v[160:161], off
	s_add_i32 m0, s40, 0x2000
	v_lshl_add_u64 v[160:161], s[38:39], 0, v[128:129]
	global_load_lds_dwordx4 v[160:161], off
	s_mov_b32 m0, s57
	v_lshl_add_u64 v[160:161], v[218:219], 0, s[16:17]
	global_load_lds_dwordx4 v[160:161], off
	s_mov_b32 m0, s58
	v_lshl_add_u64 v[160:161], v[220:221], 0, s[16:17]
	global_load_lds_dwordx4 v[160:161], off
	s_waitcnt vmcnt(8) lgkmcnt(0)
	s_barrier
	s_setprio 1
	v_mfma_f32_16x16x32_bf16 v[60:63], v[144:147], v[184:187], v[60:63]
	v_mfma_f32_16x16x32_bf16 v[60:63], v[148:151], v[188:191], v[60:63]
	v_mfma_f32_16x16x32_bf16 v[44:47], v[148:151], v[196:199], v[44:47]
	v_mfma_f32_16x16x32_bf16 v[44:47], v[144:147], v[192:195], v[44:47]
	v_mfma_f32_16x16x32_bf16 v[28:31], v[144:147], v[200:203], v[28:31]
	v_mfma_f32_16x16x32_bf16 v[28:31], v[148:151], v[204:207], v[28:31]
	v_mfma_f32_16x16x32_bf16 v[12:15], v[148:151], v[212:215], v[12:15]
	v_mfma_f32_16x16x32_bf16 v[12:15], v[144:147], v[208:211], v[12:15]
	v_mfma_f32_16x16x32_bf16 v[56:59], v[152:155], v[184:187], v[56:59]
	v_mfma_f32_16x16x32_bf16 v[56:59], v[156:159], v[188:191], v[56:59]
	v_mfma_f32_16x16x32_bf16 v[40:43], v[156:159], v[196:199], v[40:43]
	v_mfma_f32_16x16x32_bf16 v[40:43], v[152:155], v[192:195], v[40:43]
	v_mfma_f32_16x16x32_bf16 v[24:27], v[152:155], v[200:203], v[24:27]
	v_mfma_f32_16x16x32_bf16 v[24:27], v[156:159], v[204:207], v[24:27]
	v_mfma_f32_16x16x32_bf16 v[8:11], v[156:159], v[212:215], v[8:11]
	v_mfma_f32_16x16x32_bf16 v[8:11], v[152:155], v[208:211], v[8:11]
	v_mfma_f32_16x16x32_bf16 v[52:55], v[168:171], v[184:187], v[52:55]
	v_mfma_f32_16x16x32_bf16 v[52:55], v[172:175], v[188:191], v[52:55]
	v_mfma_f32_16x16x32_bf16 v[36:39], v[172:175], v[196:199], v[36:39]
	v_mfma_f32_16x16x32_bf16 v[36:39], v[168:171], v[192:195], v[36:39]
	v_mfma_f32_16x16x32_bf16 v[20:23], v[168:171], v[200:203], v[20:23]
	v_mfma_f32_16x16x32_bf16 v[20:23], v[172:175], v[204:207], v[20:23]
	v_mfma_f32_16x16x32_bf16 v[4:7], v[172:175], v[212:215], v[4:7]
	v_mfma_f32_16x16x32_bf16 v[4:7], v[168:171], v[208:211], v[4:7]
	v_mfma_f32_16x16x32_bf16 v[48:51], v[176:179], v[184:187], v[48:51]
	v_mfma_f32_16x16x32_bf16 v[48:51], v[180:183], v[188:191], v[48:51]
	v_mfma_f32_16x16x32_bf16 v[32:35], v[180:183], v[196:199], v[32:35]
	v_mfma_f32_16x16x32_bf16 v[32:35], v[176:179], v[192:195], v[32:35]
	s_setprio 2
	s_barrier
	v_mfma_f32_16x16x32_bf16 v[16:19], v[176:179], v[200:203], v[16:19]
	v_mfma_f32_16x16x32_bf16 v[16:19], v[180:183], v[204:207], v[16:19]
	v_mfma_f32_16x16x32_bf16 v[0:3], v[180:183], v[212:215], v[0:3]
	v_mfma_f32_16x16x32_bf16 v[0:3], v[176:179], v[208:211], v[0:3]
	s_setprio 0
	s_add_i32 s65, s65, 2
	s_add_u32 s36, s36, 0x100
	s_addc_u32 s37, s37, 0
	s_add_u32 s63, s63, 0x100
	s_addc_u32 s64, s64, 0
	s_cmp_gt_u32 s65, 13
.LBB0_784:
	ds_read_b128 v[144:147], v163
	ds_read_b128 v[148:151], v163 offset:1024
	ds_read_b128 v[152:155], v163 offset:2048
	ds_read_b128 v[156:159], v163 offset:3072
	ds_read_b128 v[168:171], v164
	ds_read_b128 v[172:175], v164 offset:1024
	ds_read_b128 v[176:179], v164 offset:2048
	ds_read_b128 v[180:183], v164 offset:3072
	s_add_u32 s38, s36, 0xfffc0080
	s_addc_u32 s39, s37, -1
	s_cmp_eq_u32 s65, 12
	s_cselect_b32 s41, s23, s39
	s_cselect_b32 s40, s31, s38
	s_cselect_b32 s39, s25, s64
	s_cselect_b32 s38, s62, s63
	v_lshl_add_u64 v[160:161], s[36:37], 0, v[136:137]
	s_add_i32 m0, s50, 0xc000
	ds_read_b128 v[184:187], v165
	ds_read_b128 v[188:191], v165 offset:1024
	ds_read_b128 v[192:195], v165 offset:2048
	ds_read_b128 v[196:199], v165 offset:3072
	ds_read_b128 v[200:203], v165 offset:4096
	ds_read_b128 v[204:207], v165 offset:5120
	ds_read_b128 v[208:211], v165 offset:6144
	ds_read_b128 v[212:215], v165 offset:7168
	global_load_lds_dwordx4 v[160:161], off
	s_add_i32 m0, s50, 0xe000
	v_lshl_add_u64 v[160:161], s[36:37], 0, v[138:139]
	global_load_lds_dwordx4 v[160:161], off
	s_waitcnt vmcnt(8) lgkmcnt(0)
	s_barrier
	s_setprio 1
	v_mfma_f32_16x16x32_bf16 v[124:127], v[144:147], v[184:187], v[124:127]
	v_mfma_f32_16x16x32_bf16 v[124:127], v[148:151], v[188:191], v[124:127]
	v_mfma_f32_16x16x32_bf16 v[108:111], v[148:151], v[196:199], v[108:111]
	v_mfma_f32_16x16x32_bf16 v[108:111], v[144:147], v[192:195], v[108:111]
	v_mfma_f32_16x16x32_bf16 v[92:95], v[144:147], v[200:203], v[92:95]
	v_mfma_f32_16x16x32_bf16 v[92:95], v[148:151], v[204:207], v[92:95]
	v_mfma_f32_16x16x32_bf16 v[76:79], v[148:151], v[212:215], v[76:79]
	v_mfma_f32_16x16x32_bf16 v[76:79], v[144:147], v[208:211], v[76:79]
	v_mfma_f32_16x16x32_bf16 v[120:123], v[152:155], v[184:187], v[120:123]
	v_mfma_f32_16x16x32_bf16 v[120:123], v[156:159], v[188:191], v[120:123]
	v_mfma_f32_16x16x32_bf16 v[104:107], v[156:159], v[196:199], v[104:107]
	v_mfma_f32_16x16x32_bf16 v[104:107], v[152:155], v[192:195], v[104:107]
	v_mfma_f32_16x16x32_bf16 v[88:91], v[152:155], v[200:203], v[88:91]
	v_mfma_f32_16x16x32_bf16 v[88:91], v[156:159], v[204:207], v[88:91]
	v_mfma_f32_16x16x32_bf16 v[72:75], v[156:159], v[212:215], v[72:75]
	v_mfma_f32_16x16x32_bf16 v[72:75], v[152:155], v[208:211], v[72:75]
	v_mfma_f32_16x16x32_bf16 v[116:119], v[168:171], v[184:187], v[116:119]
	v_mfma_f32_16x16x32_bf16 v[116:119], v[172:175], v[188:191], v[116:119]
	v_mfma_f32_16x16x32_bf16 v[100:103], v[172:175], v[196:199], v[100:103]
	v_mfma_f32_16x16x32_bf16 v[100:103], v[168:171], v[192:195], v[100:103]
	v_mfma_f32_16x16x32_bf16 v[84:87], v[168:171], v[200:203], v[84:87]
	v_mfma_f32_16x16x32_bf16 v[84:87], v[172:175], v[204:207], v[84:87]
	v_mfma_f32_16x16x32_bf16 v[68:71], v[172:175], v[212:215], v[68:71]
	v_mfma_f32_16x16x32_bf16 v[68:71], v[168:171], v[208:211], v[68:71]
	v_mfma_f32_16x16x32_bf16 v[112:115], v[176:179], v[184:187], v[112:115]
	v_mfma_f32_16x16x32_bf16 v[112:115], v[180:183], v[188:191], v[112:115]
	v_mfma_f32_16x16x32_bf16 v[96:99], v[180:183], v[196:199], v[96:99]
	v_mfma_f32_16x16x32_bf16 v[96:99], v[176:179], v[192:195], v[96:99]
	s_setprio 2
	s_barrier
	ds_read_b128 v[184:187], v165 offset:16384
	ds_read_b128 v[188:191], v165 offset:17408
	ds_read_b128 v[192:195], v165 offset:18432
	ds_read_b128 v[196:199], v165 offset:19456
	v_mfma_f32_16x16x32_bf16 v[80:83], v[176:179], v[200:203], v[80:83]
	v_mfma_f32_16x16x32_bf16 v[80:83], v[180:183], v[204:207], v[80:83]
	v_mfma_f32_16x16x32_bf16 v[64:67], v[180:183], v[212:215], v[64:67]
	v_mfma_f32_16x16x32_bf16 v[64:67], v[176:179], v[208:211], v[64:67]
	s_setprio 2
	s_add_i32 s66, s59, s47
	v_lshl_add_u64 v[160:161], s[38:39], 0, v[132:133]
	s_mov_b32 m0, s66
	ds_read_b128 v[200:203], v165 offset:20480
	ds_read_b128 v[204:207], v165 offset:21504
	ds_read_b128 v[208:211], v165 offset:22528
	ds_read_b128 v[212:215], v165 offset:23552
	global_load_lds_dwordx4 v[160:161], off
	s_add_i32 m0, s66, 0x2000
	s_add_u32 s66, s38, 0x40000
	v_lshl_add_u64 v[216:217], s[38:39], 0, v[128:129]
	s_addc_u32 s67, s39, 0
	s_add_i32 s68, s60, s47
	global_load_lds_dwordx4 v[216:217], off
	v_lshl_add_u64 v[218:219], s[66:67], 0, v[132:133]
	s_mov_b32 m0, s68
	v_lshl_add_u64 v[220:221], s[40:41], 0, v[130:131]
	global_load_lds_dwordx4 v[218:219], off
	s_add_i32 m0, s68, 0x2000
	v_lshl_add_u64 v[218:219], s[66:67], 0, v[128:129]
	global_load_lds_dwordx4 v[218:219], off
	s_mov_b32 m0, s50
	v_lshl_add_u64 v[218:219], s[40:41], 0, v[134:135]
	global_load_lds_dwordx4 v[218:219], off
	s_mov_b32 m0, s51
	s_nop 0
	global_load_lds_dwordx4 v[220:221], off
	s_waitcnt vmcnt(8) lgkmcnt(0)
	s_barrier
	s_setprio 1
	v_mfma_f32_16x16x32_bf16 v[60:63], v[144:147], v[184:187], v[60:63]
	v_mfma_f32_16x16x32_bf16 v[60:63], v[148:151], v[188:191], v[60:63]
	v_mfma_f32_16x16x32_bf16 v[44:47], v[148:151], v[196:199], v[44:47]
	v_mfma_f32_16x16x32_bf16 v[44:47], v[144:147], v[192:195], v[44:47]
	v_mfma_f32_16x16x32_bf16 v[28:31], v[144:147], v[200:203], v[28:31]
	v_mfma_f32_16x16x32_bf16 v[28:31], v[148:151], v[204:207], v[28:31]
	v_mfma_f32_16x16x32_bf16 v[12:15], v[148:151], v[212:215], v[12:15]
	v_mfma_f32_16x16x32_bf16 v[12:15], v[144:147], v[208:211], v[12:15]
	v_mfma_f32_16x16x32_bf16 v[56:59], v[152:155], v[184:187], v[56:59]
	v_mfma_f32_16x16x32_bf16 v[56:59], v[156:159], v[188:191], v[56:59]
	v_mfma_f32_16x16x32_bf16 v[40:43], v[156:159], v[196:199], v[40:43]
	v_mfma_f32_16x16x32_bf16 v[40:43], v[152:155], v[192:195], v[40:43]
	v_mfma_f32_16x16x32_bf16 v[24:27], v[152:155], v[200:203], v[24:27]
	v_mfma_f32_16x16x32_bf16 v[24:27], v[156:159], v[204:207], v[24:27]
	v_mfma_f32_16x16x32_bf16 v[8:11], v[156:159], v[212:215], v[8:11]
	v_mfma_f32_16x16x32_bf16 v[8:11], v[152:155], v[208:211], v[8:11]
	v_mfma_f32_16x16x32_bf16 v[52:55], v[168:171], v[184:187], v[52:55]
	v_mfma_f32_16x16x32_bf16 v[52:55], v[172:175], v[188:191], v[52:55]
	v_mfma_f32_16x16x32_bf16 v[36:39], v[172:175], v[196:199], v[36:39]
	v_mfma_f32_16x16x32_bf16 v[36:39], v[168:171], v[192:195], v[36:39]
	v_mfma_f32_16x16x32_bf16 v[20:23], v[168:171], v[200:203], v[20:23]
	v_mfma_f32_16x16x32_bf16 v[20:23], v[172:175], v[204:207], v[20:23]
	v_mfma_f32_16x16x32_bf16 v[4:7], v[172:175], v[212:215], v[4:7]
	v_mfma_f32_16x16x32_bf16 v[4:7], v[168:171], v[208:211], v[4:7]
	v_mfma_f32_16x16x32_bf16 v[48:51], v[176:179], v[184:187], v[48:51]
	v_mfma_f32_16x16x32_bf16 v[48:51], v[180:183], v[188:191], v[48:51]
	v_mfma_f32_16x16x32_bf16 v[32:35], v[180:183], v[196:199], v[32:35]
	v_mfma_f32_16x16x32_bf16 v[32:35], v[176:179], v[192:195], v[32:35]
	s_setprio 2
	s_barrier
	ds_read_b128 v[184:187], v165 offset:32768
	ds_read_b128 v[188:191], v165 offset:33792
	ds_read_b128 v[192:195], v165 offset:34816
	ds_read_b128 v[196:199], v165 offset:35840
	v_mfma_f32_16x16x32_bf16 v[16:19], v[176:179], v[200:203], v[16:19]
	v_mfma_f32_16x16x32_bf16 v[16:19], v[180:183], v[204:207], v[16:19]
	v_mfma_f32_16x16x32_bf16 v[0:3], v[180:183], v[212:215], v[0:3]
	v_mfma_f32_16x16x32_bf16 v[0:3], v[176:179], v[208:211], v[0:3]
	s_setprio 0
	s_add_i32 s66, 0, 0x18000
	s_add_i32 s67, 0, 0x1c000
	v_add_u32_e32 v156, s66, v162
	v_add_u32_e32 v167, s67, v162
	ds_read_b128 v[144:147], v156
	ds_read_b128 v[148:151], v156 offset:1024
	ds_read_b128 v[152:155], v156 offset:2048
	ds_read_b128 v[156:159], v156 offset:3072
	ds_read_b128 v[168:171], v167
	ds_read_b128 v[172:175], v167 offset:1024
	ds_read_b128 v[176:179], v167 offset:2048
	ds_read_b128 v[180:183], v167 offset:3072
	s_add_u32 s40, s40, 0x40000
	s_addc_u32 s41, s41, 0
	s_mov_b32 m0, s54
	v_lshl_add_u64 v[222:223], s[40:41], 0, v[134:135]
	ds_read_b128 v[200:203], v165 offset:36864
	ds_read_b128 v[204:207], v165 offset:37888
	ds_read_b128 v[208:211], v165 offset:38912
	ds_read_b128 v[212:215], v165 offset:39936
	global_load_lds_dwordx4 v[222:223], off
	s_mov_b32 m0, s55
	v_lshl_add_u64 v[222:223], s[40:41], 0, v[130:131]
	global_load_lds_dwordx4 v[222:223], off
	s_waitcnt vmcnt(8) lgkmcnt(0)
	s_barrier
	s_setprio 1
	v_mfma_f32_16x16x32_bf16 v[124:127], v[144:147], v[184:187], v[124:127]
	v_mfma_f32_16x16x32_bf16 v[124:127], v[148:151], v[188:191], v[124:127]
	v_mfma_f32_16x16x32_bf16 v[108:111], v[148:151], v[196:199], v[108:111]
	v_mfma_f32_16x16x32_bf16 v[108:111], v[144:147], v[192:195], v[108:111]
	v_mfma_f32_16x16x32_bf16 v[92:95], v[144:147], v[200:203], v[92:95]
	v_mfma_f32_16x16x32_bf16 v[92:95], v[148:151], v[204:207], v[92:95]
	v_mfma_f32_16x16x32_bf16 v[76:79], v[148:151], v[212:215], v[76:79]
	v_mfma_f32_16x16x32_bf16 v[76:79], v[144:147], v[208:211], v[76:79]
	v_mfma_f32_16x16x32_bf16 v[120:123], v[152:155], v[184:187], v[120:123]
	v_mfma_f32_16x16x32_bf16 v[120:123], v[156:159], v[188:191], v[120:123]
	v_mfma_f32_16x16x32_bf16 v[104:107], v[156:159], v[196:199], v[104:107]
	v_mfma_f32_16x16x32_bf16 v[104:107], v[152:155], v[192:195], v[104:107]
	v_mfma_f32_16x16x32_bf16 v[88:91], v[152:155], v[200:203], v[88:91]
	v_mfma_f32_16x16x32_bf16 v[88:91], v[156:159], v[204:207], v[88:91]
	v_mfma_f32_16x16x32_bf16 v[72:75], v[156:159], v[212:215], v[72:75]
	v_mfma_f32_16x16x32_bf16 v[72:75], v[152:155], v[208:211], v[72:75]
	v_mfma_f32_16x16x32_bf16 v[116:119], v[168:171], v[184:187], v[116:119]
	v_mfma_f32_16x16x32_bf16 v[116:119], v[172:175], v[188:191], v[116:119]
	v_mfma_f32_16x16x32_bf16 v[100:103], v[172:175], v[196:199], v[100:103]
	v_mfma_f32_16x16x32_bf16 v[100:103], v[168:171], v[192:195], v[100:103]
	v_mfma_f32_16x16x32_bf16 v[84:87], v[168:171], v[200:203], v[84:87]
	v_mfma_f32_16x16x32_bf16 v[84:87], v[172:175], v[204:207], v[84:87]
	v_mfma_f32_16x16x32_bf16 v[68:71], v[172:175], v[212:215], v[68:71]
	v_mfma_f32_16x16x32_bf16 v[68:71], v[168:171], v[208:211], v[68:71]
	v_mfma_f32_16x16x32_bf16 v[112:115], v[176:179], v[184:187], v[112:115]
	v_mfma_f32_16x16x32_bf16 v[112:115], v[180:183], v[188:191], v[112:115]
	v_mfma_f32_16x16x32_bf16 v[96:99], v[180:183], v[196:199], v[96:99]
	v_mfma_f32_16x16x32_bf16 v[96:99], v[176:179], v[192:195], v[96:99]
	s_setprio 2
	s_barrier
	ds_read_b128 v[184:187], v165 offset:49152
	ds_read_b128 v[188:191], v165 offset:50176
	ds_read_b128 v[192:195], v165 offset:51200
	ds_read_b128 v[196:199], v165 offset:52224
	v_mfma_f32_16x16x32_bf16 v[80:83], v[176:179], v[200:203], v[80:83]
	v_mfma_f32_16x16x32_bf16 v[80:83], v[180:183], v[204:207], v[80:83]
	v_mfma_f32_16x16x32_bf16 v[64:67], v[180:183], v[212:215], v[64:67]
	v_mfma_f32_16x16x32_bf16 v[64:67], v[176:179], v[208:211], v[64:67]
	s_setprio 2
	s_add_i32 s40, s66, s47
	v_lshl_add_u64 v[160:161], v[160:161], 0, s[16:17]
	s_mov_b32 m0, s40
	ds_read_b128 v[200:203], v165 offset:53248
	ds_read_b128 v[204:207], v165 offset:54272
	ds_read_b128 v[208:211], v165 offset:55296
	ds_read_b128 v[212:215], v165 offset:56320
	global_load_lds_dwordx4 v[160:161], off
	s_add_i32 m0, s40, 0x2000
	s_add_u32 s38, s38, 0x40080
	v_lshl_add_u64 v[160:161], v[216:217], 0, s[16:17]
	s_addc_u32 s39, s39, 0
	s_add_i32 s40, s67, s47
	global_load_lds_dwordx4 v[160:161], off
	s_mov_b32 m0, s40
	v_lshl_add_u64 v[160:161], s[38:39], 0, v[132:133]
	global_load_lds_dwordx4 v[160:161], off
	s_add_i32 m0, s40, 0x2000
	v_lshl_add_u64 v[160:161], s[38:39], 0, v[128:129]
	global_load_lds_dwordx4 v[160:161], off
	s_mov_b32 m0, s57
	v_lshl_add_u64 v[160:161], v[218:219], 0, s[16:17]
	global_load_lds_dwordx4 v[160:161], off
	s_mov_b32 m0, s58
	v_lshl_add_u64 v[160:161], v[220:221], 0, s[16:17]
	global_load_lds_dwordx4 v[160:161], off
	s_waitcnt vmcnt(8) lgkmcnt(0)
	s_barrier
	s_setprio 1
	v_mfma_f32_16x16x32_bf16 v[60:63], v[144:147], v[184:187], v[60:63]
	v_mfma_f32_16x16x32_bf16 v[60:63], v[148:151], v[188:191], v[60:63]
	v_mfma_f32_16x16x32_bf16 v[44:47], v[148:151], v[196:199], v[44:47]
	v_mfma_f32_16x16x32_bf16 v[44:47], v[144:147], v[192:195], v[44:47]
	v_mfma_f32_16x16x32_bf16 v[28:31], v[144:147], v[200:203], v[28:31]
	v_mfma_f32_16x16x32_bf16 v[28:31], v[148:151], v[204:207], v[28:31]
	v_mfma_f32_16x16x32_bf16 v[12:15], v[148:151], v[212:215], v[12:15]
	v_mfma_f32_16x16x32_bf16 v[12:15], v[144:147], v[208:211], v[12:15]
	v_mfma_f32_16x16x32_bf16 v[56:59], v[152:155], v[184:187], v[56:59]
	v_mfma_f32_16x16x32_bf16 v[56:59], v[156:159], v[188:191], v[56:59]
	v_mfma_f32_16x16x32_bf16 v[40:43], v[156:159], v[196:199], v[40:43]
	v_mfma_f32_16x16x32_bf16 v[40:43], v[152:155], v[192:195], v[40:43]
	v_mfma_f32_16x16x32_bf16 v[24:27], v[152:155], v[200:203], v[24:27]
	v_mfma_f32_16x16x32_bf16 v[24:27], v[156:159], v[204:207], v[24:27]
	v_mfma_f32_16x16x32_bf16 v[8:11], v[156:159], v[212:215], v[8:11]
	v_mfma_f32_16x16x32_bf16 v[8:11], v[152:155], v[208:211], v[8:11]
	v_mfma_f32_16x16x32_bf16 v[52:55], v[168:171], v[184:187], v[52:55]
	v_mfma_f32_16x16x32_bf16 v[52:55], v[172:175], v[188:191], v[52:55]
	v_mfma_f32_16x16x32_bf16 v[36:39], v[172:175], v[196:199], v[36:39]
	v_mfma_f32_16x16x32_bf16 v[36:39], v[168:171], v[192:195], v[36:39]
	v_mfma_f32_16x16x32_bf16 v[20:23], v[168:171], v[200:203], v[20:23]
	v_mfma_f32_16x16x32_bf16 v[20:23], v[172:175], v[204:207], v[20:23]
	v_mfma_f32_16x16x32_bf16 v[4:7], v[172:175], v[212:215], v[4:7]
	v_mfma_f32_16x16x32_bf16 v[4:7], v[168:171], v[208:211], v[4:7]
	v_mfma_f32_16x16x32_bf16 v[48:51], v[176:179], v[184:187], v[48:51]
	v_mfma_f32_16x16x32_bf16 v[48:51], v[180:183], v[188:191], v[48:51]
	v_mfma_f32_16x16x32_bf16 v[32:35], v[180:183], v[196:199], v[32:35]
	v_mfma_f32_16x16x32_bf16 v[32:35], v[176:179], v[192:195], v[32:35]
	s_setprio 2
	s_barrier
	v_mfma_f32_16x16x32_bf16 v[16:19], v[176:179], v[200:203], v[16:19]
	v_mfma_f32_16x16x32_bf16 v[16:19], v[180:183], v[204:207], v[16:19]
	v_mfma_f32_16x16x32_bf16 v[0:3], v[180:183], v[212:215], v[0:3]
	v_mfma_f32_16x16x32_bf16 v[0:3], v[176:179], v[208:211], v[0:3]
	s_setprio 0
	s_add_i32 s65, s65, 2
	s_add_u32 s36, s36, 0x100
	s_addc_u32 s37, s37, 0
	s_add_u32 s63, s63, 0x100
	s_addc_u32 s64, s64, 0
	s_cmp_gt_u32 s65, 13
	s_cbranch_scc0 .LBB0_784

.LBB0_865:
	s_add_u32 s62, s28, 0x100
	s_addc_u32 s63, s29, 0
	s_mov_b32 s64, -2
	ds_read_b128 v[120:123], v233
	ds_read_b128 v[124:127], v233 offset:1024
	ds_read_b128 v[136:139], v233 offset:2048
	ds_read_b128 v[140:143], v233 offset:3072
	ds_read_b128 v[144:147], v234
	ds_read_b128 v[148:151], v234 offset:1024
	ds_read_b128 v[152:155], v234 offset:2048
	ds_read_b128 v[156:159], v234 offset:3072
	s_add_u32 s28, s26, 0x100
	s_addc_u32 s29, s27, 0
	s_cmp_eq_u32 s64, 40
	s_cselect_b32 s37, s7, s29
	s_cselect_b32 s36, s6, s28
	s_cselect_b32 s31, s25, s63
	s_cselect_b32 s30, s24, s62
	v_lshl_add_u64 v[208:209], s[26:27], 0, v[192:193]
	s_add_i32 m0, s44, 0xc000
	ds_read_b128 v[160:163], v235
	ds_read_b128 v[164:167], v235 offset:1024
	ds_read_b128 v[168:171], v235 offset:2048
	ds_read_b128 v[172:175], v235 offset:3072
	ds_read_b128 v[176:179], v235 offset:4096
	ds_read_b128 v[180:183], v235 offset:5120
	ds_read_b128 v[200:203], v235 offset:6144
	ds_read_b128 v[204:207], v235 offset:7168
	global_load_lds_dwordx4 v[208:209], off
	s_add_i32 m0, s44, 0xe000
	v_lshl_add_u64 v[208:209], s[26:27], 0, v[194:195]
	global_load_lds_dwordx4 v[208:209], off
	s_waitcnt vmcnt(8) lgkmcnt(0)
	s_barrier
	s_setprio 1
	v_mfma_f32_16x16x32_bf16 v[132:135], v[120:123], v[160:163], 0
	v_mfma_f32_16x16x32_bf16 v[132:135], v[124:127], v[164:167], v[132:135]
	v_mfma_f32_16x16x32_bf16 v[108:111], v[124:127], v[172:175], 0
	v_mfma_f32_16x16x32_bf16 v[108:111], v[120:123], v[168:171], v[108:111]
	v_mfma_f32_16x16x32_bf16 v[92:95], v[120:123], v[176:179], 0
	v_mfma_f32_16x16x32_bf16 v[92:95], v[124:127], v[180:183], v[92:95]
	v_mfma_f32_16x16x32_bf16 v[76:79], v[124:127], v[204:207], 0
	v_mfma_f32_16x16x32_bf16 v[76:79], v[120:123], v[200:203], v[76:79]
	v_mfma_f32_16x16x32_bf16 v[128:131], v[136:139], v[160:163], 0
	v_mfma_f32_16x16x32_bf16 v[128:131], v[140:143], v[164:167], v[128:131]
	v_mfma_f32_16x16x32_bf16 v[104:107], v[140:143], v[172:175], 0
	v_mfma_f32_16x16x32_bf16 v[104:107], v[136:139], v[168:171], v[104:107]
	v_mfma_f32_16x16x32_bf16 v[88:91], v[136:139], v[176:179], 0
	v_mfma_f32_16x16x32_bf16 v[88:91], v[140:143], v[180:183], v[88:91]
	v_mfma_f32_16x16x32_bf16 v[72:75], v[140:143], v[204:207], 0
	v_mfma_f32_16x16x32_bf16 v[72:75], v[136:139], v[200:203], v[72:75]
	v_mfma_f32_16x16x32_bf16 v[116:119], v[144:147], v[160:163], 0
	v_mfma_f32_16x16x32_bf16 v[116:119], v[148:151], v[164:167], v[116:119]
	v_mfma_f32_16x16x32_bf16 v[100:103], v[148:151], v[172:175], 0
	v_mfma_f32_16x16x32_bf16 v[100:103], v[144:147], v[168:171], v[100:103]
	v_mfma_f32_16x16x32_bf16 v[84:87], v[144:147], v[176:179], 0
	v_mfma_f32_16x16x32_bf16 v[84:87], v[148:151], v[180:183], v[84:87]
	v_mfma_f32_16x16x32_bf16 v[68:71], v[148:151], v[204:207], 0
	v_mfma_f32_16x16x32_bf16 v[68:71], v[144:147], v[200:203], v[68:71]
	v_mfma_f32_16x16x32_bf16 v[112:115], v[152:155], v[160:163], 0
	v_mfma_f32_16x16x32_bf16 v[112:115], v[156:159], v[164:167], v[112:115]
	v_mfma_f32_16x16x32_bf16 v[96:99], v[156:159], v[172:175], 0
	v_mfma_f32_16x16x32_bf16 v[96:99], v[152:155], v[168:171], v[96:99]
	s_setprio 2
	s_barrier
	ds_read_b128 v[160:163], v235 offset:16384
	ds_read_b128 v[164:167], v235 offset:17408
	ds_read_b128 v[168:171], v235 offset:18432
	ds_read_b128 v[172:175], v235 offset:19456
	v_mfma_f32_16x16x32_bf16 v[80:83], v[152:155], v[176:179], 0
	v_mfma_f32_16x16x32_bf16 v[80:83], v[156:159], v[180:183], v[80:83]
	v_mfma_f32_16x16x32_bf16 v[64:67], v[156:159], v[204:207], 0
	v_mfma_f32_16x16x32_bf16 v[64:67], v[152:155], v[200:203], v[64:67]
	s_setprio 2
	s_add_i32 s26, s56, s43
	v_lshl_add_u64 v[208:209], s[30:31], 0, v[186:187]
	s_mov_b32 m0, s26
	ds_read_b128 v[176:179], v235 offset:20480
	ds_read_b128 v[180:183], v235 offset:21504
	ds_read_b128 v[200:203], v235 offset:22528
	ds_read_b128 v[204:207], v235 offset:23552
	global_load_lds_dwordx4 v[208:209], off
	s_add_i32 m0, s26, 0x2000
	s_add_u32 s26, s30, 0xb0000
	v_lshl_add_u64 v[210:211], s[30:31], 0, v[190:191]
	s_addc_u32 s27, s31, 0
	s_add_i32 s65, s57, s43
	global_load_lds_dwordx4 v[210:211], off
	v_lshl_add_u64 v[212:213], s[26:27], 0, v[186:187]
	s_mov_b32 m0, s65
	v_lshl_add_u64 v[214:215], s[36:37], 0, v[188:189]
	global_load_lds_dwordx4 v[212:213], off
	s_add_i32 m0, s65, 0x2000
	v_lshl_add_u64 v[212:213], s[26:27], 0, v[190:191]
	global_load_lds_dwordx4 v[212:213], off
	s_mov_b32 m0, s44
	v_lshl_add_u64 v[212:213], s[36:37], 0, v[184:185]
	global_load_lds_dwordx4 v[212:213], off
	s_mov_b32 m0, s45
	s_nop 0
	global_load_lds_dwordx4 v[214:215], off
	s_waitcnt vmcnt(8) lgkmcnt(0)
	s_barrier
	s_setprio 1
	v_mfma_f32_16x16x32_bf16 v[60:63], v[120:123], v[160:163], 0
	v_mfma_f32_16x16x32_bf16 v[60:63], v[124:127], v[164:167], v[60:63]
	v_mfma_f32_16x16x32_bf16 v[44:47], v[124:127], v[172:175], 0
	v_mfma_f32_16x16x32_bf16 v[44:47], v[120:123], v[168:171], v[44:47]
	v_mfma_f32_16x16x32_bf16 v[28:31], v[120:123], v[176:179], 0
	v_mfma_f32_16x16x32_bf16 v[28:31], v[124:127], v[180:183], v[28:31]
	v_mfma_f32_16x16x32_bf16 v[12:15], v[124:127], v[204:207], 0
	v_mfma_f32_16x16x32_bf16 v[12:15], v[120:123], v[200:203], v[12:15]
	v_mfma_f32_16x16x32_bf16 v[56:59], v[136:139], v[160:163], 0
	v_mfma_f32_16x16x32_bf16 v[56:59], v[140:143], v[164:167], v[56:59]
	v_mfma_f32_16x16x32_bf16 v[40:43], v[140:143], v[172:175], 0
	v_mfma_f32_16x16x32_bf16 v[40:43], v[136:139], v[168:171], v[40:43]
	v_mfma_f32_16x16x32_bf16 v[24:27], v[136:139], v[176:179], 0
	v_mfma_f32_16x16x32_bf16 v[24:27], v[140:143], v[180:183], v[24:27]
	v_mfma_f32_16x16x32_bf16 v[8:11], v[140:143], v[204:207], 0
	v_mfma_f32_16x16x32_bf16 v[8:11], v[136:139], v[200:203], v[8:11]
	v_mfma_f32_16x16x32_bf16 v[52:55], v[144:147], v[160:163], 0
	v_mfma_f32_16x16x32_bf16 v[52:55], v[148:151], v[164:167], v[52:55]
	v_mfma_f32_16x16x32_bf16 v[36:39], v[148:151], v[172:175], 0
	v_mfma_f32_16x16x32_bf16 v[36:39], v[144:147], v[168:171], v[36:39]
	v_mfma_f32_16x16x32_bf16 v[20:23], v[144:147], v[176:179], 0
	v_mfma_f32_16x16x32_bf16 v[20:23], v[148:151], v[180:183], v[20:23]
	v_mfma_f32_16x16x32_bf16 v[4:7], v[148:151], v[204:207], 0
	v_mfma_f32_16x16x32_bf16 v[4:7], v[144:147], v[200:203], v[4:7]
	v_mfma_f32_16x16x32_bf16 v[48:51], v[152:155], v[160:163], 0
	v_mfma_f32_16x16x32_bf16 v[48:51], v[156:159], v[164:167], v[48:51]
	v_mfma_f32_16x16x32_bf16 v[32:35], v[156:159], v[172:175], 0
	v_mfma_f32_16x16x32_bf16 v[32:35], v[152:155], v[168:171], v[32:35]
	s_setprio 2
	s_barrier
	ds_read_b128 v[160:163], v235 offset:32768
	ds_read_b128 v[164:167], v235 offset:33792
	ds_read_b128 v[168:171], v235 offset:34816
	ds_read_b128 v[172:175], v235 offset:35840
	v_mfma_f32_16x16x32_bf16 v[16:19], v[152:155], v[176:179], 0
	v_mfma_f32_16x16x32_bf16 v[16:19], v[156:159], v[180:183], v[16:19]
	v_mfma_f32_16x16x32_bf16 v[0:3], v[156:159], v[204:207], 0
	v_mfma_f32_16x16x32_bf16 v[0:3], v[152:155], v[200:203], v[0:3]
	s_setprio 0
	s_add_i32 s65, 0, 0x18000
	s_add_i32 s66, 0, 0x1c000
	v_add_u32_e32 v140, s65, v232
	v_add_u32_e32 v156, s66, v232
	ds_read_b128 v[120:123], v140
	ds_read_b128 v[124:127], v140 offset:1024
	ds_read_b128 v[136:139], v140 offset:2048
	ds_read_b128 v[140:143], v140 offset:3072
	ds_read_b128 v[144:147], v156
	ds_read_b128 v[148:151], v156 offset:1024
	ds_read_b128 v[152:155], v156 offset:2048
	ds_read_b128 v[156:159], v156 offset:3072
	s_add_u32 s26, s36, 0xb0000
	s_addc_u32 s27, s37, 0
	s_mov_b32 m0, s46
	v_lshl_add_u64 v[216:217], s[26:27], 0, v[184:185]
	ds_read_b128 v[176:179], v235 offset:36864
	ds_read_b128 v[180:183], v235 offset:37888
	ds_read_b128 v[200:203], v235 offset:38912
	ds_read_b128 v[204:207], v235 offset:39936
	global_load_lds_dwordx4 v[216:217], off
	s_mov_b32 m0, s47
	v_lshl_add_u64 v[216:217], s[26:27], 0, v[188:189]
	global_load_lds_dwordx4 v[216:217], off
	s_waitcnt vmcnt(8) lgkmcnt(0)
	s_barrier
	s_setprio 1
	v_mfma_f32_16x16x32_bf16 v[132:135], v[120:123], v[160:163], v[132:135]
	v_mfma_f32_16x16x32_bf16 v[132:135], v[124:127], v[164:167], v[132:135]
	v_mfma_f32_16x16x32_bf16 v[108:111], v[124:127], v[172:175], v[108:111]
	v_mfma_f32_16x16x32_bf16 v[108:111], v[120:123], v[168:171], v[108:111]
	v_mfma_f32_16x16x32_bf16 v[92:95], v[120:123], v[176:179], v[92:95]
	v_mfma_f32_16x16x32_bf16 v[92:95], v[124:127], v[180:183], v[92:95]
	v_mfma_f32_16x16x32_bf16 v[76:79], v[124:127], v[204:207], v[76:79]
	v_mfma_f32_16x16x32_bf16 v[76:79], v[120:123], v[200:203], v[76:79]
	v_mfma_f32_16x16x32_bf16 v[128:131], v[136:139], v[160:163], v[128:131]
	v_mfma_f32_16x16x32_bf16 v[128:131], v[140:143], v[164:167], v[128:131]
	v_mfma_f32_16x16x32_bf16 v[104:107], v[140:143], v[172:175], v[104:107]
	v_mfma_f32_16x16x32_bf16 v[104:107], v[136:139], v[168:171], v[104:107]
	v_mfma_f32_16x16x32_bf16 v[88:91], v[136:139], v[176:179], v[88:91]
	v_mfma_f32_16x16x32_bf16 v[88:91], v[140:143], v[180:183], v[88:91]
	v_mfma_f32_16x16x32_bf16 v[72:75], v[140:143], v[204:207], v[72:75]
	v_mfma_f32_16x16x32_bf16 v[72:75], v[136:139], v[200:203], v[72:75]
	v_mfma_f32_16x16x32_bf16 v[116:119], v[144:147], v[160:163], v[116:119]
	v_mfma_f32_16x16x32_bf16 v[116:119], v[148:151], v[164:167], v[116:119]
	v_mfma_f32_16x16x32_bf16 v[100:103], v[148:151], v[172:175], v[100:103]
	v_mfma_f32_16x16x32_bf16 v[100:103], v[144:147], v[168:171], v[100:103]
	v_mfma_f32_16x16x32_bf16 v[84:87], v[144:147], v[176:179], v[84:87]
	v_mfma_f32_16x16x32_bf16 v[84:87], v[148:151], v[180:183], v[84:87]
	v_mfma_f32_16x16x32_bf16 v[68:71], v[148:151], v[204:207], v[68:71]
	v_mfma_f32_16x16x32_bf16 v[68:71], v[144:147], v[200:203], v[68:71]
	v_mfma_f32_16x16x32_bf16 v[112:115], v[152:155], v[160:163], v[112:115]
	v_mfma_f32_16x16x32_bf16 v[112:115], v[156:159], v[164:167], v[112:115]
	v_mfma_f32_16x16x32_bf16 v[96:99], v[156:159], v[172:175], v[96:99]
	v_mfma_f32_16x16x32_bf16 v[96:99], v[152:155], v[168:171], v[96:99]
	s_setprio 2
	s_barrier
	ds_read_b128 v[160:163], v235 offset:49152
	ds_read_b128 v[164:167], v235 offset:50176
	ds_read_b128 v[168:171], v235 offset:51200
	ds_read_b128 v[172:175], v235 offset:52224
	v_mfma_f32_16x16x32_bf16 v[80:83], v[152:155], v[176:179], v[80:83]
	v_mfma_f32_16x16x32_bf16 v[80:83], v[156:159], v[180:183], v[80:83]
	v_mfma_f32_16x16x32_bf16 v[64:67], v[156:159], v[204:207], v[64:67]
	v_mfma_f32_16x16x32_bf16 v[64:67], v[152:155], v[200:203], v[64:67]
	s_setprio 2
	s_add_i32 s26, s65, s43
	v_lshl_add_u64 v[208:209], v[208:209], 0, s[20:21]
	s_mov_b32 m0, s26
	ds_read_b128 v[176:179], v235 offset:53248
	ds_read_b128 v[180:183], v235 offset:54272
	ds_read_b128 v[200:203], v235 offset:55296
	ds_read_b128 v[204:207], v235 offset:56320
	global_load_lds_dwordx4 v[208:209], off
	s_add_i32 m0, s26, 0x2000
	s_add_u32 s26, s30, 0xb0080
	v_lshl_add_u64 v[208:209], v[210:211], 0, s[20:21]
	s_addc_u32 s27, s31, 0
	s_add_i32 s30, s66, s43
	global_load_lds_dwordx4 v[208:209], off
	s_mov_b32 m0, s30
	v_lshl_add_u64 v[208:209], s[26:27], 0, v[186:187]
	global_load_lds_dwordx4 v[208:209], off
	s_add_i32 m0, s30, 0x2000
	v_lshl_add_u64 v[208:209], s[26:27], 0, v[190:191]
	global_load_lds_dwordx4 v[208:209], off
	s_mov_b32 m0, s49
	v_lshl_add_u64 v[208:209], v[212:213], 0, s[20:21]
	global_load_lds_dwordx4 v[208:209], off
	s_mov_b32 m0, s50
	v_lshl_add_u64 v[208:209], v[214:215], 0, s[20:21]
	global_load_lds_dwordx4 v[208:209], off
	s_waitcnt vmcnt(8) lgkmcnt(0)
	s_barrier
	s_setprio 1
	v_mfma_f32_16x16x32_bf16 v[60:63], v[120:123], v[160:163], v[60:63]
	v_mfma_f32_16x16x32_bf16 v[60:63], v[124:127], v[164:167], v[60:63]
	v_mfma_f32_16x16x32_bf16 v[44:47], v[124:127], v[172:175], v[44:47]
	v_mfma_f32_16x16x32_bf16 v[44:47], v[120:123], v[168:171], v[44:47]
	v_mfma_f32_16x16x32_bf16 v[28:31], v[120:123], v[176:179], v[28:31]
	v_mfma_f32_16x16x32_bf16 v[28:31], v[124:127], v[180:183], v[28:31]
	v_mfma_f32_16x16x32_bf16 v[12:15], v[124:127], v[204:207], v[12:15]
	v_mfma_f32_16x16x32_bf16 v[12:15], v[120:123], v[200:203], v[12:15]
	v_mfma_f32_16x16x32_bf16 v[56:59], v[136:139], v[160:163], v[56:59]
	v_mfma_f32_16x16x32_bf16 v[56:59], v[140:143], v[164:167], v[56:59]
	v_mfma_f32_16x16x32_bf16 v[40:43], v[140:143], v[172:175], v[40:43]
	v_mfma_f32_16x16x32_bf16 v[40:43], v[136:139], v[168:171], v[40:43]
	v_mfma_f32_16x16x32_bf16 v[24:27], v[136:139], v[176:179], v[24:27]
	v_mfma_f32_16x16x32_bf16 v[24:27], v[140:143], v[180:183], v[24:27]
	v_mfma_f32_16x16x32_bf16 v[8:11], v[140:143], v[204:207], v[8:11]
	v_mfma_f32_16x16x32_bf16 v[8:11], v[136:139], v[200:203], v[8:11]
	v_mfma_f32_16x16x32_bf16 v[52:55], v[144:147], v[160:163], v[52:55]
	v_mfma_f32_16x16x32_bf16 v[52:55], v[148:151], v[164:167], v[52:55]
	v_mfma_f32_16x16x32_bf16 v[36:39], v[148:151], v[172:175], v[36:39]
	v_mfma_f32_16x16x32_bf16 v[36:39], v[144:147], v[168:171], v[36:39]
	v_mfma_f32_16x16x32_bf16 v[20:23], v[144:147], v[176:179], v[20:23]
	v_mfma_f32_16x16x32_bf16 v[20:23], v[148:151], v[180:183], v[20:23]
	v_mfma_f32_16x16x32_bf16 v[4:7], v[148:151], v[204:207], v[4:7]
	v_mfma_f32_16x16x32_bf16 v[4:7], v[144:147], v[200:203], v[4:7]
	v_mfma_f32_16x16x32_bf16 v[48:51], v[152:155], v[160:163], v[48:51]
	v_mfma_f32_16x16x32_bf16 v[48:51], v[156:159], v[164:167], v[48:51]
	v_mfma_f32_16x16x32_bf16 v[32:35], v[156:159], v[172:175], v[32:35]
	v_mfma_f32_16x16x32_bf16 v[32:35], v[152:155], v[168:171], v[32:35]
	s_setprio 2
	s_barrier
	v_mfma_f32_16x16x32_bf16 v[16:19], v[152:155], v[176:179], v[16:19]
	v_mfma_f32_16x16x32_bf16 v[16:19], v[156:159], v[180:183], v[16:19]
	v_mfma_f32_16x16x32_bf16 v[0:3], v[156:159], v[204:207], v[0:3]
	v_mfma_f32_16x16x32_bf16 v[0:3], v[152:155], v[200:203], v[0:3]
	s_setprio 0
	s_add_i32 s64, s64, 2
	s_add_u32 s62, s62, 0x100
	s_addc_u32 s63, s63, 0
	s_cmp_gt_u32 s64, 41
	s_mov_b64 s[26:27], s[28:29]
.LBB0_866:
	ds_read_b128 v[120:123], v233
	ds_read_b128 v[124:127], v233 offset:1024
	ds_read_b128 v[136:139], v233 offset:2048
	ds_read_b128 v[140:143], v233 offset:3072
	ds_read_b128 v[144:147], v234
	ds_read_b128 v[148:151], v234 offset:1024
	ds_read_b128 v[152:155], v234 offset:2048
	ds_read_b128 v[156:159], v234 offset:3072
	s_add_u32 s28, s26, 0x100
	s_addc_u32 s29, s27, 0
	s_cmp_eq_u32 s64, 40
	s_cselect_b32 s37, s7, s29
	s_cselect_b32 s36, s6, s28
	s_cselect_b32 s31, s25, s63
	s_cselect_b32 s30, s24, s62
	v_lshl_add_u64 v[208:209], s[26:27], 0, v[192:193]
	s_add_i32 m0, s44, 0xc000
	ds_read_b128 v[160:163], v235
	ds_read_b128 v[164:167], v235 offset:1024
	ds_read_b128 v[168:171], v235 offset:2048
	ds_read_b128 v[172:175], v235 offset:3072
	ds_read_b128 v[176:179], v235 offset:4096
	ds_read_b128 v[180:183], v235 offset:5120
	ds_read_b128 v[200:203], v235 offset:6144
	ds_read_b128 v[204:207], v235 offset:7168
	global_load_lds_dwordx4 v[208:209], off
	s_add_i32 m0, s44, 0xe000
	v_lshl_add_u64 v[208:209], s[26:27], 0, v[194:195]
	global_load_lds_dwordx4 v[208:209], off
	s_waitcnt vmcnt(8) lgkmcnt(0)
	s_barrier
	s_setprio 1
	v_mfma_f32_16x16x32_bf16 v[132:135], v[120:123], v[160:163], v[132:135]
	v_mfma_f32_16x16x32_bf16 v[132:135], v[124:127], v[164:167], v[132:135]
	v_mfma_f32_16x16x32_bf16 v[108:111], v[124:127], v[172:175], v[108:111]
	v_mfma_f32_16x16x32_bf16 v[108:111], v[120:123], v[168:171], v[108:111]
	v_mfma_f32_16x16x32_bf16 v[92:95], v[120:123], v[176:179], v[92:95]
	v_mfma_f32_16x16x32_bf16 v[92:95], v[124:127], v[180:183], v[92:95]
	v_mfma_f32_16x16x32_bf16 v[76:79], v[124:127], v[204:207], v[76:79]
	v_mfma_f32_16x16x32_bf16 v[76:79], v[120:123], v[200:203], v[76:79]
	v_mfma_f32_16x16x32_bf16 v[128:131], v[136:139], v[160:163], v[128:131]
	v_mfma_f32_16x16x32_bf16 v[128:131], v[140:143], v[164:167], v[128:131]
	v_mfma_f32_16x16x32_bf16 v[104:107], v[140:143], v[172:175], v[104:107]
	v_mfma_f32_16x16x32_bf16 v[104:107], v[136:139], v[168:171], v[104:107]
	v_mfma_f32_16x16x32_bf16 v[88:91], v[136:139], v[176:179], v[88:91]
	v_mfma_f32_16x16x32_bf16 v[88:91], v[140:143], v[180:183], v[88:91]
	v_mfma_f32_16x16x32_bf16 v[72:75], v[140:143], v[204:207], v[72:75]
	v_mfma_f32_16x16x32_bf16 v[72:75], v[136:139], v[200:203], v[72:75]
	v_mfma_f32_16x16x32_bf16 v[116:119], v[144:147], v[160:163], v[116:119]
	v_mfma_f32_16x16x32_bf16 v[116:119], v[148:151], v[164:167], v[116:119]
	v_mfma_f32_16x16x32_bf16 v[100:103], v[148:151], v[172:175], v[100:103]
	v_mfma_f32_16x16x32_bf16 v[100:103], v[144:147], v[168:171], v[100:103]
	v_mfma_f32_16x16x32_bf16 v[84:87], v[144:147], v[176:179], v[84:87]
	v_mfma_f32_16x16x32_bf16 v[84:87], v[148:151], v[180:183], v[84:87]
	v_mfma_f32_16x16x32_bf16 v[68:71], v[148:151], v[204:207], v[68:71]
	v_mfma_f32_16x16x32_bf16 v[68:71], v[144:147], v[200:203], v[68:71]
	v_mfma_f32_16x16x32_bf16 v[112:115], v[152:155], v[160:163], v[112:115]
	v_mfma_f32_16x16x32_bf16 v[112:115], v[156:159], v[164:167], v[112:115]
	v_mfma_f32_16x16x32_bf16 v[96:99], v[156:159], v[172:175], v[96:99]
	v_mfma_f32_16x16x32_bf16 v[96:99], v[152:155], v[168:171], v[96:99]
	s_setprio 2
	s_barrier
	ds_read_b128 v[160:163], v235 offset:16384
	ds_read_b128 v[164:167], v235 offset:17408
	ds_read_b128 v[168:171], v235 offset:18432
	ds_read_b128 v[172:175], v235 offset:19456
	v_mfma_f32_16x16x32_bf16 v[80:83], v[152:155], v[176:179], v[80:83]
	v_mfma_f32_16x16x32_bf16 v[80:83], v[156:159], v[180:183], v[80:83]
	v_mfma_f32_16x16x32_bf16 v[64:67], v[156:159], v[204:207], v[64:67]
	v_mfma_f32_16x16x32_bf16 v[64:67], v[152:155], v[200:203], v[64:67]
	s_setprio 2
	s_add_i32 s26, s56, s43
	v_lshl_add_u64 v[208:209], s[30:31], 0, v[186:187]
	s_mov_b32 m0, s26
	ds_read_b128 v[176:179], v235 offset:20480
	ds_read_b128 v[180:183], v235 offset:21504
	ds_read_b128 v[200:203], v235 offset:22528
	ds_read_b128 v[204:207], v235 offset:23552
	global_load_lds_dwordx4 v[208:209], off
	s_add_i32 m0, s26, 0x2000
	s_add_u32 s26, s30, 0xb0000
	v_lshl_add_u64 v[210:211], s[30:31], 0, v[190:191]
	s_addc_u32 s27, s31, 0
	s_add_i32 s65, s57, s43
	global_load_lds_dwordx4 v[210:211], off
	v_lshl_add_u64 v[212:213], s[26:27], 0, v[186:187]
	s_mov_b32 m0, s65
	v_lshl_add_u64 v[214:215], s[36:37], 0, v[188:189]
	global_load_lds_dwordx4 v[212:213], off
	s_add_i32 m0, s65, 0x2000
	v_lshl_add_u64 v[212:213], s[26:27], 0, v[190:191]
	global_load_lds_dwordx4 v[212:213], off
	s_mov_b32 m0, s44
	v_lshl_add_u64 v[212:213], s[36:37], 0, v[184:185]
	global_load_lds_dwordx4 v[212:213], off
	s_mov_b32 m0, s45
	s_nop 0
	global_load_lds_dwordx4 v[214:215], off
	s_waitcnt vmcnt(8) lgkmcnt(0)
	s_barrier
	s_setprio 1
	v_mfma_f32_16x16x32_bf16 v[60:63], v[120:123], v[160:163], v[60:63]
	v_mfma_f32_16x16x32_bf16 v[60:63], v[124:127], v[164:167], v[60:63]
	v_mfma_f32_16x16x32_bf16 v[44:47], v[124:127], v[172:175], v[44:47]
	v_mfma_f32_16x16x32_bf16 v[44:47], v[120:123], v[168:171], v[44:47]
	v_mfma_f32_16x16x32_bf16 v[28:31], v[120:123], v[176:179], v[28:31]
	v_mfma_f32_16x16x32_bf16 v[28:31], v[124:127], v[180:183], v[28:31]
	v_mfma_f32_16x16x32_bf16 v[12:15], v[124:127], v[204:207], v[12:15]
	v_mfma_f32_16x16x32_bf16 v[12:15], v[120:123], v[200:203], v[12:15]
	v_mfma_f32_16x16x32_bf16 v[56:59], v[136:139], v[160:163], v[56:59]
	v_mfma_f32_16x16x32_bf16 v[56:59], v[140:143], v[164:167], v[56:59]
	v_mfma_f32_16x16x32_bf16 v[40:43], v[140:143], v[172:175], v[40:43]
	v_mfma_f32_16x16x32_bf16 v[40:43], v[136:139], v[168:171], v[40:43]
	v_mfma_f32_16x16x32_bf16 v[24:27], v[136:139], v[176:179], v[24:27]
	v_mfma_f32_16x16x32_bf16 v[24:27], v[140:143], v[180:183], v[24:27]
	v_mfma_f32_16x16x32_bf16 v[8:11], v[140:143], v[204:207], v[8:11]
	v_mfma_f32_16x16x32_bf16 v[8:11], v[136:139], v[200:203], v[8:11]
	v_mfma_f32_16x16x32_bf16 v[52:55], v[144:147], v[160:163], v[52:55]
	v_mfma_f32_16x16x32_bf16 v[52:55], v[148:151], v[164:167], v[52:55]
	v_mfma_f32_16x16x32_bf16 v[36:39], v[148:151], v[172:175], v[36:39]
	v_mfma_f32_16x16x32_bf16 v[36:39], v[144:147], v[168:171], v[36:39]
	v_mfma_f32_16x16x32_bf16 v[20:23], v[144:147], v[176:179], v[20:23]
	v_mfma_f32_16x16x32_bf16 v[20:23], v[148:151], v[180:183], v[20:23]
	v_mfma_f32_16x16x32_bf16 v[4:7], v[148:151], v[204:207], v[4:7]
	v_mfma_f32_16x16x32_bf16 v[4:7], v[144:147], v[200:203], v[4:7]
	v_mfma_f32_16x16x32_bf16 v[48:51], v[152:155], v[160:163], v[48:51]
	v_mfma_f32_16x16x32_bf16 v[48:51], v[156:159], v[164:167], v[48:51]
	v_mfma_f32_16x16x32_bf16 v[32:35], v[156:159], v[172:175], v[32:35]
	v_mfma_f32_16x16x32_bf16 v[32:35], v[152:155], v[168:171], v[32:35]
	s_setprio 2
	s_barrier
	ds_read_b128 v[160:163], v235 offset:32768
	ds_read_b128 v[164:167], v235 offset:33792
	ds_read_b128 v[168:171], v235 offset:34816
	ds_read_b128 v[172:175], v235 offset:35840
	v_mfma_f32_16x16x32_bf16 v[16:19], v[152:155], v[176:179], v[16:19]
	v_mfma_f32_16x16x32_bf16 v[16:19], v[156:159], v[180:183], v[16:19]
	v_mfma_f32_16x16x32_bf16 v[0:3], v[156:159], v[204:207], v[0:3]
	v_mfma_f32_16x16x32_bf16 v[0:3], v[152:155], v[200:203], v[0:3]
	s_setprio 0
	s_add_i32 s65, 0, 0x18000
	s_add_i32 s66, 0, 0x1c000
	v_add_u32_e32 v140, s65, v232
	v_add_u32_e32 v156, s66, v232
	ds_read_b128 v[120:123], v140
	ds_read_b128 v[124:127], v140 offset:1024
	ds_read_b128 v[136:139], v140 offset:2048
	ds_read_b128 v[140:143], v140 offset:3072
	ds_read_b128 v[144:147], v156
	ds_read_b128 v[148:151], v156 offset:1024
	ds_read_b128 v[152:155], v156 offset:2048
	ds_read_b128 v[156:159], v156 offset:3072
	s_add_u32 s26, s36, 0xb0000
	s_addc_u32 s27, s37, 0
	s_mov_b32 m0, s46
	v_lshl_add_u64 v[216:217], s[26:27], 0, v[184:185]
	ds_read_b128 v[176:179], v235 offset:36864
	ds_read_b128 v[180:183], v235 offset:37888
	ds_read_b128 v[200:203], v235 offset:38912
	ds_read_b128 v[204:207], v235 offset:39936
	global_load_lds_dwordx4 v[216:217], off
	s_mov_b32 m0, s47
	v_lshl_add_u64 v[216:217], s[26:27], 0, v[188:189]
	global_load_lds_dwordx4 v[216:217], off
	s_waitcnt vmcnt(8) lgkmcnt(0)
	s_barrier
	s_setprio 1
	v_mfma_f32_16x16x32_bf16 v[132:135], v[120:123], v[160:163], v[132:135]
	v_mfma_f32_16x16x32_bf16 v[132:135], v[124:127], v[164:167], v[132:135]
	v_mfma_f32_16x16x32_bf16 v[108:111], v[124:127], v[172:175], v[108:111]
	v_mfma_f32_16x16x32_bf16 v[108:111], v[120:123], v[168:171], v[108:111]
	v_mfma_f32_16x16x32_bf16 v[92:95], v[120:123], v[176:179], v[92:95]
	v_mfma_f32_16x16x32_bf16 v[92:95], v[124:127], v[180:183], v[92:95]
	v_mfma_f32_16x16x32_bf16 v[76:79], v[124:127], v[204:207], v[76:79]
	v_mfma_f32_16x16x32_bf16 v[76:79], v[120:123], v[200:203], v[76:79]
	v_mfma_f32_16x16x32_bf16 v[128:131], v[136:139], v[160:163], v[128:131]
	v_mfma_f32_16x16x32_bf16 v[128:131], v[140:143], v[164:167], v[128:131]
	v_mfma_f32_16x16x32_bf16 v[104:107], v[140:143], v[172:175], v[104:107]
	v_mfma_f32_16x16x32_bf16 v[104:107], v[136:139], v[168:171], v[104:107]
	v_mfma_f32_16x16x32_bf16 v[88:91], v[136:139], v[176:179], v[88:91]
	v_mfma_f32_16x16x32_bf16 v[88:91], v[140:143], v[180:183], v[88:91]
	v_mfma_f32_16x16x32_bf16 v[72:75], v[140:143], v[204:207], v[72:75]
	v_mfma_f32_16x16x32_bf16 v[72:75], v[136:139], v[200:203], v[72:75]
	v_mfma_f32_16x16x32_bf16 v[116:119], v[144:147], v[160:163], v[116:119]
	v_mfma_f32_16x16x32_bf16 v[116:119], v[148:151], v[164:167], v[116:119]
	v_mfma_f32_16x16x32_bf16 v[100:103], v[148:151], v[172:175], v[100:103]
	v_mfma_f32_16x16x32_bf16 v[100:103], v[144:147], v[168:171], v[100:103]
	v_mfma_f32_16x16x32_bf16 v[84:87], v[144:147], v[176:179], v[84:87]
	v_mfma_f32_16x16x32_bf16 v[84:87], v[148:151], v[180:183], v[84:87]
	v_mfma_f32_16x16x32_bf16 v[68:71], v[148:151], v[204:207], v[68:71]
	v_mfma_f32_16x16x32_bf16 v[68:71], v[144:147], v[200:203], v[68:71]
	v_mfma_f32_16x16x32_bf16 v[112:115], v[152:155], v[160:163], v[112:115]
	v_mfma_f32_16x16x32_bf16 v[112:115], v[156:159], v[164:167], v[112:115]
	v_mfma_f32_16x16x32_bf16 v[96:99], v[156:159], v[172:175], v[96:99]
	v_mfma_f32_16x16x32_bf16 v[96:99], v[152:155], v[168:171], v[96:99]
	s_setprio 2
	s_barrier
	ds_read_b128 v[160:163], v235 offset:49152
	ds_read_b128 v[164:167], v235 offset:50176
	ds_read_b128 v[168:171], v235 offset:51200
	ds_read_b128 v[172:175], v235 offset:52224
	v_mfma_f32_16x16x32_bf16 v[80:83], v[152:155], v[176:179], v[80:83]
	v_mfma_f32_16x16x32_bf16 v[80:83], v[156:159], v[180:183], v[80:83]
	v_mfma_f32_16x16x32_bf16 v[64:67], v[156:159], v[204:207], v[64:67]
	v_mfma_f32_16x16x32_bf16 v[64:67], v[152:155], v[200:203], v[64:67]
	s_setprio 2
	s_add_i32 s26, s65, s43
	v_lshl_add_u64 v[208:209], v[208:209], 0, s[20:21]
	s_mov_b32 m0, s26
	ds_read_b128 v[176:179], v235 offset:53248
	ds_read_b128 v[180:183], v235 offset:54272
	ds_read_b128 v[200:203], v235 offset:55296
	ds_read_b128 v[204:207], v235 offset:56320
	global_load_lds_dwordx4 v[208:209], off
	s_add_i32 m0, s26, 0x2000
	s_add_u32 s26, s30, 0xb0080
	v_lshl_add_u64 v[208:209], v[210:211], 0, s[20:21]
	s_addc_u32 s27, s31, 0
	s_add_i32 s30, s66, s43
	global_load_lds_dwordx4 v[208:209], off
	s_mov_b32 m0, s30
	v_lshl_add_u64 v[208:209], s[26:27], 0, v[186:187]
	global_load_lds_dwordx4 v[208:209], off
	s_add_i32 m0, s30, 0x2000
	v_lshl_add_u64 v[208:209], s[26:27], 0, v[190:191]
	global_load_lds_dwordx4 v[208:209], off
	s_mov_b32 m0, s49
	v_lshl_add_u64 v[208:209], v[212:213], 0, s[20:21]
	global_load_lds_dwordx4 v[208:209], off
	s_mov_b32 m0, s50
	v_lshl_add_u64 v[208:209], v[214:215], 0, s[20:21]
	global_load_lds_dwordx4 v[208:209], off
	s_waitcnt vmcnt(8) lgkmcnt(0)
	s_barrier
	s_setprio 1
	v_mfma_f32_16x16x32_bf16 v[60:63], v[120:123], v[160:163], v[60:63]
	v_mfma_f32_16x16x32_bf16 v[60:63], v[124:127], v[164:167], v[60:63]
	v_mfma_f32_16x16x32_bf16 v[44:47], v[124:127], v[172:175], v[44:47]
	v_mfma_f32_16x16x32_bf16 v[44:47], v[120:123], v[168:171], v[44:47]
	v_mfma_f32_16x16x32_bf16 v[28:31], v[120:123], v[176:179], v[28:31]
	v_mfma_f32_16x16x32_bf16 v[28:31], v[124:127], v[180:183], v[28:31]
	v_mfma_f32_16x16x32_bf16 v[12:15], v[124:127], v[204:207], v[12:15]
	v_mfma_f32_16x16x32_bf16 v[12:15], v[120:123], v[200:203], v[12:15]
	v_mfma_f32_16x16x32_bf16 v[56:59], v[136:139], v[160:163], v[56:59]
	v_mfma_f32_16x16x32_bf16 v[56:59], v[140:143], v[164:167], v[56:59]
	v_mfma_f32_16x16x32_bf16 v[40:43], v[140:143], v[172:175], v[40:43]
	v_mfma_f32_16x16x32_bf16 v[40:43], v[136:139], v[168:171], v[40:43]
	v_mfma_f32_16x16x32_bf16 v[24:27], v[136:139], v[176:179], v[24:27]
	v_mfma_f32_16x16x32_bf16 v[24:27], v[140:143], v[180:183], v[24:27]
	v_mfma_f32_16x16x32_bf16 v[8:11], v[140:143], v[204:207], v[8:11]
	v_mfma_f32_16x16x32_bf16 v[8:11], v[136:139], v[200:203], v[8:11]
	v_mfma_f32_16x16x32_bf16 v[52:55], v[144:147], v[160:163], v[52:55]
	v_mfma_f32_16x16x32_bf16 v[52:55], v[148:151], v[164:167], v[52:55]
	v_mfma_f32_16x16x32_bf16 v[36:39], v[148:151], v[172:175], v[36:39]
	v_mfma_f32_16x16x32_bf16 v[36:39], v[144:147], v[168:171], v[36:39]
	v_mfma_f32_16x16x32_bf16 v[20:23], v[144:147], v[176:179], v[20:23]
	v_mfma_f32_16x16x32_bf16 v[20:23], v[148:151], v[180:183], v[20:23]
	v_mfma_f32_16x16x32_bf16 v[4:7], v[148:151], v[204:207], v[4:7]
	v_mfma_f32_16x16x32_bf16 v[4:7], v[144:147], v[200:203], v[4:7]
	v_mfma_f32_16x16x32_bf16 v[48:51], v[152:155], v[160:163], v[48:51]
	v_mfma_f32_16x16x32_bf16 v[48:51], v[156:159], v[164:167], v[48:51]
	v_mfma_f32_16x16x32_bf16 v[32:35], v[156:159], v[172:175], v[32:35]
	v_mfma_f32_16x16x32_bf16 v[32:35], v[152:155], v[168:171], v[32:35]
	s_setprio 2
	s_barrier
	v_mfma_f32_16x16x32_bf16 v[16:19], v[152:155], v[176:179], v[16:19]
	v_mfma_f32_16x16x32_bf16 v[16:19], v[156:159], v[180:183], v[16:19]
	v_mfma_f32_16x16x32_bf16 v[0:3], v[156:159], v[204:207], v[0:3]
	v_mfma_f32_16x16x32_bf16 v[0:3], v[152:155], v[200:203], v[0:3]
	s_setprio 0
	s_add_i32 s64, s64, 2
	s_add_u32 s62, s62, 0x100
	s_addc_u32 s63, s63, 0
	s_cmp_gt_u32 s64, 41
	s_mov_b64 s[26:27], s[28:29]
	s_cbranch_scc0 .LBB0_866

.LBB0_951:
	s_ashr_i32 s27, s26, 31
	s_lshl_b64 s[30:31], s[26:27], 19
	s_add_u32 s30, s47, s30
	s_addc_u32 s31, s48, s31
	s_and_b64 s[36:37], s[4:5], exec
	s_cselect_b32 s27, s31, s7
	s_cselect_b32 s39, s30, s6
	s_ashr_i32 s29, s28, 31
	s_lshl_b64 s[36:37], s[28:29], 19
	s_add_u32 s36, s49, s36
	s_addc_u32 s37, s50, s37
	s_and_b64 s[44:45], s[4:5], exec
	s_cselect_b32 s29, s37, s41
	s_cselect_b32 s43, s36, s40
	s_add_u32 s6, s6, 0x40080
	s_addc_u32 s7, s7, 0
	s_add_u32 s71, s40, 0x100
	s_addc_u32 s72, s41, 0
	s_mov_b32 s73, -2
	ds_read_b128 v[144:147], v179
	ds_read_b128 v[148:151], v179 offset:1024
	ds_read_b128 v[152:155], v179 offset:2048
	ds_read_b128 v[156:159], v179 offset:3072
	ds_read_b128 v[160:163], v180
	ds_read_b128 v[164:167], v180 offset:1024
	ds_read_b128 v[168:171], v180 offset:2048
	ds_read_b128 v[172:175], v180 offset:3072
	s_add_u32 s40, s6, 0xfffc0080
	s_addc_u32 s41, s7, -1
	s_cmp_eq_u32 s73, 12
	s_cselect_b32 s45, s27, s41
	s_cselect_b32 s44, s39, s40
	s_cselect_b32 s41, s29, s72
	s_cselect_b32 s40, s43, s71
	v_lshl_add_u64 v[176:177], s[6:7], 0, v[136:137]
	s_add_i32 m0, s54, 0xc000
	ds_read_b128 v[184:187], v181
	ds_read_b128 v[188:191], v181 offset:1024
	ds_read_b128 v[192:195], v181 offset:2048
	ds_read_b128 v[196:199], v181 offset:3072
	ds_read_b128 v[200:203], v181 offset:4096
	ds_read_b128 v[204:207], v181 offset:5120
	ds_read_b128 v[208:211], v181 offset:6144
	ds_read_b128 v[212:215], v181 offset:7168
	global_load_lds_dwordx4 v[176:177], off
	s_add_i32 m0, s54, 0xe000
	v_lshl_add_u64 v[176:177], s[6:7], 0, v[138:139]
	global_load_lds_dwordx4 v[176:177], off
	s_waitcnt vmcnt(8) lgkmcnt(0)
	s_barrier
	s_setprio 1
	v_mfma_f32_16x16x32_bf16 v[124:127], v[144:147], v[184:187], 0
	v_mfma_f32_16x16x32_bf16 v[124:127], v[148:151], v[188:191], v[124:127]
	v_mfma_f32_16x16x32_bf16 v[108:111], v[148:151], v[196:199], 0
	v_mfma_f32_16x16x32_bf16 v[108:111], v[144:147], v[192:195], v[108:111]
	v_mfma_f32_16x16x32_bf16 v[92:95], v[144:147], v[200:203], 0
	v_mfma_f32_16x16x32_bf16 v[92:95], v[148:151], v[204:207], v[92:95]
	v_mfma_f32_16x16x32_bf16 v[76:79], v[148:151], v[212:215], 0
	v_mfma_f32_16x16x32_bf16 v[76:79], v[144:147], v[208:211], v[76:79]
	v_mfma_f32_16x16x32_bf16 v[120:123], v[152:155], v[184:187], 0
	v_mfma_f32_16x16x32_bf16 v[120:123], v[156:159], v[188:191], v[120:123]
	v_mfma_f32_16x16x32_bf16 v[104:107], v[156:159], v[196:199], 0
	v_mfma_f32_16x16x32_bf16 v[104:107], v[152:155], v[192:195], v[104:107]
	v_mfma_f32_16x16x32_bf16 v[88:91], v[152:155], v[200:203], 0
	v_mfma_f32_16x16x32_bf16 v[88:91], v[156:159], v[204:207], v[88:91]
	v_mfma_f32_16x16x32_bf16 v[72:75], v[156:159], v[212:215], 0
	v_mfma_f32_16x16x32_bf16 v[72:75], v[152:155], v[208:211], v[72:75]
	v_mfma_f32_16x16x32_bf16 v[116:119], v[160:163], v[184:187], 0
	v_mfma_f32_16x16x32_bf16 v[116:119], v[164:167], v[188:191], v[116:119]
	v_mfma_f32_16x16x32_bf16 v[100:103], v[164:167], v[196:199], 0
	v_mfma_f32_16x16x32_bf16 v[100:103], v[160:163], v[192:195], v[100:103]
	v_mfma_f32_16x16x32_bf16 v[84:87], v[160:163], v[200:203], 0
	v_mfma_f32_16x16x32_bf16 v[84:87], v[164:167], v[204:207], v[84:87]
	v_mfma_f32_16x16x32_bf16 v[68:71], v[164:167], v[212:215], 0
	v_mfma_f32_16x16x32_bf16 v[68:71], v[160:163], v[208:211], v[68:71]
	v_mfma_f32_16x16x32_bf16 v[112:115], v[168:171], v[184:187], 0
	v_mfma_f32_16x16x32_bf16 v[112:115], v[172:175], v[188:191], v[112:115]
	v_mfma_f32_16x16x32_bf16 v[96:99], v[172:175], v[196:199], 0
	v_mfma_f32_16x16x32_bf16 v[96:99], v[168:171], v[192:195], v[96:99]
	s_setprio 2
	s_barrier
	ds_read_b128 v[184:187], v181 offset:16384
	ds_read_b128 v[188:191], v181 offset:17408
	ds_read_b128 v[192:195], v181 offset:18432
	ds_read_b128 v[196:199], v181 offset:19456
	v_mfma_f32_16x16x32_bf16 v[80:83], v[168:171], v[200:203], 0
	v_mfma_f32_16x16x32_bf16 v[80:83], v[172:175], v[204:207], v[80:83]
	v_mfma_f32_16x16x32_bf16 v[64:67], v[172:175], v[212:215], 0
	v_mfma_f32_16x16x32_bf16 v[64:67], v[168:171], v[208:211], v[64:67]
	s_setprio 2
	s_add_i32 s74, s69, s51
	v_lshl_add_u64 v[176:177], s[40:41], 0, v[130:131]
	s_mov_b32 m0, s74
	ds_read_b128 v[200:203], v181 offset:20480
	ds_read_b128 v[204:207], v181 offset:21504
	ds_read_b128 v[208:211], v181 offset:22528
	ds_read_b128 v[212:215], v181 offset:23552
	global_load_lds_dwordx4 v[176:177], off
	s_add_i32 m0, s74, 0x2000
	s_add_u32 s74, s40, 0x40000
	v_lshl_add_u64 v[216:217], s[40:41], 0, v[134:135]
	s_addc_u32 s75, s41, 0
	s_add_i32 s76, s70, s51
	global_load_lds_dwordx4 v[216:217], off
	v_lshl_add_u64 v[218:219], s[74:75], 0, v[130:131]
	s_mov_b32 m0, s76
	v_lshl_add_u64 v[220:221], s[44:45], 0, v[132:133]
	global_load_lds_dwordx4 v[218:219], off
	s_add_i32 m0, s76, 0x2000
	v_lshl_add_u64 v[218:219], s[74:75], 0, v[134:135]
	global_load_lds_dwordx4 v[218:219], off
	s_mov_b32 m0, s54
	v_lshl_add_u64 v[218:219], s[44:45], 0, v[128:129]
	global_load_lds_dwordx4 v[218:219], off
	s_mov_b32 m0, s55
	s_nop 0
	global_load_lds_dwordx4 v[220:221], off
	s_waitcnt vmcnt(8) lgkmcnt(0)
	s_barrier
	s_setprio 1
	v_mfma_f32_16x16x32_bf16 v[60:63], v[144:147], v[184:187], 0
	v_mfma_f32_16x16x32_bf16 v[60:63], v[148:151], v[188:191], v[60:63]
	v_mfma_f32_16x16x32_bf16 v[44:47], v[148:151], v[196:199], 0
	v_mfma_f32_16x16x32_bf16 v[44:47], v[144:147], v[192:195], v[44:47]
	v_mfma_f32_16x16x32_bf16 v[28:31], v[144:147], v[200:203], 0
	v_mfma_f32_16x16x32_bf16 v[28:31], v[148:151], v[204:207], v[28:31]
	v_mfma_f32_16x16x32_bf16 v[12:15], v[148:151], v[212:215], 0
	v_mfma_f32_16x16x32_bf16 v[12:15], v[144:147], v[208:211], v[12:15]
	v_mfma_f32_16x16x32_bf16 v[56:59], v[152:155], v[184:187], 0
	v_mfma_f32_16x16x32_bf16 v[56:59], v[156:159], v[188:191], v[56:59]
	v_mfma_f32_16x16x32_bf16 v[40:43], v[156:159], v[196:199], 0
	v_mfma_f32_16x16x32_bf16 v[40:43], v[152:155], v[192:195], v[40:43]
	v_mfma_f32_16x16x32_bf16 v[24:27], v[152:155], v[200:203], 0
	v_mfma_f32_16x16x32_bf16 v[24:27], v[156:159], v[204:207], v[24:27]
	v_mfma_f32_16x16x32_bf16 v[8:11], v[156:159], v[212:215], 0
	v_mfma_f32_16x16x32_bf16 v[8:11], v[152:155], v[208:211], v[8:11]
	v_mfma_f32_16x16x32_bf16 v[52:55], v[160:163], v[184:187], 0
	v_mfma_f32_16x16x32_bf16 v[52:55], v[164:167], v[188:191], v[52:55]
	v_mfma_f32_16x16x32_bf16 v[36:39], v[164:167], v[196:199], 0
	v_mfma_f32_16x16x32_bf16 v[36:39], v[160:163], v[192:195], v[36:39]
	v_mfma_f32_16x16x32_bf16 v[20:23], v[160:163], v[200:203], 0
	v_mfma_f32_16x16x32_bf16 v[20:23], v[164:167], v[204:207], v[20:23]
	v_mfma_f32_16x16x32_bf16 v[4:7], v[164:167], v[212:215], 0
	v_mfma_f32_16x16x32_bf16 v[4:7], v[160:163], v[208:211], v[4:7]
	v_mfma_f32_16x16x32_bf16 v[48:51], v[168:171], v[184:187], 0
	v_mfma_f32_16x16x32_bf16 v[48:51], v[172:175], v[188:191], v[48:51]
	v_mfma_f32_16x16x32_bf16 v[32:35], v[172:175], v[196:199], 0
	v_mfma_f32_16x16x32_bf16 v[32:35], v[168:171], v[192:195], v[32:35]
	s_setprio 2
	s_barrier
	ds_read_b128 v[184:187], v181 offset:32768
	ds_read_b128 v[188:191], v181 offset:33792
	ds_read_b128 v[192:195], v181 offset:34816
	ds_read_b128 v[196:199], v181 offset:35840
	v_mfma_f32_16x16x32_bf16 v[16:19], v[168:171], v[200:203], 0
	v_mfma_f32_16x16x32_bf16 v[16:19], v[172:175], v[204:207], v[16:19]
	v_mfma_f32_16x16x32_bf16 v[0:3], v[172:175], v[212:215], 0
	v_mfma_f32_16x16x32_bf16 v[0:3], v[168:171], v[208:211], v[0:3]
	s_setprio 0
	s_add_i32 s74, 0, 0x18000
	s_add_i32 s75, 0, 0x1c000
	v_add_u32_e32 v156, s74, v178
	v_add_u32_e32 v172, s75, v178
	ds_read_b128 v[144:147], v156
	ds_read_b128 v[148:151], v156 offset:1024
	ds_read_b128 v[152:155], v156 offset:2048
	ds_read_b128 v[156:159], v156 offset:3072
	ds_read_b128 v[160:163], v172
	ds_read_b128 v[164:167], v172 offset:1024
	ds_read_b128 v[168:171], v172 offset:2048
	ds_read_b128 v[172:175], v172 offset:3072
	s_add_u32 s44, s44, 0x40000
	s_addc_u32 s45, s45, 0
	s_mov_b32 m0, s56
	v_lshl_add_u64 v[222:223], s[44:45], 0, v[128:129]
	ds_read_b128 v[200:203], v181 offset:36864
	ds_read_b128 v[204:207], v181 offset:37888
	ds_read_b128 v[208:211], v181 offset:38912
	ds_read_b128 v[212:215], v181 offset:39936
	global_load_lds_dwordx4 v[222:223], off
	s_mov_b32 m0, s57
	v_lshl_add_u64 v[222:223], s[44:45], 0, v[132:133]
	global_load_lds_dwordx4 v[222:223], off
	s_waitcnt vmcnt(8) lgkmcnt(0)
	s_barrier
	s_setprio 1
	v_mfma_f32_16x16x32_bf16 v[124:127], v[144:147], v[184:187], v[124:127]
	v_mfma_f32_16x16x32_bf16 v[124:127], v[148:151], v[188:191], v[124:127]
	v_mfma_f32_16x16x32_bf16 v[108:111], v[148:151], v[196:199], v[108:111]
	v_mfma_f32_16x16x32_bf16 v[108:111], v[144:147], v[192:195], v[108:111]
	v_mfma_f32_16x16x32_bf16 v[92:95], v[144:147], v[200:203], v[92:95]
	v_mfma_f32_16x16x32_bf16 v[92:95], v[148:151], v[204:207], v[92:95]
	v_mfma_f32_16x16x32_bf16 v[76:79], v[148:151], v[212:215], v[76:79]
	v_mfma_f32_16x16x32_bf16 v[76:79], v[144:147], v[208:211], v[76:79]
	v_mfma_f32_16x16x32_bf16 v[120:123], v[152:155], v[184:187], v[120:123]
	v_mfma_f32_16x16x32_bf16 v[120:123], v[156:159], v[188:191], v[120:123]
	v_mfma_f32_16x16x32_bf16 v[104:107], v[156:159], v[196:199], v[104:107]
	v_mfma_f32_16x16x32_bf16 v[104:107], v[152:155], v[192:195], v[104:107]
	v_mfma_f32_16x16x32_bf16 v[88:91], v[152:155], v[200:203], v[88:91]
	v_mfma_f32_16x16x32_bf16 v[88:91], v[156:159], v[204:207], v[88:91]
	v_mfma_f32_16x16x32_bf16 v[72:75], v[156:159], v[212:215], v[72:75]
	v_mfma_f32_16x16x32_bf16 v[72:75], v[152:155], v[208:211], v[72:75]
	v_mfma_f32_16x16x32_bf16 v[116:119], v[160:163], v[184:187], v[116:119]
	v_mfma_f32_16x16x32_bf16 v[116:119], v[164:167], v[188:191], v[116:119]
	v_mfma_f32_16x16x32_bf16 v[100:103], v[164:167], v[196:199], v[100:103]
	v_mfma_f32_16x16x32_bf16 v[100:103], v[160:163], v[192:195], v[100:103]
	v_mfma_f32_16x16x32_bf16 v[84:87], v[160:163], v[200:203], v[84:87]
	v_mfma_f32_16x16x32_bf16 v[84:87], v[164:167], v[204:207], v[84:87]
	v_mfma_f32_16x16x32_bf16 v[68:71], v[164:167], v[212:215], v[68:71]
	v_mfma_f32_16x16x32_bf16 v[68:71], v[160:163], v[208:211], v[68:71]
	v_mfma_f32_16x16x32_bf16 v[112:115], v[168:171], v[184:187], v[112:115]
	v_mfma_f32_16x16x32_bf16 v[112:115], v[172:175], v[188:191], v[112:115]
	v_mfma_f32_16x16x32_bf16 v[96:99], v[172:175], v[196:199], v[96:99]
	v_mfma_f32_16x16x32_bf16 v[96:99], v[168:171], v[192:195], v[96:99]
	s_setprio 2
	s_barrier
	ds_read_b128 v[184:187], v181 offset:49152
	ds_read_b128 v[188:191], v181 offset:50176
	ds_read_b128 v[192:195], v181 offset:51200
	ds_read_b128 v[196:199], v181 offset:52224
	v_mfma_f32_16x16x32_bf16 v[80:83], v[168:171], v[200:203], v[80:83]
	v_mfma_f32_16x16x32_bf16 v[80:83], v[172:175], v[204:207], v[80:83]
	v_mfma_f32_16x16x32_bf16 v[64:67], v[172:175], v[212:215], v[64:67]
	v_mfma_f32_16x16x32_bf16 v[64:67], v[168:171], v[208:211], v[64:67]
	s_setprio 2
	s_add_i32 s44, s74, s51
	v_lshl_add_u64 v[176:177], v[176:177], 0, s[22:23]
	s_mov_b32 m0, s44
	ds_read_b128 v[200:203], v181 offset:53248
	ds_read_b128 v[204:207], v181 offset:54272
	ds_read_b128 v[208:211], v181 offset:55296
	ds_read_b128 v[212:215], v181 offset:56320
	global_load_lds_dwordx4 v[176:177], off
	s_add_i32 m0, s44, 0x2000
	s_add_u32 s40, s40, 0x40080
	v_lshl_add_u64 v[176:177], v[216:217], 0, s[22:23]
	s_addc_u32 s41, s41, 0
	s_add_i32 s44, s75, s51
	global_load_lds_dwordx4 v[176:177], off
	s_mov_b32 m0, s44
	v_lshl_add_u64 v[176:177], s[40:41], 0, v[130:131]
	global_load_lds_dwordx4 v[176:177], off
	s_add_i32 m0, s44, 0x2000
	v_lshl_add_u64 v[176:177], s[40:41], 0, v[134:135]
	global_load_lds_dwordx4 v[176:177], off
	s_mov_b32 m0, s64
	v_lshl_add_u64 v[176:177], v[218:219], 0, s[22:23]
	global_load_lds_dwordx4 v[176:177], off
	s_mov_b32 m0, s65
	v_lshl_add_u64 v[176:177], v[220:221], 0, s[22:23]
	global_load_lds_dwordx4 v[176:177], off
	s_waitcnt vmcnt(8) lgkmcnt(0)
	s_barrier
	s_setprio 1
	v_mfma_f32_16x16x32_bf16 v[60:63], v[144:147], v[184:187], v[60:63]
	v_mfma_f32_16x16x32_bf16 v[60:63], v[148:151], v[188:191], v[60:63]
	v_mfma_f32_16x16x32_bf16 v[44:47], v[148:151], v[196:199], v[44:47]
	v_mfma_f32_16x16x32_bf16 v[44:47], v[144:147], v[192:195], v[44:47]
	v_mfma_f32_16x16x32_bf16 v[28:31], v[144:147], v[200:203], v[28:31]
	v_mfma_f32_16x16x32_bf16 v[28:31], v[148:151], v[204:207], v[28:31]
	v_mfma_f32_16x16x32_bf16 v[12:15], v[148:151], v[212:215], v[12:15]
	v_mfma_f32_16x16x32_bf16 v[12:15], v[144:147], v[208:211], v[12:15]
	v_mfma_f32_16x16x32_bf16 v[56:59], v[152:155], v[184:187], v[56:59]
	v_mfma_f32_16x16x32_bf16 v[56:59], v[156:159], v[188:191], v[56:59]
	v_mfma_f32_16x16x32_bf16 v[40:43], v[156:159], v[196:199], v[40:43]
	v_mfma_f32_16x16x32_bf16 v[40:43], v[152:155], v[192:195], v[40:43]
	v_mfma_f32_16x16x32_bf16 v[24:27], v[152:155], v[200:203], v[24:27]
	v_mfma_f32_16x16x32_bf16 v[24:27], v[156:159], v[204:207], v[24:27]
	v_mfma_f32_16x16x32_bf16 v[8:11], v[156:159], v[212:215], v[8:11]
	v_mfma_f32_16x16x32_bf16 v[8:11], v[152:155], v[208:211], v[8:11]
	v_mfma_f32_16x16x32_bf16 v[52:55], v[160:163], v[184:187], v[52:55]
	v_mfma_f32_16x16x32_bf16 v[52:55], v[164:167], v[188:191], v[52:55]
	v_mfma_f32_16x16x32_bf16 v[36:39], v[164:167], v[196:199], v[36:39]
	v_mfma_f32_16x16x32_bf16 v[36:39], v[160:163], v[192:195], v[36:39]
	v_mfma_f32_16x16x32_bf16 v[20:23], v[160:163], v[200:203], v[20:23]
	v_mfma_f32_16x16x32_bf16 v[20:23], v[164:167], v[204:207], v[20:23]
	v_mfma_f32_16x16x32_bf16 v[4:7], v[164:167], v[212:215], v[4:7]
	v_mfma_f32_16x16x32_bf16 v[4:7], v[160:163], v[208:211], v[4:7]
	v_mfma_f32_16x16x32_bf16 v[48:51], v[168:171], v[184:187], v[48:51]
	v_mfma_f32_16x16x32_bf16 v[48:51], v[172:175], v[188:191], v[48:51]
	v_mfma_f32_16x16x32_bf16 v[32:35], v[172:175], v[196:199], v[32:35]
	v_mfma_f32_16x16x32_bf16 v[32:35], v[168:171], v[192:195], v[32:35]
	s_setprio 2
	s_barrier
	v_mfma_f32_16x16x32_bf16 v[16:19], v[168:171], v[200:203], v[16:19]
	v_mfma_f32_16x16x32_bf16 v[16:19], v[172:175], v[204:207], v[16:19]
	v_mfma_f32_16x16x32_bf16 v[0:3], v[172:175], v[212:215], v[0:3]
	v_mfma_f32_16x16x32_bf16 v[0:3], v[168:171], v[208:211], v[0:3]
	s_setprio 0
	s_add_i32 s73, s73, 2
	s_add_u32 s6, s6, 0x100
	s_addc_u32 s7, s7, 0
	s_add_u32 s71, s71, 0x100
	s_addc_u32 s72, s72, 0
	s_cmp_gt_u32 s73, 13
.LBB0_952:
	ds_read_b128 v[144:147], v179
	ds_read_b128 v[148:151], v179 offset:1024
	ds_read_b128 v[152:155], v179 offset:2048
	ds_read_b128 v[156:159], v179 offset:3072
	ds_read_b128 v[160:163], v180
	ds_read_b128 v[164:167], v180 offset:1024
	ds_read_b128 v[168:171], v180 offset:2048
	ds_read_b128 v[172:175], v180 offset:3072
	s_add_u32 s40, s6, 0xfffc0080
	s_addc_u32 s41, s7, -1
	s_cmp_eq_u32 s73, 12
	s_cselect_b32 s45, s27, s41
	s_cselect_b32 s44, s39, s40
	s_cselect_b32 s41, s29, s72
	s_cselect_b32 s40, s43, s71
	v_lshl_add_u64 v[176:177], s[6:7], 0, v[136:137]
	s_add_i32 m0, s54, 0xc000
	ds_read_b128 v[184:187], v181
	ds_read_b128 v[188:191], v181 offset:1024
	ds_read_b128 v[192:195], v181 offset:2048
	ds_read_b128 v[196:199], v181 offset:3072
	ds_read_b128 v[200:203], v181 offset:4096
	ds_read_b128 v[204:207], v181 offset:5120
	ds_read_b128 v[208:211], v181 offset:6144
	ds_read_b128 v[212:215], v181 offset:7168
	global_load_lds_dwordx4 v[176:177], off
	s_add_i32 m0, s54, 0xe000
	v_lshl_add_u64 v[176:177], s[6:7], 0, v[138:139]
	global_load_lds_dwordx4 v[176:177], off
	s_waitcnt vmcnt(8) lgkmcnt(0)
	s_barrier
	s_setprio 1
	v_mfma_f32_16x16x32_bf16 v[124:127], v[144:147], v[184:187], v[124:127]
	v_mfma_f32_16x16x32_bf16 v[124:127], v[148:151], v[188:191], v[124:127]
	v_mfma_f32_16x16x32_bf16 v[108:111], v[148:151], v[196:199], v[108:111]
	v_mfma_f32_16x16x32_bf16 v[108:111], v[144:147], v[192:195], v[108:111]
	v_mfma_f32_16x16x32_bf16 v[92:95], v[144:147], v[200:203], v[92:95]
	v_mfma_f32_16x16x32_bf16 v[92:95], v[148:151], v[204:207], v[92:95]
	v_mfma_f32_16x16x32_bf16 v[76:79], v[148:151], v[212:215], v[76:79]
	v_mfma_f32_16x16x32_bf16 v[76:79], v[144:147], v[208:211], v[76:79]
	v_mfma_f32_16x16x32_bf16 v[120:123], v[152:155], v[184:187], v[120:123]
	v_mfma_f32_16x16x32_bf16 v[120:123], v[156:159], v[188:191], v[120:123]
	v_mfma_f32_16x16x32_bf16 v[104:107], v[156:159], v[196:199], v[104:107]
	v_mfma_f32_16x16x32_bf16 v[104:107], v[152:155], v[192:195], v[104:107]
	v_mfma_f32_16x16x32_bf16 v[88:91], v[152:155], v[200:203], v[88:91]
	v_mfma_f32_16x16x32_bf16 v[88:91], v[156:159], v[204:207], v[88:91]
	v_mfma_f32_16x16x32_bf16 v[72:75], v[156:159], v[212:215], v[72:75]
	v_mfma_f32_16x16x32_bf16 v[72:75], v[152:155], v[208:211], v[72:75]
	v_mfma_f32_16x16x32_bf16 v[116:119], v[160:163], v[184:187], v[116:119]
	v_mfma_f32_16x16x32_bf16 v[116:119], v[164:167], v[188:191], v[116:119]
	v_mfma_f32_16x16x32_bf16 v[100:103], v[164:167], v[196:199], v[100:103]
	v_mfma_f32_16x16x32_bf16 v[100:103], v[160:163], v[192:195], v[100:103]
	v_mfma_f32_16x16x32_bf16 v[84:87], v[160:163], v[200:203], v[84:87]
	v_mfma_f32_16x16x32_bf16 v[84:87], v[164:167], v[204:207], v[84:87]
	v_mfma_f32_16x16x32_bf16 v[68:71], v[164:167], v[212:215], v[68:71]
	v_mfma_f32_16x16x32_bf16 v[68:71], v[160:163], v[208:211], v[68:71]
	v_mfma_f32_16x16x32_bf16 v[112:115], v[168:171], v[184:187], v[112:115]
	v_mfma_f32_16x16x32_bf16 v[112:115], v[172:175], v[188:191], v[112:115]
	v_mfma_f32_16x16x32_bf16 v[96:99], v[172:175], v[196:199], v[96:99]
	v_mfma_f32_16x16x32_bf16 v[96:99], v[168:171], v[192:195], v[96:99]
	s_setprio 2
	s_barrier
	ds_read_b128 v[184:187], v181 offset:16384
	ds_read_b128 v[188:191], v181 offset:17408
	ds_read_b128 v[192:195], v181 offset:18432
	ds_read_b128 v[196:199], v181 offset:19456
	v_mfma_f32_16x16x32_bf16 v[80:83], v[168:171], v[200:203], v[80:83]
	v_mfma_f32_16x16x32_bf16 v[80:83], v[172:175], v[204:207], v[80:83]
	v_mfma_f32_16x16x32_bf16 v[64:67], v[172:175], v[212:215], v[64:67]
	v_mfma_f32_16x16x32_bf16 v[64:67], v[168:171], v[208:211], v[64:67]
	s_setprio 2
	s_add_i32 s74, s69, s51
	v_lshl_add_u64 v[176:177], s[40:41], 0, v[130:131]
	s_mov_b32 m0, s74
	ds_read_b128 v[200:203], v181 offset:20480
	ds_read_b128 v[204:207], v181 offset:21504
	ds_read_b128 v[208:211], v181 offset:22528
	ds_read_b128 v[212:215], v181 offset:23552
	global_load_lds_dwordx4 v[176:177], off
	s_add_i32 m0, s74, 0x2000
	s_add_u32 s74, s40, 0x40000
	v_lshl_add_u64 v[216:217], s[40:41], 0, v[134:135]
	s_addc_u32 s75, s41, 0
	s_add_i32 s76, s70, s51
	global_load_lds_dwordx4 v[216:217], off
	v_lshl_add_u64 v[218:219], s[74:75], 0, v[130:131]
	s_mov_b32 m0, s76
	v_lshl_add_u64 v[220:221], s[44:45], 0, v[132:133]
	global_load_lds_dwordx4 v[218:219], off
	s_add_i32 m0, s76, 0x2000
	v_lshl_add_u64 v[218:219], s[74:75], 0, v[134:135]
	global_load_lds_dwordx4 v[218:219], off
	s_mov_b32 m0, s54
	v_lshl_add_u64 v[218:219], s[44:45], 0, v[128:129]
	global_load_lds_dwordx4 v[218:219], off
	s_mov_b32 m0, s55
	s_nop 0
	global_load_lds_dwordx4 v[220:221], off
	s_waitcnt vmcnt(8) lgkmcnt(0)
	s_barrier
	s_setprio 1
	v_mfma_f32_16x16x32_bf16 v[60:63], v[144:147], v[184:187], v[60:63]
	v_mfma_f32_16x16x32_bf16 v[60:63], v[148:151], v[188:191], v[60:63]
	v_mfma_f32_16x16x32_bf16 v[44:47], v[148:151], v[196:199], v[44:47]
	v_mfma_f32_16x16x32_bf16 v[44:47], v[144:147], v[192:195], v[44:47]
	v_mfma_f32_16x16x32_bf16 v[28:31], v[144:147], v[200:203], v[28:31]
	v_mfma_f32_16x16x32_bf16 v[28:31], v[148:151], v[204:207], v[28:31]
	v_mfma_f32_16x16x32_bf16 v[12:15], v[148:151], v[212:215], v[12:15]
	v_mfma_f32_16x16x32_bf16 v[12:15], v[144:147], v[208:211], v[12:15]
	v_mfma_f32_16x16x32_bf16 v[56:59], v[152:155], v[184:187], v[56:59]
	v_mfma_f32_16x16x32_bf16 v[56:59], v[156:159], v[188:191], v[56:59]
	v_mfma_f32_16x16x32_bf16 v[40:43], v[156:159], v[196:199], v[40:43]
	v_mfma_f32_16x16x32_bf16 v[40:43], v[152:155], v[192:195], v[40:43]
	v_mfma_f32_16x16x32_bf16 v[24:27], v[152:155], v[200:203], v[24:27]
	v_mfma_f32_16x16x32_bf16 v[24:27], v[156:159], v[204:207], v[24:27]
	v_mfma_f32_16x16x32_bf16 v[8:11], v[156:159], v[212:215], v[8:11]
	v_mfma_f32_16x16x32_bf16 v[8:11], v[152:155], v[208:211], v[8:11]
	v_mfma_f32_16x16x32_bf16 v[52:55], v[160:163], v[184:187], v[52:55]
	v_mfma_f32_16x16x32_bf16 v[52:55], v[164:167], v[188:191], v[52:55]
	v_mfma_f32_16x16x32_bf16 v[36:39], v[164:167], v[196:199], v[36:39]
	v_mfma_f32_16x16x32_bf16 v[36:39], v[160:163], v[192:195], v[36:39]
	v_mfma_f32_16x16x32_bf16 v[20:23], v[160:163], v[200:203], v[20:23]
	v_mfma_f32_16x16x32_bf16 v[20:23], v[164:167], v[204:207], v[20:23]
	v_mfma_f32_16x16x32_bf16 v[4:7], v[164:167], v[212:215], v[4:7]
	v_mfma_f32_16x16x32_bf16 v[4:7], v[160:163], v[208:211], v[4:7]
	v_mfma_f32_16x16x32_bf16 v[48:51], v[168:171], v[184:187], v[48:51]
	v_mfma_f32_16x16x32_bf16 v[48:51], v[172:175], v[188:191], v[48:51]
	v_mfma_f32_16x16x32_bf16 v[32:35], v[172:175], v[196:199], v[32:35]
	v_mfma_f32_16x16x32_bf16 v[32:35], v[168:171], v[192:195], v[32:35]
	s_setprio 2
	s_barrier
	ds_read_b128 v[184:187], v181 offset:32768
	ds_read_b128 v[188:191], v181 offset:33792
	ds_read_b128 v[192:195], v181 offset:34816
	ds_read_b128 v[196:199], v181 offset:35840
	v_mfma_f32_16x16x32_bf16 v[16:19], v[168:171], v[200:203], v[16:19]
	v_mfma_f32_16x16x32_bf16 v[16:19], v[172:175], v[204:207], v[16:19]
	v_mfma_f32_16x16x32_bf16 v[0:3], v[172:175], v[212:215], v[0:3]
	v_mfma_f32_16x16x32_bf16 v[0:3], v[168:171], v[208:211], v[0:3]
	s_setprio 0
	s_add_i32 s74, 0, 0x18000
	s_add_i32 s75, 0, 0x1c000
	v_add_u32_e32 v156, s74, v178
	v_add_u32_e32 v172, s75, v178
	ds_read_b128 v[144:147], v156
	ds_read_b128 v[148:151], v156 offset:1024
	ds_read_b128 v[152:155], v156 offset:2048
	ds_read_b128 v[156:159], v156 offset:3072
	ds_read_b128 v[160:163], v172
	ds_read_b128 v[164:167], v172 offset:1024
	ds_read_b128 v[168:171], v172 offset:2048
	ds_read_b128 v[172:175], v172 offset:3072
	s_add_u32 s44, s44, 0x40000
	s_addc_u32 s45, s45, 0
	s_mov_b32 m0, s56
	v_lshl_add_u64 v[222:223], s[44:45], 0, v[128:129]
	ds_read_b128 v[200:203], v181 offset:36864
	ds_read_b128 v[204:207], v181 offset:37888
	ds_read_b128 v[208:211], v181 offset:38912
	ds_read_b128 v[212:215], v181 offset:39936
	global_load_lds_dwordx4 v[222:223], off
	s_mov_b32 m0, s57
	v_lshl_add_u64 v[222:223], s[44:45], 0, v[132:133]
	global_load_lds_dwordx4 v[222:223], off
	s_waitcnt vmcnt(8) lgkmcnt(0)
	s_barrier
	s_setprio 1
	v_mfma_f32_16x16x32_bf16 v[124:127], v[144:147], v[184:187], v[124:127]
	v_mfma_f32_16x16x32_bf16 v[124:127], v[148:151], v[188:191], v[124:127]
	v_mfma_f32_16x16x32_bf16 v[108:111], v[148:151], v[196:199], v[108:111]
	v_mfma_f32_16x16x32_bf16 v[108:111], v[144:147], v[192:195], v[108:111]
	v_mfma_f32_16x16x32_bf16 v[92:95], v[144:147], v[200:203], v[92:95]
	v_mfma_f32_16x16x32_bf16 v[92:95], v[148:151], v[204:207], v[92:95]
	v_mfma_f32_16x16x32_bf16 v[76:79], v[148:151], v[212:215], v[76:79]
	v_mfma_f32_16x16x32_bf16 v[76:79], v[144:147], v[208:211], v[76:79]
	v_mfma_f32_16x16x32_bf16 v[120:123], v[152:155], v[184:187], v[120:123]
	v_mfma_f32_16x16x32_bf16 v[120:123], v[156:159], v[188:191], v[120:123]
	v_mfma_f32_16x16x32_bf16 v[104:107], v[156:159], v[196:199], v[104:107]
	v_mfma_f32_16x16x32_bf16 v[104:107], v[152:155], v[192:195], v[104:107]
	v_mfma_f32_16x16x32_bf16 v[88:91], v[152:155], v[200:203], v[88:91]
	v_mfma_f32_16x16x32_bf16 v[88:91], v[156:159], v[204:207], v[88:91]
	v_mfma_f32_16x16x32_bf16 v[72:75], v[156:159], v[212:215], v[72:75]
	v_mfma_f32_16x16x32_bf16 v[72:75], v[152:155], v[208:211], v[72:75]
	v_mfma_f32_16x16x32_bf16 v[116:119], v[160:163], v[184:187], v[116:119]
	v_mfma_f32_16x16x32_bf16 v[116:119], v[164:167], v[188:191], v[116:119]
	v_mfma_f32_16x16x32_bf16 v[100:103], v[164:167], v[196:199], v[100:103]
	v_mfma_f32_16x16x32_bf16 v[100:103], v[160:163], v[192:195], v[100:103]
	v_mfma_f32_16x16x32_bf16 v[84:87], v[160:163], v[200:203], v[84:87]
	v_mfma_f32_16x16x32_bf16 v[84:87], v[164:167], v[204:207], v[84:87]
	v_mfma_f32_16x16x32_bf16 v[68:71], v[164:167], v[212:215], v[68:71]
	v_mfma_f32_16x16x32_bf16 v[68:71], v[160:163], v[208:211], v[68:71]
	v_mfma_f32_16x16x32_bf16 v[112:115], v[168:171], v[184:187], v[112:115]
	v_mfma_f32_16x16x32_bf16 v[112:115], v[172:175], v[188:191], v[112:115]
	v_mfma_f32_16x16x32_bf16 v[96:99], v[172:175], v[196:199], v[96:99]
	v_mfma_f32_16x16x32_bf16 v[96:99], v[168:171], v[192:195], v[96:99]
	s_setprio 2
	s_barrier
	ds_read_b128 v[184:187], v181 offset:49152
	ds_read_b128 v[188:191], v181 offset:50176
	ds_read_b128 v[192:195], v181 offset:51200
	ds_read_b128 v[196:199], v181 offset:52224
	v_mfma_f32_16x16x32_bf16 v[80:83], v[168:171], v[200:203], v[80:83]
	v_mfma_f32_16x16x32_bf16 v[80:83], v[172:175], v[204:207], v[80:83]
	v_mfma_f32_16x16x32_bf16 v[64:67], v[172:175], v[212:215], v[64:67]
	v_mfma_f32_16x16x32_bf16 v[64:67], v[168:171], v[208:211], v[64:67]
	s_setprio 2
	s_add_i32 s44, s74, s51
	v_lshl_add_u64 v[176:177], v[176:177], 0, s[22:23]
	s_mov_b32 m0, s44
	ds_read_b128 v[200:203], v181 offset:53248
	ds_read_b128 v[204:207], v181 offset:54272
	ds_read_b128 v[208:211], v181 offset:55296
	ds_read_b128 v[212:215], v181 offset:56320
	global_load_lds_dwordx4 v[176:177], off
	s_add_i32 m0, s44, 0x2000
	s_add_u32 s40, s40, 0x40080
	v_lshl_add_u64 v[176:177], v[216:217], 0, s[22:23]
	s_addc_u32 s41, s41, 0
	s_add_i32 s44, s75, s51
	global_load_lds_dwordx4 v[176:177], off
	s_mov_b32 m0, s44
	v_lshl_add_u64 v[176:177], s[40:41], 0, v[130:131]
	global_load_lds_dwordx4 v[176:177], off
	s_add_i32 m0, s44, 0x2000
	v_lshl_add_u64 v[176:177], s[40:41], 0, v[134:135]
	global_load_lds_dwordx4 v[176:177], off
	s_mov_b32 m0, s64
	v_lshl_add_u64 v[176:177], v[218:219], 0, s[22:23]
	global_load_lds_dwordx4 v[176:177], off
	s_mov_b32 m0, s65
	v_lshl_add_u64 v[176:177], v[220:221], 0, s[22:23]
	global_load_lds_dwordx4 v[176:177], off
	s_waitcnt vmcnt(8) lgkmcnt(0)
	s_barrier
	s_setprio 1
	v_mfma_f32_16x16x32_bf16 v[60:63], v[144:147], v[184:187], v[60:63]
	v_mfma_f32_16x16x32_bf16 v[60:63], v[148:151], v[188:191], v[60:63]
	v_mfma_f32_16x16x32_bf16 v[44:47], v[148:151], v[196:199], v[44:47]
	v_mfma_f32_16x16x32_bf16 v[44:47], v[144:147], v[192:195], v[44:47]
	v_mfma_f32_16x16x32_bf16 v[28:31], v[144:147], v[200:203], v[28:31]
	v_mfma_f32_16x16x32_bf16 v[28:31], v[148:151], v[204:207], v[28:31]
	v_mfma_f32_16x16x32_bf16 v[12:15], v[148:151], v[212:215], v[12:15]
	v_mfma_f32_16x16x32_bf16 v[12:15], v[144:147], v[208:211], v[12:15]
	v_mfma_f32_16x16x32_bf16 v[56:59], v[152:155], v[184:187], v[56:59]
	v_mfma_f32_16x16x32_bf16 v[56:59], v[156:159], v[188:191], v[56:59]
	v_mfma_f32_16x16x32_bf16 v[40:43], v[156:159], v[196:199], v[40:43]
	v_mfma_f32_16x16x32_bf16 v[40:43], v[152:155], v[192:195], v[40:43]
	v_mfma_f32_16x16x32_bf16 v[24:27], v[152:155], v[200:203], v[24:27]
	v_mfma_f32_16x16x32_bf16 v[24:27], v[156:159], v[204:207], v[24:27]
	v_mfma_f32_16x16x32_bf16 v[8:11], v[156:159], v[212:215], v[8:11]
	v_mfma_f32_16x16x32_bf16 v[8:11], v[152:155], v[208:211], v[8:11]
	v_mfma_f32_16x16x32_bf16 v[52:55], v[160:163], v[184:187], v[52:55]
	v_mfma_f32_16x16x32_bf16 v[52:55], v[164:167], v[188:191], v[52:55]
	v_mfma_f32_16x16x32_bf16 v[36:39], v[164:167], v[196:199], v[36:39]
	v_mfma_f32_16x16x32_bf16 v[36:39], v[160:163], v[192:195], v[36:39]
	v_mfma_f32_16x16x32_bf16 v[20:23], v[160:163], v[200:203], v[20:23]
	v_mfma_f32_16x16x32_bf16 v[20:23], v[164:167], v[204:207], v[20:23]
	v_mfma_f32_16x16x32_bf16 v[4:7], v[164:167], v[212:215], v[4:7]
	v_mfma_f32_16x16x32_bf16 v[4:7], v[160:163], v[208:211], v[4:7]
	v_mfma_f32_16x16x32_bf16 v[48:51], v[168:171], v[184:187], v[48:51]
	v_mfma_f32_16x16x32_bf16 v[48:51], v[172:175], v[188:191], v[48:51]
	v_mfma_f32_16x16x32_bf16 v[32:35], v[172:175], v[196:199], v[32:35]
	v_mfma_f32_16x16x32_bf16 v[32:35], v[168:171], v[192:195], v[32:35]
	s_setprio 2
	s_barrier
	v_mfma_f32_16x16x32_bf16 v[16:19], v[168:171], v[200:203], v[16:19]
	v_mfma_f32_16x16x32_bf16 v[16:19], v[172:175], v[204:207], v[16:19]
	v_mfma_f32_16x16x32_bf16 v[0:3], v[172:175], v[212:215], v[0:3]
	v_mfma_f32_16x16x32_bf16 v[0:3], v[168:171], v[208:211], v[0:3]
	s_setprio 0
	s_add_i32 s73, s73, 2
	s_add_u32 s6, s6, 0x100
	s_addc_u32 s7, s7, 0
	s_add_u32 s71, s71, 0x100
	s_addc_u32 s72, s72, 0
	s_cmp_gt_u32 s73, 13
	s_cbranch_scc0 .LBB0_952

.LBB0_1145:
	s_ashr_i32 s23, s22, 31
	s_lshl_b64 s[26:27], s[22:23], 19
	s_add_u32 s26, s45, s26
	s_addc_u32 s27, s46, s27
	s_and_b64 s[28:29], s[4:5], exec
	s_cselect_b32 s23, s27, s39
	s_cselect_b32 s31, s26, s38
	s_ashr_i32 s25, s24, 31
	s_lshl_b64 s[28:29], s[24:25], 19
	s_add_u32 s28, s47, s28
	s_addc_u32 s29, s48, s29
	s_and_b64 s[42:43], s[4:5], exec
	s_cselect_b32 s25, s29, s41
	s_cselect_b32 s37, s28, s40
	s_add_u32 s38, s38, 0x40080
	s_addc_u32 s39, s39, 0
	s_add_u32 s64, s40, 0x100
	s_addc_u32 s65, s41, 0
	s_mov_b32 s66, -2
	ds_read_b128 v[120:123], v233
	ds_read_b128 v[132:135], v233 offset:1024
	ds_read_b128 v[136:139], v233 offset:2048
	ds_read_b128 v[140:143], v233 offset:3072
	ds_read_b128 v[144:147], v234
	ds_read_b128 v[148:151], v234 offset:1024
	ds_read_b128 v[152:155], v234 offset:2048
	ds_read_b128 v[156:159], v234 offset:3072
	s_add_u32 s40, s38, 0xfffc0080
	s_addc_u32 s41, s39, -1
	s_cmp_eq_u32 s66, 12
	s_cselect_b32 s43, s23, s41
	s_cselect_b32 s42, s31, s40
	s_cselect_b32 s41, s25, s65
	s_cselect_b32 s40, s37, s64
	v_lshl_add_u64 v[208:209], s[38:39], 0, v[192:193]
	s_add_i32 m0, s50, 0xc000
	ds_read_b128 v[160:163], v235
	ds_read_b128 v[164:167], v235 offset:1024
	ds_read_b128 v[168:171], v235 offset:2048
	ds_read_b128 v[172:175], v235 offset:3072
	ds_read_b128 v[176:179], v235 offset:4096
	ds_read_b128 v[180:183], v235 offset:5120
	ds_read_b128 v[200:203], v235 offset:6144
	ds_read_b128 v[204:207], v235 offset:7168
	global_load_lds_dwordx4 v[208:209], off
	s_add_i32 m0, s50, 0xe000
	v_lshl_add_u64 v[208:209], s[38:39], 0, v[194:195]
	global_load_lds_dwordx4 v[208:209], off
	s_waitcnt vmcnt(8) lgkmcnt(0)
	s_barrier
	s_setprio 1
	v_mfma_f32_16x16x32_bf16 v[128:131], v[120:123], v[160:163], 0
	v_mfma_f32_16x16x32_bf16 v[128:131], v[132:135], v[164:167], v[128:131]
	v_mfma_f32_16x16x32_bf16 v[108:111], v[132:135], v[172:175], 0
	v_mfma_f32_16x16x32_bf16 v[108:111], v[120:123], v[168:171], v[108:111]
	v_mfma_f32_16x16x32_bf16 v[92:95], v[120:123], v[176:179], 0
	v_mfma_f32_16x16x32_bf16 v[92:95], v[132:135], v[180:183], v[92:95]
	v_mfma_f32_16x16x32_bf16 v[76:79], v[132:135], v[204:207], 0
	v_mfma_f32_16x16x32_bf16 v[76:79], v[120:123], v[200:203], v[76:79]
	v_mfma_f32_16x16x32_bf16 v[124:127], v[136:139], v[160:163], 0
	v_mfma_f32_16x16x32_bf16 v[124:127], v[140:143], v[164:167], v[124:127]
	v_mfma_f32_16x16x32_bf16 v[104:107], v[140:143], v[172:175], 0
	v_mfma_f32_16x16x32_bf16 v[104:107], v[136:139], v[168:171], v[104:107]
	v_mfma_f32_16x16x32_bf16 v[88:91], v[136:139], v[176:179], 0
	v_mfma_f32_16x16x32_bf16 v[88:91], v[140:143], v[180:183], v[88:91]
	v_mfma_f32_16x16x32_bf16 v[72:75], v[140:143], v[204:207], 0
	v_mfma_f32_16x16x32_bf16 v[72:75], v[136:139], v[200:203], v[72:75]
	v_mfma_f32_16x16x32_bf16 v[116:119], v[144:147], v[160:163], 0
	v_mfma_f32_16x16x32_bf16 v[116:119], v[148:151], v[164:167], v[116:119]
	v_mfma_f32_16x16x32_bf16 v[100:103], v[148:151], v[172:175], 0
	v_mfma_f32_16x16x32_bf16 v[100:103], v[144:147], v[168:171], v[100:103]
	v_mfma_f32_16x16x32_bf16 v[84:87], v[144:147], v[176:179], 0
	v_mfma_f32_16x16x32_bf16 v[84:87], v[148:151], v[180:183], v[84:87]
	v_mfma_f32_16x16x32_bf16 v[68:71], v[148:151], v[204:207], 0
	v_mfma_f32_16x16x32_bf16 v[68:71], v[144:147], v[200:203], v[68:71]
	v_mfma_f32_16x16x32_bf16 v[112:115], v[152:155], v[160:163], 0
	v_mfma_f32_16x16x32_bf16 v[112:115], v[156:159], v[164:167], v[112:115]
	v_mfma_f32_16x16x32_bf16 v[96:99], v[156:159], v[172:175], 0
	v_mfma_f32_16x16x32_bf16 v[96:99], v[152:155], v[168:171], v[96:99]
	s_setprio 2
	s_barrier
	ds_read_b128 v[160:163], v235 offset:16384
	ds_read_b128 v[164:167], v235 offset:17408
	ds_read_b128 v[168:171], v235 offset:18432
	ds_read_b128 v[172:175], v235 offset:19456
	v_mfma_f32_16x16x32_bf16 v[80:83], v[152:155], v[176:179], 0
	v_mfma_f32_16x16x32_bf16 v[80:83], v[156:159], v[180:183], v[80:83]
	v_mfma_f32_16x16x32_bf16 v[64:67], v[156:159], v[204:207], 0
	v_mfma_f32_16x16x32_bf16 v[64:67], v[152:155], v[200:203], v[64:67]
	s_setprio 2
	s_add_i32 s67, s62, s49
	v_lshl_add_u64 v[208:209], s[40:41], 0, v[186:187]
	s_mov_b32 m0, s67
	ds_read_b128 v[176:179], v235 offset:20480
	ds_read_b128 v[180:183], v235 offset:21504
	ds_read_b128 v[200:203], v235 offset:22528
	ds_read_b128 v[204:207], v235 offset:23552
	global_load_lds_dwordx4 v[208:209], off
	s_add_i32 m0, s67, 0x2000
	s_add_u32 s68, s40, 0x40000
	v_lshl_add_u64 v[210:211], s[40:41], 0, v[190:191]
	s_addc_u32 s69, s41, 0
	s_add_i32 s67, s63, s49
	global_load_lds_dwordx4 v[210:211], off
	v_lshl_add_u64 v[212:213], s[68:69], 0, v[186:187]
	s_mov_b32 m0, s67
	v_lshl_add_u64 v[214:215], s[42:43], 0, v[188:189]
	global_load_lds_dwordx4 v[212:213], off
	s_add_i32 m0, s67, 0x2000
	v_lshl_add_u64 v[212:213], s[68:69], 0, v[190:191]
	global_load_lds_dwordx4 v[212:213], off
	s_mov_b32 m0, s50
	v_lshl_add_u64 v[212:213], s[42:43], 0, v[184:185]
	global_load_lds_dwordx4 v[212:213], off
	s_mov_b32 m0, s51
	s_nop 0
	global_load_lds_dwordx4 v[214:215], off
	s_waitcnt vmcnt(8) lgkmcnt(0)
	s_barrier
	s_setprio 1
	v_mfma_f32_16x16x32_bf16 v[60:63], v[120:123], v[160:163], 0
	v_mfma_f32_16x16x32_bf16 v[60:63], v[132:135], v[164:167], v[60:63]
	v_mfma_f32_16x16x32_bf16 v[44:47], v[132:135], v[172:175], 0
	v_mfma_f32_16x16x32_bf16 v[44:47], v[120:123], v[168:171], v[44:47]
	v_mfma_f32_16x16x32_bf16 v[28:31], v[120:123], v[176:179], 0
	v_mfma_f32_16x16x32_bf16 v[28:31], v[132:135], v[180:183], v[28:31]
	v_mfma_f32_16x16x32_bf16 v[12:15], v[132:135], v[204:207], 0
	v_mfma_f32_16x16x32_bf16 v[12:15], v[120:123], v[200:203], v[12:15]
	v_mfma_f32_16x16x32_bf16 v[56:59], v[136:139], v[160:163], 0
	v_mfma_f32_16x16x32_bf16 v[56:59], v[140:143], v[164:167], v[56:59]
	v_mfma_f32_16x16x32_bf16 v[40:43], v[140:143], v[172:175], 0
	v_mfma_f32_16x16x32_bf16 v[40:43], v[136:139], v[168:171], v[40:43]
	v_mfma_f32_16x16x32_bf16 v[24:27], v[136:139], v[176:179], 0
	v_mfma_f32_16x16x32_bf16 v[24:27], v[140:143], v[180:183], v[24:27]
	v_mfma_f32_16x16x32_bf16 v[8:11], v[140:143], v[204:207], 0
	v_mfma_f32_16x16x32_bf16 v[8:11], v[136:139], v[200:203], v[8:11]
	v_mfma_f32_16x16x32_bf16 v[52:55], v[144:147], v[160:163], 0
	v_mfma_f32_16x16x32_bf16 v[52:55], v[148:151], v[164:167], v[52:55]
	v_mfma_f32_16x16x32_bf16 v[36:39], v[148:151], v[172:175], 0
	v_mfma_f32_16x16x32_bf16 v[36:39], v[144:147], v[168:171], v[36:39]
	v_mfma_f32_16x16x32_bf16 v[20:23], v[144:147], v[176:179], 0
	v_mfma_f32_16x16x32_bf16 v[20:23], v[148:151], v[180:183], v[20:23]
	v_mfma_f32_16x16x32_bf16 v[4:7], v[148:151], v[204:207], 0
	v_mfma_f32_16x16x32_bf16 v[4:7], v[144:147], v[200:203], v[4:7]
	v_mfma_f32_16x16x32_bf16 v[48:51], v[152:155], v[160:163], 0
	v_mfma_f32_16x16x32_bf16 v[48:51], v[156:159], v[164:167], v[48:51]
	v_mfma_f32_16x16x32_bf16 v[32:35], v[156:159], v[172:175], 0
	v_mfma_f32_16x16x32_bf16 v[32:35], v[152:155], v[168:171], v[32:35]
	s_setprio 2
	s_barrier
	ds_read_b128 v[160:163], v235 offset:32768
	ds_read_b128 v[164:167], v235 offset:33792
	ds_read_b128 v[168:171], v235 offset:34816
	ds_read_b128 v[172:175], v235 offset:35840
	v_mfma_f32_16x16x32_bf16 v[16:19], v[152:155], v[176:179], 0
	v_mfma_f32_16x16x32_bf16 v[16:19], v[156:159], v[180:183], v[16:19]
	v_mfma_f32_16x16x32_bf16 v[0:3], v[156:159], v[204:207], 0
	v_mfma_f32_16x16x32_bf16 v[0:3], v[152:155], v[200:203], v[0:3]
	s_setprio 0
	s_add_i32 s67, 0, 0x18000
	s_add_i32 s68, 0, 0x1c000
	v_add_u32_e32 v140, s67, v232
	v_add_u32_e32 v156, s68, v232
	ds_read_b128 v[120:123], v140
	ds_read_b128 v[132:135], v140 offset:1024
	ds_read_b128 v[136:139], v140 offset:2048
	ds_read_b128 v[140:143], v140 offset:3072
	ds_read_b128 v[144:147], v156
	ds_read_b128 v[148:151], v156 offset:1024
	ds_read_b128 v[152:155], v156 offset:2048
	ds_read_b128 v[156:159], v156 offset:3072
	s_add_u32 s42, s42, 0x40000
	s_addc_u32 s43, s43, 0
	s_mov_b32 m0, s54
	v_lshl_add_u64 v[216:217], s[42:43], 0, v[184:185]
	ds_read_b128 v[176:179], v235 offset:36864
	ds_read_b128 v[180:183], v235 offset:37888
	ds_read_b128 v[200:203], v235 offset:38912
	ds_read_b128 v[204:207], v235 offset:39936
	global_load_lds_dwordx4 v[216:217], off
	s_mov_b32 m0, s55
	v_lshl_add_u64 v[216:217], s[42:43], 0, v[188:189]
	global_load_lds_dwordx4 v[216:217], off
	s_waitcnt vmcnt(8) lgkmcnt(0)
	s_barrier
	s_setprio 1
	v_mfma_f32_16x16x32_bf16 v[128:131], v[120:123], v[160:163], v[128:131]
	v_mfma_f32_16x16x32_bf16 v[128:131], v[132:135], v[164:167], v[128:131]
	v_mfma_f32_16x16x32_bf16 v[108:111], v[132:135], v[172:175], v[108:111]
	v_mfma_f32_16x16x32_bf16 v[108:111], v[120:123], v[168:171], v[108:111]
	v_mfma_f32_16x16x32_bf16 v[92:95], v[120:123], v[176:179], v[92:95]
	v_mfma_f32_16x16x32_bf16 v[92:95], v[132:135], v[180:183], v[92:95]
	v_mfma_f32_16x16x32_bf16 v[76:79], v[132:135], v[204:207], v[76:79]
	v_mfma_f32_16x16x32_bf16 v[76:79], v[120:123], v[200:203], v[76:79]
	v_mfma_f32_16x16x32_bf16 v[124:127], v[136:139], v[160:163], v[124:127]
	v_mfma_f32_16x16x32_bf16 v[124:127], v[140:143], v[164:167], v[124:127]
	v_mfma_f32_16x16x32_bf16 v[104:107], v[140:143], v[172:175], v[104:107]
	v_mfma_f32_16x16x32_bf16 v[104:107], v[136:139], v[168:171], v[104:107]
	v_mfma_f32_16x16x32_bf16 v[88:91], v[136:139], v[176:179], v[88:91]
	v_mfma_f32_16x16x32_bf16 v[88:91], v[140:143], v[180:183], v[88:91]
	v_mfma_f32_16x16x32_bf16 v[72:75], v[140:143], v[204:207], v[72:75]
	v_mfma_f32_16x16x32_bf16 v[72:75], v[136:139], v[200:203], v[72:75]
	v_mfma_f32_16x16x32_bf16 v[116:119], v[144:147], v[160:163], v[116:119]
	v_mfma_f32_16x16x32_bf16 v[116:119], v[148:151], v[164:167], v[116:119]
	v_mfma_f32_16x16x32_bf16 v[100:103], v[148:151], v[172:175], v[100:103]
	v_mfma_f32_16x16x32_bf16 v[100:103], v[144:147], v[168:171], v[100:103]
	v_mfma_f32_16x16x32_bf16 v[84:87], v[144:147], v[176:179], v[84:87]
	v_mfma_f32_16x16x32_bf16 v[84:87], v[148:151], v[180:183], v[84:87]
	v_mfma_f32_16x16x32_bf16 v[68:71], v[148:151], v[204:207], v[68:71]
	v_mfma_f32_16x16x32_bf16 v[68:71], v[144:147], v[200:203], v[68:71]
	v_mfma_f32_16x16x32_bf16 v[112:115], v[152:155], v[160:163], v[112:115]
	v_mfma_f32_16x16x32_bf16 v[112:115], v[156:159], v[164:167], v[112:115]
	v_mfma_f32_16x16x32_bf16 v[96:99], v[156:159], v[172:175], v[96:99]
	v_mfma_f32_16x16x32_bf16 v[96:99], v[152:155], v[168:171], v[96:99]
	s_setprio 2
	s_barrier
	ds_read_b128 v[160:163], v235 offset:49152
	ds_read_b128 v[164:167], v235 offset:50176
	ds_read_b128 v[168:171], v235 offset:51200
	ds_read_b128 v[172:175], v235 offset:52224
	v_mfma_f32_16x16x32_bf16 v[80:83], v[152:155], v[176:179], v[80:83]
	v_mfma_f32_16x16x32_bf16 v[80:83], v[156:159], v[180:183], v[80:83]
	v_mfma_f32_16x16x32_bf16 v[64:67], v[156:159], v[204:207], v[64:67]
	v_mfma_f32_16x16x32_bf16 v[64:67], v[152:155], v[200:203], v[64:67]
	s_setprio 2
	s_add_i32 s42, s67, s49
	v_lshl_add_u64 v[208:209], v[208:209], 0, s[18:19]
	s_mov_b32 m0, s42
	ds_read_b128 v[176:179], v235 offset:53248
	ds_read_b128 v[180:183], v235 offset:54272
	ds_read_b128 v[200:203], v235 offset:55296
	ds_read_b128 v[204:207], v235 offset:56320
	global_load_lds_dwordx4 v[208:209], off
	s_add_i32 m0, s42, 0x2000
	s_add_u32 s40, s40, 0x40080
	v_lshl_add_u64 v[208:209], v[210:211], 0, s[18:19]
	s_addc_u32 s41, s41, 0
	s_add_i32 s42, s68, s49
	global_load_lds_dwordx4 v[208:209], off
	s_mov_b32 m0, s42
	v_lshl_add_u64 v[208:209], s[40:41], 0, v[186:187]
	global_load_lds_dwordx4 v[208:209], off
	s_add_i32 m0, s42, 0x2000
	v_lshl_add_u64 v[208:209], s[40:41], 0, v[190:191]
	global_load_lds_dwordx4 v[208:209], off
	s_mov_b32 m0, s57
	v_lshl_add_u64 v[208:209], v[212:213], 0, s[18:19]
	global_load_lds_dwordx4 v[208:209], off
	s_mov_b32 m0, s58
	v_lshl_add_u64 v[208:209], v[214:215], 0, s[18:19]
	global_load_lds_dwordx4 v[208:209], off
	s_waitcnt vmcnt(8) lgkmcnt(0)
	s_barrier
	s_setprio 1
	v_mfma_f32_16x16x32_bf16 v[60:63], v[120:123], v[160:163], v[60:63]
	v_mfma_f32_16x16x32_bf16 v[60:63], v[132:135], v[164:167], v[60:63]
	v_mfma_f32_16x16x32_bf16 v[44:47], v[132:135], v[172:175], v[44:47]
	v_mfma_f32_16x16x32_bf16 v[44:47], v[120:123], v[168:171], v[44:47]
	v_mfma_f32_16x16x32_bf16 v[28:31], v[120:123], v[176:179], v[28:31]
	v_mfma_f32_16x16x32_bf16 v[28:31], v[132:135], v[180:183], v[28:31]
	v_mfma_f32_16x16x32_bf16 v[12:15], v[132:135], v[204:207], v[12:15]
	v_mfma_f32_16x16x32_bf16 v[12:15], v[120:123], v[200:203], v[12:15]
	v_mfma_f32_16x16x32_bf16 v[56:59], v[136:139], v[160:163], v[56:59]
	v_mfma_f32_16x16x32_bf16 v[56:59], v[140:143], v[164:167], v[56:59]
	v_mfma_f32_16x16x32_bf16 v[40:43], v[140:143], v[172:175], v[40:43]
	v_mfma_f32_16x16x32_bf16 v[40:43], v[136:139], v[168:171], v[40:43]
	v_mfma_f32_16x16x32_bf16 v[24:27], v[136:139], v[176:179], v[24:27]
	v_mfma_f32_16x16x32_bf16 v[24:27], v[140:143], v[180:183], v[24:27]
	v_mfma_f32_16x16x32_bf16 v[8:11], v[140:143], v[204:207], v[8:11]
	v_mfma_f32_16x16x32_bf16 v[8:11], v[136:139], v[200:203], v[8:11]
	v_mfma_f32_16x16x32_bf16 v[52:55], v[144:147], v[160:163], v[52:55]
	v_mfma_f32_16x16x32_bf16 v[52:55], v[148:151], v[164:167], v[52:55]
	v_mfma_f32_16x16x32_bf16 v[36:39], v[148:151], v[172:175], v[36:39]
	v_mfma_f32_16x16x32_bf16 v[36:39], v[144:147], v[168:171], v[36:39]
	v_mfma_f32_16x16x32_bf16 v[20:23], v[144:147], v[176:179], v[20:23]
	v_mfma_f32_16x16x32_bf16 v[20:23], v[148:151], v[180:183], v[20:23]
	v_mfma_f32_16x16x32_bf16 v[4:7], v[148:151], v[204:207], v[4:7]
	v_mfma_f32_16x16x32_bf16 v[4:7], v[144:147], v[200:203], v[4:7]
	v_mfma_f32_16x16x32_bf16 v[48:51], v[152:155], v[160:163], v[48:51]
	v_mfma_f32_16x16x32_bf16 v[48:51], v[156:159], v[164:167], v[48:51]
	v_mfma_f32_16x16x32_bf16 v[32:35], v[156:159], v[172:175], v[32:35]
	v_mfma_f32_16x16x32_bf16 v[32:35], v[152:155], v[168:171], v[32:35]
	s_setprio 2
	s_barrier
	v_mfma_f32_16x16x32_bf16 v[16:19], v[152:155], v[176:179], v[16:19]
	v_mfma_f32_16x16x32_bf16 v[16:19], v[156:159], v[180:183], v[16:19]
	v_mfma_f32_16x16x32_bf16 v[0:3], v[156:159], v[204:207], v[0:3]
	v_mfma_f32_16x16x32_bf16 v[0:3], v[152:155], v[200:203], v[0:3]
	s_setprio 0
	s_add_i32 s66, s66, 2
	s_add_u32 s38, s38, 0x100
	s_addc_u32 s39, s39, 0
	s_add_u32 s64, s64, 0x100
	s_addc_u32 s65, s65, 0
	s_cmp_gt_u32 s66, 13
.LBB0_1146:
	ds_read_b128 v[120:123], v233
	ds_read_b128 v[132:135], v233 offset:1024
	ds_read_b128 v[136:139], v233 offset:2048
	ds_read_b128 v[140:143], v233 offset:3072
	ds_read_b128 v[144:147], v234
	ds_read_b128 v[148:151], v234 offset:1024
	ds_read_b128 v[152:155], v234 offset:2048
	ds_read_b128 v[156:159], v234 offset:3072
	s_add_u32 s40, s38, 0xfffc0080
	s_addc_u32 s41, s39, -1
	s_cmp_eq_u32 s66, 12
	s_cselect_b32 s43, s23, s41
	s_cselect_b32 s42, s31, s40
	s_cselect_b32 s41, s25, s65
	s_cselect_b32 s40, s37, s64
	v_lshl_add_u64 v[208:209], s[38:39], 0, v[192:193]
	s_add_i32 m0, s50, 0xc000
	ds_read_b128 v[160:163], v235
	ds_read_b128 v[164:167], v235 offset:1024
	ds_read_b128 v[168:171], v235 offset:2048
	ds_read_b128 v[172:175], v235 offset:3072
	ds_read_b128 v[176:179], v235 offset:4096
	ds_read_b128 v[180:183], v235 offset:5120
	ds_read_b128 v[200:203], v235 offset:6144
	ds_read_b128 v[204:207], v235 offset:7168
	global_load_lds_dwordx4 v[208:209], off
	s_add_i32 m0, s50, 0xe000
	v_lshl_add_u64 v[208:209], s[38:39], 0, v[194:195]
	global_load_lds_dwordx4 v[208:209], off
	s_waitcnt vmcnt(8) lgkmcnt(0)
	s_barrier
	s_setprio 1
	v_mfma_f32_16x16x32_bf16 v[128:131], v[120:123], v[160:163], v[128:131]
	v_mfma_f32_16x16x32_bf16 v[128:131], v[132:135], v[164:167], v[128:131]
	v_mfma_f32_16x16x32_bf16 v[108:111], v[132:135], v[172:175], v[108:111]
	v_mfma_f32_16x16x32_bf16 v[108:111], v[120:123], v[168:171], v[108:111]
	v_mfma_f32_16x16x32_bf16 v[92:95], v[120:123], v[176:179], v[92:95]
	v_mfma_f32_16x16x32_bf16 v[92:95], v[132:135], v[180:183], v[92:95]
	v_mfma_f32_16x16x32_bf16 v[76:79], v[132:135], v[204:207], v[76:79]
	v_mfma_f32_16x16x32_bf16 v[76:79], v[120:123], v[200:203], v[76:79]
	v_mfma_f32_16x16x32_bf16 v[124:127], v[136:139], v[160:163], v[124:127]
	v_mfma_f32_16x16x32_bf16 v[124:127], v[140:143], v[164:167], v[124:127]
	v_mfma_f32_16x16x32_bf16 v[104:107], v[140:143], v[172:175], v[104:107]
	v_mfma_f32_16x16x32_bf16 v[104:107], v[136:139], v[168:171], v[104:107]
	v_mfma_f32_16x16x32_bf16 v[88:91], v[136:139], v[176:179], v[88:91]
	v_mfma_f32_16x16x32_bf16 v[88:91], v[140:143], v[180:183], v[88:91]
	v_mfma_f32_16x16x32_bf16 v[72:75], v[140:143], v[204:207], v[72:75]
	v_mfma_f32_16x16x32_bf16 v[72:75], v[136:139], v[200:203], v[72:75]
	v_mfma_f32_16x16x32_bf16 v[116:119], v[144:147], v[160:163], v[116:119]
	v_mfma_f32_16x16x32_bf16 v[116:119], v[148:151], v[164:167], v[116:119]
	v_mfma_f32_16x16x32_bf16 v[100:103], v[148:151], v[172:175], v[100:103]
	v_mfma_f32_16x16x32_bf16 v[100:103], v[144:147], v[168:171], v[100:103]
	v_mfma_f32_16x16x32_bf16 v[84:87], v[144:147], v[176:179], v[84:87]
	v_mfma_f32_16x16x32_bf16 v[84:87], v[148:151], v[180:183], v[84:87]
	v_mfma_f32_16x16x32_bf16 v[68:71], v[148:151], v[204:207], v[68:71]
	v_mfma_f32_16x16x32_bf16 v[68:71], v[144:147], v[200:203], v[68:71]
	v_mfma_f32_16x16x32_bf16 v[112:115], v[152:155], v[160:163], v[112:115]
	v_mfma_f32_16x16x32_bf16 v[112:115], v[156:159], v[164:167], v[112:115]
	v_mfma_f32_16x16x32_bf16 v[96:99], v[156:159], v[172:175], v[96:99]
	v_mfma_f32_16x16x32_bf16 v[96:99], v[152:155], v[168:171], v[96:99]
	s_setprio 2
	s_barrier
	ds_read_b128 v[160:163], v235 offset:16384
	ds_read_b128 v[164:167], v235 offset:17408
	ds_read_b128 v[168:171], v235 offset:18432
	ds_read_b128 v[172:175], v235 offset:19456
	v_mfma_f32_16x16x32_bf16 v[80:83], v[152:155], v[176:179], v[80:83]
	v_mfma_f32_16x16x32_bf16 v[80:83], v[156:159], v[180:183], v[80:83]
	v_mfma_f32_16x16x32_bf16 v[64:67], v[156:159], v[204:207], v[64:67]
	v_mfma_f32_16x16x32_bf16 v[64:67], v[152:155], v[200:203], v[64:67]
	s_setprio 2
	s_add_i32 s67, s62, s49
	v_lshl_add_u64 v[208:209], s[40:41], 0, v[186:187]
	s_mov_b32 m0, s67
	ds_read_b128 v[176:179], v235 offset:20480
	ds_read_b128 v[180:183], v235 offset:21504
	ds_read_b128 v[200:203], v235 offset:22528
	ds_read_b128 v[204:207], v235 offset:23552
	global_load_lds_dwordx4 v[208:209], off
	s_add_i32 m0, s67, 0x2000
	s_add_u32 s68, s40, 0x40000
	v_lshl_add_u64 v[210:211], s[40:41], 0, v[190:191]
	s_addc_u32 s69, s41, 0
	s_add_i32 s67, s63, s49
	global_load_lds_dwordx4 v[210:211], off
	v_lshl_add_u64 v[212:213], s[68:69], 0, v[186:187]
	s_mov_b32 m0, s67
	v_lshl_add_u64 v[214:215], s[42:43], 0, v[188:189]
	global_load_lds_dwordx4 v[212:213], off
	s_add_i32 m0, s67, 0x2000
	v_lshl_add_u64 v[212:213], s[68:69], 0, v[190:191]
	global_load_lds_dwordx4 v[212:213], off
	s_mov_b32 m0, s50
	v_lshl_add_u64 v[212:213], s[42:43], 0, v[184:185]
	global_load_lds_dwordx4 v[212:213], off
	s_mov_b32 m0, s51
	s_nop 0
	global_load_lds_dwordx4 v[214:215], off
	s_waitcnt vmcnt(8) lgkmcnt(0)
	s_barrier
	s_setprio 1
	v_mfma_f32_16x16x32_bf16 v[60:63], v[120:123], v[160:163], v[60:63]
	v_mfma_f32_16x16x32_bf16 v[60:63], v[132:135], v[164:167], v[60:63]
	v_mfma_f32_16x16x32_bf16 v[44:47], v[132:135], v[172:175], v[44:47]
	v_mfma_f32_16x16x32_bf16 v[44:47], v[120:123], v[168:171], v[44:47]
	v_mfma_f32_16x16x32_bf16 v[28:31], v[120:123], v[176:179], v[28:31]
	v_mfma_f32_16x16x32_bf16 v[28:31], v[132:135], v[180:183], v[28:31]
	v_mfma_f32_16x16x32_bf16 v[12:15], v[132:135], v[204:207], v[12:15]
	v_mfma_f32_16x16x32_bf16 v[12:15], v[120:123], v[200:203], v[12:15]
	v_mfma_f32_16x16x32_bf16 v[56:59], v[136:139], v[160:163], v[56:59]
	v_mfma_f32_16x16x32_bf16 v[56:59], v[140:143], v[164:167], v[56:59]
	v_mfma_f32_16x16x32_bf16 v[40:43], v[140:143], v[172:175], v[40:43]
	v_mfma_f32_16x16x32_bf16 v[40:43], v[136:139], v[168:171], v[40:43]
	v_mfma_f32_16x16x32_bf16 v[24:27], v[136:139], v[176:179], v[24:27]
	v_mfma_f32_16x16x32_bf16 v[24:27], v[140:143], v[180:183], v[24:27]
	v_mfma_f32_16x16x32_bf16 v[8:11], v[140:143], v[204:207], v[8:11]
	v_mfma_f32_16x16x32_bf16 v[8:11], v[136:139], v[200:203], v[8:11]
	v_mfma_f32_16x16x32_bf16 v[52:55], v[144:147], v[160:163], v[52:55]
	v_mfma_f32_16x16x32_bf16 v[52:55], v[148:151], v[164:167], v[52:55]
	v_mfma_f32_16x16x32_bf16 v[36:39], v[148:151], v[172:175], v[36:39]
	v_mfma_f32_16x16x32_bf16 v[36:39], v[144:147], v[168:171], v[36:39]
	v_mfma_f32_16x16x32_bf16 v[20:23], v[144:147], v[176:179], v[20:23]
	v_mfma_f32_16x16x32_bf16 v[20:23], v[148:151], v[180:183], v[20:23]
	v_mfma_f32_16x16x32_bf16 v[4:7], v[148:151], v[204:207], v[4:7]
	v_mfma_f32_16x16x32_bf16 v[4:7], v[144:147], v[200:203], v[4:7]
	v_mfma_f32_16x16x32_bf16 v[48:51], v[152:155], v[160:163], v[48:51]
	v_mfma_f32_16x16x32_bf16 v[48:51], v[156:159], v[164:167], v[48:51]
	v_mfma_f32_16x16x32_bf16 v[32:35], v[156:159], v[172:175], v[32:35]
	v_mfma_f32_16x16x32_bf16 v[32:35], v[152:155], v[168:171], v[32:35]
	s_setprio 2
	s_barrier
	ds_read_b128 v[160:163], v235 offset:32768
	ds_read_b128 v[164:167], v235 offset:33792
	ds_read_b128 v[168:171], v235 offset:34816
	ds_read_b128 v[172:175], v235 offset:35840
	v_mfma_f32_16x16x32_bf16 v[16:19], v[152:155], v[176:179], v[16:19]
	v_mfma_f32_16x16x32_bf16 v[16:19], v[156:159], v[180:183], v[16:19]
	v_mfma_f32_16x16x32_bf16 v[0:3], v[156:159], v[204:207], v[0:3]
	v_mfma_f32_16x16x32_bf16 v[0:3], v[152:155], v[200:203], v[0:3]
	s_setprio 0
	s_add_i32 s67, 0, 0x18000
	s_add_i32 s68, 0, 0x1c000
	v_add_u32_e32 v140, s67, v232
	v_add_u32_e32 v156, s68, v232
	ds_read_b128 v[120:123], v140
	ds_read_b128 v[132:135], v140 offset:1024
	ds_read_b128 v[136:139], v140 offset:2048
	ds_read_b128 v[140:143], v140 offset:3072
	ds_read_b128 v[144:147], v156
	ds_read_b128 v[148:151], v156 offset:1024
	ds_read_b128 v[152:155], v156 offset:2048
	ds_read_b128 v[156:159], v156 offset:3072
	s_add_u32 s42, s42, 0x40000
	s_addc_u32 s43, s43, 0
	s_mov_b32 m0, s54
	v_lshl_add_u64 v[216:217], s[42:43], 0, v[184:185]
	ds_read_b128 v[176:179], v235 offset:36864
	ds_read_b128 v[180:183], v235 offset:37888
	ds_read_b128 v[200:203], v235 offset:38912
	ds_read_b128 v[204:207], v235 offset:39936
	global_load_lds_dwordx4 v[216:217], off
	s_mov_b32 m0, s55
	v_lshl_add_u64 v[216:217], s[42:43], 0, v[188:189]
	global_load_lds_dwordx4 v[216:217], off
	s_waitcnt vmcnt(8) lgkmcnt(0)
	s_barrier
	s_setprio 1
	v_mfma_f32_16x16x32_bf16 v[128:131], v[120:123], v[160:163], v[128:131]
	v_mfma_f32_16x16x32_bf16 v[128:131], v[132:135], v[164:167], v[128:131]
	v_mfma_f32_16x16x32_bf16 v[108:111], v[132:135], v[172:175], v[108:111]
	v_mfma_f32_16x16x32_bf16 v[108:111], v[120:123], v[168:171], v[108:111]
	v_mfma_f32_16x16x32_bf16 v[92:95], v[120:123], v[176:179], v[92:95]
	v_mfma_f32_16x16x32_bf16 v[92:95], v[132:135], v[180:183], v[92:95]
	v_mfma_f32_16x16x32_bf16 v[76:79], v[132:135], v[204:207], v[76:79]
	v_mfma_f32_16x16x32_bf16 v[76:79], v[120:123], v[200:203], v[76:79]
	v_mfma_f32_16x16x32_bf16 v[124:127], v[136:139], v[160:163], v[124:127]
	v_mfma_f32_16x16x32_bf16 v[124:127], v[140:143], v[164:167], v[124:127]
	v_mfma_f32_16x16x32_bf16 v[104:107], v[140:143], v[172:175], v[104:107]
	v_mfma_f32_16x16x32_bf16 v[104:107], v[136:139], v[168:171], v[104:107]
	v_mfma_f32_16x16x32_bf16 v[88:91], v[136:139], v[176:179], v[88:91]
	v_mfma_f32_16x16x32_bf16 v[88:91], v[140:143], v[180:183], v[88:91]
	v_mfma_f32_16x16x32_bf16 v[72:75], v[140:143], v[204:207], v[72:75]
	v_mfma_f32_16x16x32_bf16 v[72:75], v[136:139], v[200:203], v[72:75]
	v_mfma_f32_16x16x32_bf16 v[116:119], v[144:147], v[160:163], v[116:119]
	v_mfma_f32_16x16x32_bf16 v[116:119], v[148:151], v[164:167], v[116:119]
	v_mfma_f32_16x16x32_bf16 v[100:103], v[148:151], v[172:175], v[100:103]
	v_mfma_f32_16x16x32_bf16 v[100:103], v[144:147], v[168:171], v[100:103]
	v_mfma_f32_16x16x32_bf16 v[84:87], v[144:147], v[176:179], v[84:87]
	v_mfma_f32_16x16x32_bf16 v[84:87], v[148:151], v[180:183], v[84:87]
	v_mfma_f32_16x16x32_bf16 v[68:71], v[148:151], v[204:207], v[68:71]
	v_mfma_f32_16x16x32_bf16 v[68:71], v[144:147], v[200:203], v[68:71]
	v_mfma_f32_16x16x32_bf16 v[112:115], v[152:155], v[160:163], v[112:115]
	v_mfma_f32_16x16x32_bf16 v[112:115], v[156:159], v[164:167], v[112:115]
	v_mfma_f32_16x16x32_bf16 v[96:99], v[156:159], v[172:175], v[96:99]
	v_mfma_f32_16x16x32_bf16 v[96:99], v[152:155], v[168:171], v[96:99]
	s_setprio 2
	s_barrier
	ds_read_b128 v[160:163], v235 offset:49152
	ds_read_b128 v[164:167], v235 offset:50176
	ds_read_b128 v[168:171], v235 offset:51200
	ds_read_b128 v[172:175], v235 offset:52224
	v_mfma_f32_16x16x32_bf16 v[80:83], v[152:155], v[176:179], v[80:83]
	v_mfma_f32_16x16x32_bf16 v[80:83], v[156:159], v[180:183], v[80:83]
	v_mfma_f32_16x16x32_bf16 v[64:67], v[156:159], v[204:207], v[64:67]
	v_mfma_f32_16x16x32_bf16 v[64:67], v[152:155], v[200:203], v[64:67]
	s_setprio 2
	s_add_i32 s42, s67, s49
	v_lshl_add_u64 v[208:209], v[208:209], 0, s[18:19]
	s_mov_b32 m0, s42
	ds_read_b128 v[176:179], v235 offset:53248
	ds_read_b128 v[180:183], v235 offset:54272
	ds_read_b128 v[200:203], v235 offset:55296
	ds_read_b128 v[204:207], v235 offset:56320
	global_load_lds_dwordx4 v[208:209], off
	s_add_i32 m0, s42, 0x2000
	s_add_u32 s40, s40, 0x40080
	v_lshl_add_u64 v[208:209], v[210:211], 0, s[18:19]
	s_addc_u32 s41, s41, 0
	s_add_i32 s42, s68, s49
	global_load_lds_dwordx4 v[208:209], off
	s_mov_b32 m0, s42
	v_lshl_add_u64 v[208:209], s[40:41], 0, v[186:187]
	global_load_lds_dwordx4 v[208:209], off
	s_add_i32 m0, s42, 0x2000
	v_lshl_add_u64 v[208:209], s[40:41], 0, v[190:191]
	global_load_lds_dwordx4 v[208:209], off
	s_mov_b32 m0, s57
	v_lshl_add_u64 v[208:209], v[212:213], 0, s[18:19]
	global_load_lds_dwordx4 v[208:209], off
	s_mov_b32 m0, s58
	v_lshl_add_u64 v[208:209], v[214:215], 0, s[18:19]
	global_load_lds_dwordx4 v[208:209], off
	s_waitcnt vmcnt(8) lgkmcnt(0)
	s_barrier
	s_setprio 1
	v_mfma_f32_16x16x32_bf16 v[60:63], v[120:123], v[160:163], v[60:63]
	v_mfma_f32_16x16x32_bf16 v[60:63], v[132:135], v[164:167], v[60:63]
	v_mfma_f32_16x16x32_bf16 v[44:47], v[132:135], v[172:175], v[44:47]
	v_mfma_f32_16x16x32_bf16 v[44:47], v[120:123], v[168:171], v[44:47]
	v_mfma_f32_16x16x32_bf16 v[28:31], v[120:123], v[176:179], v[28:31]
	v_mfma_f32_16x16x32_bf16 v[28:31], v[132:135], v[180:183], v[28:31]
	v_mfma_f32_16x16x32_bf16 v[12:15], v[132:135], v[204:207], v[12:15]
	v_mfma_f32_16x16x32_bf16 v[12:15], v[120:123], v[200:203], v[12:15]
	v_mfma_f32_16x16x32_bf16 v[56:59], v[136:139], v[160:163], v[56:59]
	v_mfma_f32_16x16x32_bf16 v[56:59], v[140:143], v[164:167], v[56:59]
	v_mfma_f32_16x16x32_bf16 v[40:43], v[140:143], v[172:175], v[40:43]
	v_mfma_f32_16x16x32_bf16 v[40:43], v[136:139], v[168:171], v[40:43]
	v_mfma_f32_16x16x32_bf16 v[24:27], v[136:139], v[176:179], v[24:27]
	v_mfma_f32_16x16x32_bf16 v[24:27], v[140:143], v[180:183], v[24:27]
	v_mfma_f32_16x16x32_bf16 v[8:11], v[140:143], v[204:207], v[8:11]
	v_mfma_f32_16x16x32_bf16 v[8:11], v[136:139], v[200:203], v[8:11]
	v_mfma_f32_16x16x32_bf16 v[52:55], v[144:147], v[160:163], v[52:55]
	v_mfma_f32_16x16x32_bf16 v[52:55], v[148:151], v[164:167], v[52:55]
	v_mfma_f32_16x16x32_bf16 v[36:39], v[148:151], v[172:175], v[36:39]
	v_mfma_f32_16x16x32_bf16 v[36:39], v[144:147], v[168:171], v[36:39]
	v_mfma_f32_16x16x32_bf16 v[20:23], v[144:147], v[176:179], v[20:23]
	v_mfma_f32_16x16x32_bf16 v[20:23], v[148:151], v[180:183], v[20:23]
	v_mfma_f32_16x16x32_bf16 v[4:7], v[148:151], v[204:207], v[4:7]
	v_mfma_f32_16x16x32_bf16 v[4:7], v[144:147], v[200:203], v[4:7]
	v_mfma_f32_16x16x32_bf16 v[48:51], v[152:155], v[160:163], v[48:51]
	v_mfma_f32_16x16x32_bf16 v[48:51], v[156:159], v[164:167], v[48:51]
	v_mfma_f32_16x16x32_bf16 v[32:35], v[156:159], v[172:175], v[32:35]
	v_mfma_f32_16x16x32_bf16 v[32:35], v[152:155], v[168:171], v[32:35]
	s_setprio 2
	s_barrier
	v_mfma_f32_16x16x32_bf16 v[16:19], v[152:155], v[176:179], v[16:19]
	v_mfma_f32_16x16x32_bf16 v[16:19], v[156:159], v[180:183], v[16:19]
	v_mfma_f32_16x16x32_bf16 v[0:3], v[156:159], v[204:207], v[0:3]
	v_mfma_f32_16x16x32_bf16 v[0:3], v[152:155], v[200:203], v[0:3]
	s_setprio 0
	s_add_i32 s66, s66, 2
	s_add_u32 s38, s38, 0x100
	s_addc_u32 s39, s39, 0
	s_add_u32 s64, s64, 0x100
	s_addc_u32 s65, s65, 0
	s_cmp_gt_u32 s66, 13
	s_cbranch_scc0 .LBB0_1146

.LBB0_1309:
	s_add_u32 s51, s26, 0x100
	s_addc_u32 s52, s27, 0
	s_mov_b32 s53, -2
	ds_read_b128 v[128:131], v197
	ds_read_b128 v[132:135], v197 offset:1024
	ds_read_b128 v[136:139], v197 offset:2048
	ds_read_b128 v[140:143], v197 offset:3072
	ds_read_b128 v[144:147], v198
	ds_read_b128 v[148:151], v198 offset:1024
	ds_read_b128 v[152:155], v198 offset:2048
	ds_read_b128 v[156:159], v198 offset:3072
	s_add_u32 s4, s24, 0x100
	s_addc_u32 s5, s25, 0
	s_cmp_eq_u32 s53, 40
	s_cselect_b32 s29, s21, s5
	s_cselect_b32 s28, s20, s4
	s_cselect_b32 s27, s23, s52
	s_cselect_b32 s26, s22, s51
	v_lshl_add_u64 v[212:213], s[24:25], 0, v[172:173]
	s_add_i32 m0, s36, 0xc000
	ds_read_b128 v[160:163], v199
	ds_read_b128 v[180:183], v199 offset:1024
	ds_read_b128 v[184:187], v199 offset:2048
	ds_read_b128 v[188:191], v199 offset:3072
	ds_read_b128 v[192:195], v199 offset:4096
	ds_read_b128 v[200:203], v199 offset:5120
	ds_read_b128 v[204:207], v199 offset:6144
	ds_read_b128 v[208:211], v199 offset:7168
	global_load_lds_dwordx4 v[212:213], off
	s_add_i32 m0, s36, 0xe000
	v_lshl_add_u64 v[212:213], s[24:25], 0, v[174:175]
	global_load_lds_dwordx4 v[212:213], off
	s_waitcnt vmcnt(8) lgkmcnt(0)
	s_barrier
	s_setprio 1
	v_mfma_f32_16x16x32_bf16 v[124:127], v[128:131], v[160:163], 0
	v_mfma_f32_16x16x32_bf16 v[124:127], v[132:135], v[180:183], v[124:127]
	v_mfma_f32_16x16x32_bf16 v[116:119], v[132:135], v[188:191], 0
	v_mfma_f32_16x16x32_bf16 v[116:119], v[128:131], v[184:187], v[116:119]
	v_mfma_f32_16x16x32_bf16 v[88:91], v[128:131], v[192:195], 0
	v_mfma_f32_16x16x32_bf16 v[88:91], v[132:135], v[200:203], v[88:91]
	v_mfma_f32_16x16x32_bf16 v[72:75], v[132:135], v[208:211], 0
	v_mfma_f32_16x16x32_bf16 v[72:75], v[128:131], v[204:207], v[72:75]
	v_mfma_f32_16x16x32_bf16 v[120:123], v[136:139], v[160:163], 0
	v_mfma_f32_16x16x32_bf16 v[120:123], v[140:143], v[180:183], v[120:123]
	v_mfma_f32_16x16x32_bf16 v[108:111], v[140:143], v[188:191], 0
	v_mfma_f32_16x16x32_bf16 v[108:111], v[136:139], v[184:187], v[108:111]
	v_mfma_f32_16x16x32_bf16 v[100:103], v[136:139], v[192:195], 0
	v_mfma_f32_16x16x32_bf16 v[100:103], v[140:143], v[200:203], v[100:103]
	v_mfma_f32_16x16x32_bf16 v[76:79], v[140:143], v[208:211], 0
	v_mfma_f32_16x16x32_bf16 v[76:79], v[136:139], v[204:207], v[76:79]
	v_mfma_f32_16x16x32_bf16 v[112:115], v[144:147], v[160:163], 0
	v_mfma_f32_16x16x32_bf16 v[112:115], v[148:151], v[180:183], v[112:115]
	v_mfma_f32_16x16x32_bf16 v[96:99], v[148:151], v[188:191], 0
	v_mfma_f32_16x16x32_bf16 v[96:99], v[144:147], v[184:187], v[96:99]
	v_mfma_f32_16x16x32_bf16 v[80:83], v[144:147], v[192:195], 0
	v_mfma_f32_16x16x32_bf16 v[80:83], v[148:151], v[200:203], v[80:83]
	v_mfma_f32_16x16x32_bf16 v[64:67], v[148:151], v[208:211], 0
	v_mfma_f32_16x16x32_bf16 v[64:67], v[144:147], v[204:207], v[64:67]
	v_mfma_f32_16x16x32_bf16 v[104:107], v[152:155], v[160:163], 0
	v_mfma_f32_16x16x32_bf16 v[104:107], v[156:159], v[180:183], v[104:107]
	v_mfma_f32_16x16x32_bf16 v[92:95], v[156:159], v[188:191], 0
	v_mfma_f32_16x16x32_bf16 v[92:95], v[152:155], v[184:187], v[92:95]
	s_setprio 2
	s_barrier
	ds_read_b128 v[160:163], v199 offset:16384
	ds_read_b128 v[180:183], v199 offset:17408
	ds_read_b128 v[184:187], v199 offset:18432
	ds_read_b128 v[188:191], v199 offset:19456
	v_mfma_f32_16x16x32_bf16 v[84:87], v[152:155], v[192:195], 0
	v_mfma_f32_16x16x32_bf16 v[84:87], v[156:159], v[200:203], v[84:87]
	v_mfma_f32_16x16x32_bf16 v[68:71], v[156:159], v[208:211], 0
	v_mfma_f32_16x16x32_bf16 v[68:71], v[152:155], v[204:207], v[68:71]
	s_setprio 2
	s_add_i32 s24, s45, s35
	v_lshl_add_u64 v[212:213], s[26:27], 0, v[166:167]
	s_mov_b32 m0, s24
	ds_read_b128 v[192:195], v199 offset:20480
	ds_read_b128 v[200:203], v199 offset:21504
	ds_read_b128 v[204:207], v199 offset:22528
	ds_read_b128 v[208:211], v199 offset:23552
	global_load_lds_dwordx4 v[212:213], off
	s_add_i32 m0, s24, 0x2000
	s_add_u32 s24, s26, 0xb0000
	v_lshl_add_u64 v[214:215], s[26:27], 0, v[170:171]
	s_addc_u32 s25, s27, 0
	s_add_i32 s54, s46, s35
	global_load_lds_dwordx4 v[214:215], off
	v_lshl_add_u64 v[216:217], s[24:25], 0, v[166:167]
	s_mov_b32 m0, s54
	v_lshl_add_u64 v[218:219], s[28:29], 0, v[168:169]
	global_load_lds_dwordx4 v[216:217], off
	s_add_i32 m0, s54, 0x2000
	v_lshl_add_u64 v[216:217], s[24:25], 0, v[170:171]
	global_load_lds_dwordx4 v[216:217], off
	s_mov_b32 m0, s36
	v_lshl_add_u64 v[216:217], s[28:29], 0, v[164:165]
	global_load_lds_dwordx4 v[216:217], off
	s_mov_b32 m0, s37
	s_nop 0
	global_load_lds_dwordx4 v[218:219], off
	s_waitcnt vmcnt(8) lgkmcnt(0)
	s_barrier
	s_setprio 1
	v_mfma_f32_16x16x32_bf16 v[56:59], v[128:131], v[160:163], 0
	v_mfma_f32_16x16x32_bf16 v[56:59], v[132:135], v[180:183], v[56:59]
	v_mfma_f32_16x16x32_bf16 v[40:43], v[132:135], v[188:191], 0
	v_mfma_f32_16x16x32_bf16 v[40:43], v[128:131], v[184:187], v[40:43]
	v_mfma_f32_16x16x32_bf16 v[24:27], v[128:131], v[192:195], 0
	v_mfma_f32_16x16x32_bf16 v[24:27], v[132:135], v[200:203], v[24:27]
	v_mfma_f32_16x16x32_bf16 v[8:11], v[132:135], v[208:211], 0
	v_mfma_f32_16x16x32_bf16 v[8:11], v[128:131], v[204:207], v[8:11]
	v_mfma_f32_16x16x32_bf16 v[60:63], v[136:139], v[160:163], 0
	v_mfma_f32_16x16x32_bf16 v[60:63], v[140:143], v[180:183], v[60:63]
	v_mfma_f32_16x16x32_bf16 v[44:47], v[140:143], v[188:191], 0
	v_mfma_f32_16x16x32_bf16 v[44:47], v[136:139], v[184:187], v[44:47]
	v_mfma_f32_16x16x32_bf16 v[28:31], v[136:139], v[192:195], 0
	v_mfma_f32_16x16x32_bf16 v[28:31], v[140:143], v[200:203], v[28:31]
	v_mfma_f32_16x16x32_bf16 v[12:15], v[140:143], v[208:211], 0
	v_mfma_f32_16x16x32_bf16 v[12:15], v[136:139], v[204:207], v[12:15]
	v_mfma_f32_16x16x32_bf16 v[48:51], v[144:147], v[160:163], 0
	v_mfma_f32_16x16x32_bf16 v[48:51], v[148:151], v[180:183], v[48:51]
	v_mfma_f32_16x16x32_bf16 v[32:35], v[148:151], v[188:191], 0
	v_mfma_f32_16x16x32_bf16 v[32:35], v[144:147], v[184:187], v[32:35]
	v_mfma_f32_16x16x32_bf16 v[16:19], v[144:147], v[192:195], 0
	v_mfma_f32_16x16x32_bf16 v[16:19], v[148:151], v[200:203], v[16:19]
	v_mfma_f32_16x16x32_bf16 v[0:3], v[148:151], v[208:211], 0
	v_mfma_f32_16x16x32_bf16 v[0:3], v[144:147], v[204:207], v[0:3]
	v_mfma_f32_16x16x32_bf16 v[52:55], v[152:155], v[160:163], 0
	v_mfma_f32_16x16x32_bf16 v[52:55], v[156:159], v[180:183], v[52:55]
	v_mfma_f32_16x16x32_bf16 v[36:39], v[156:159], v[188:191], 0
	v_mfma_f32_16x16x32_bf16 v[36:39], v[152:155], v[184:187], v[36:39]
	s_setprio 2
	s_barrier
	ds_read_b128 v[160:163], v199 offset:32768
	ds_read_b128 v[180:183], v199 offset:33792
	ds_read_b128 v[184:187], v199 offset:34816
	ds_read_b128 v[188:191], v199 offset:35840
	v_mfma_f32_16x16x32_bf16 v[20:23], v[152:155], v[192:195], 0
	v_mfma_f32_16x16x32_bf16 v[20:23], v[156:159], v[200:203], v[20:23]
	v_mfma_f32_16x16x32_bf16 v[4:7], v[156:159], v[208:211], 0
	v_mfma_f32_16x16x32_bf16 v[4:7], v[152:155], v[204:207], v[4:7]
	s_setprio 0
	s_add_i32 s54, 0, 0x18000
	s_add_i32 s55, 0, 0x1c000
	v_add_u32_e32 v140, s54, v196
	v_add_u32_e32 v156, s55, v196
	ds_read_b128 v[128:131], v140
	ds_read_b128 v[132:135], v140 offset:1024
	ds_read_b128 v[136:139], v140 offset:2048
	ds_read_b128 v[140:143], v140 offset:3072
	ds_read_b128 v[144:147], v156
	ds_read_b128 v[148:151], v156 offset:1024
	ds_read_b128 v[152:155], v156 offset:2048
	ds_read_b128 v[156:159], v156 offset:3072
	s_add_u32 s24, s28, 0xb0000
	s_addc_u32 s25, s29, 0
	s_mov_b32 m0, s38
	v_lshl_add_u64 v[220:221], s[24:25], 0, v[164:165]
	ds_read_b128 v[192:195], v199 offset:36864
	ds_read_b128 v[200:203], v199 offset:37888
	ds_read_b128 v[204:207], v199 offset:38912
	ds_read_b128 v[208:211], v199 offset:39936
	global_load_lds_dwordx4 v[220:221], off
	s_mov_b32 m0, s39
	v_lshl_add_u64 v[220:221], s[24:25], 0, v[168:169]
	global_load_lds_dwordx4 v[220:221], off
	s_waitcnt vmcnt(8) lgkmcnt(0)
	s_barrier
	s_setprio 1
	v_mfma_f32_16x16x32_bf16 v[124:127], v[128:131], v[160:163], v[124:127]
	v_mfma_f32_16x16x32_bf16 v[124:127], v[132:135], v[180:183], v[124:127]
	v_mfma_f32_16x16x32_bf16 v[116:119], v[132:135], v[188:191], v[116:119]
	v_mfma_f32_16x16x32_bf16 v[116:119], v[128:131], v[184:187], v[116:119]
	v_mfma_f32_16x16x32_bf16 v[88:91], v[128:131], v[192:195], v[88:91]
	v_mfma_f32_16x16x32_bf16 v[88:91], v[132:135], v[200:203], v[88:91]
	v_mfma_f32_16x16x32_bf16 v[72:75], v[132:135], v[208:211], v[72:75]
	v_mfma_f32_16x16x32_bf16 v[72:75], v[128:131], v[204:207], v[72:75]
	v_mfma_f32_16x16x32_bf16 v[120:123], v[136:139], v[160:163], v[120:123]
	v_mfma_f32_16x16x32_bf16 v[120:123], v[140:143], v[180:183], v[120:123]
	v_mfma_f32_16x16x32_bf16 v[108:111], v[140:143], v[188:191], v[108:111]
	v_mfma_f32_16x16x32_bf16 v[108:111], v[136:139], v[184:187], v[108:111]
	v_mfma_f32_16x16x32_bf16 v[100:103], v[136:139], v[192:195], v[100:103]
	v_mfma_f32_16x16x32_bf16 v[100:103], v[140:143], v[200:203], v[100:103]
	v_mfma_f32_16x16x32_bf16 v[76:79], v[140:143], v[208:211], v[76:79]
	v_mfma_f32_16x16x32_bf16 v[76:79], v[136:139], v[204:207], v[76:79]
	v_mfma_f32_16x16x32_bf16 v[112:115], v[144:147], v[160:163], v[112:115]
	v_mfma_f32_16x16x32_bf16 v[112:115], v[148:151], v[180:183], v[112:115]
	v_mfma_f32_16x16x32_bf16 v[96:99], v[148:151], v[188:191], v[96:99]
	v_mfma_f32_16x16x32_bf16 v[96:99], v[144:147], v[184:187], v[96:99]
	v_mfma_f32_16x16x32_bf16 v[80:83], v[144:147], v[192:195], v[80:83]
	v_mfma_f32_16x16x32_bf16 v[80:83], v[148:151], v[200:203], v[80:83]
	v_mfma_f32_16x16x32_bf16 v[64:67], v[148:151], v[208:211], v[64:67]
	v_mfma_f32_16x16x32_bf16 v[64:67], v[144:147], v[204:207], v[64:67]
	v_mfma_f32_16x16x32_bf16 v[104:107], v[152:155], v[160:163], v[104:107]
	v_mfma_f32_16x16x32_bf16 v[104:107], v[156:159], v[180:183], v[104:107]
	v_mfma_f32_16x16x32_bf16 v[92:95], v[156:159], v[188:191], v[92:95]
	v_mfma_f32_16x16x32_bf16 v[92:95], v[152:155], v[184:187], v[92:95]
	s_setprio 2
	s_barrier
	ds_read_b128 v[160:163], v199 offset:49152
	ds_read_b128 v[180:183], v199 offset:50176
	ds_read_b128 v[184:187], v199 offset:51200
	ds_read_b128 v[188:191], v199 offset:52224
	v_mfma_f32_16x16x32_bf16 v[84:87], v[152:155], v[192:195], v[84:87]
	v_mfma_f32_16x16x32_bf16 v[84:87], v[156:159], v[200:203], v[84:87]
	v_mfma_f32_16x16x32_bf16 v[68:71], v[156:159], v[208:211], v[68:71]
	v_mfma_f32_16x16x32_bf16 v[68:71], v[152:155], v[204:207], v[68:71]
	s_setprio 2
	s_add_i32 s24, s54, s35
	v_lshl_add_u64 v[212:213], v[212:213], 0, s[16:17]
	s_mov_b32 m0, s24
	ds_read_b128 v[192:195], v199 offset:53248
	ds_read_b128 v[200:203], v199 offset:54272
	ds_read_b128 v[204:207], v199 offset:55296
	ds_read_b128 v[208:211], v199 offset:56320
	global_load_lds_dwordx4 v[212:213], off
	s_add_i32 m0, s24, 0x2000
	s_add_u32 s24, s26, 0xb0080
	v_lshl_add_u64 v[212:213], v[214:215], 0, s[16:17]
	s_addc_u32 s25, s27, 0
	s_add_i32 s26, s55, s35
	global_load_lds_dwordx4 v[212:213], off
	s_mov_b32 m0, s26
	v_lshl_add_u64 v[212:213], s[24:25], 0, v[166:167]
	global_load_lds_dwordx4 v[212:213], off
	s_add_i32 m0, s26, 0x2000
	v_lshl_add_u64 v[212:213], s[24:25], 0, v[170:171]
	global_load_lds_dwordx4 v[212:213], off
	s_mov_b32 m0, s41
	v_lshl_add_u64 v[212:213], v[216:217], 0, s[16:17]
	global_load_lds_dwordx4 v[212:213], off
	s_mov_b32 m0, s42
	v_lshl_add_u64 v[212:213], v[218:219], 0, s[16:17]
	global_load_lds_dwordx4 v[212:213], off
	s_waitcnt vmcnt(8) lgkmcnt(0)
	s_barrier
	s_setprio 1
	v_mfma_f32_16x16x32_bf16 v[56:59], v[128:131], v[160:163], v[56:59]
	v_mfma_f32_16x16x32_bf16 v[56:59], v[132:135], v[180:183], v[56:59]
	v_mfma_f32_16x16x32_bf16 v[40:43], v[132:135], v[188:191], v[40:43]
	v_mfma_f32_16x16x32_bf16 v[40:43], v[128:131], v[184:187], v[40:43]
	v_mfma_f32_16x16x32_bf16 v[24:27], v[128:131], v[192:195], v[24:27]
	v_mfma_f32_16x16x32_bf16 v[24:27], v[132:135], v[200:203], v[24:27]
	v_mfma_f32_16x16x32_bf16 v[8:11], v[132:135], v[208:211], v[8:11]
	v_mfma_f32_16x16x32_bf16 v[8:11], v[128:131], v[204:207], v[8:11]
	v_mfma_f32_16x16x32_bf16 v[60:63], v[136:139], v[160:163], v[60:63]
	v_mfma_f32_16x16x32_bf16 v[60:63], v[140:143], v[180:183], v[60:63]
	v_mfma_f32_16x16x32_bf16 v[44:47], v[140:143], v[188:191], v[44:47]
	v_mfma_f32_16x16x32_bf16 v[44:47], v[136:139], v[184:187], v[44:47]
	v_mfma_f32_16x16x32_bf16 v[28:31], v[136:139], v[192:195], v[28:31]
	v_mfma_f32_16x16x32_bf16 v[28:31], v[140:143], v[200:203], v[28:31]
	v_mfma_f32_16x16x32_bf16 v[12:15], v[140:143], v[208:211], v[12:15]
	v_mfma_f32_16x16x32_bf16 v[12:15], v[136:139], v[204:207], v[12:15]
	v_mfma_f32_16x16x32_bf16 v[48:51], v[144:147], v[160:163], v[48:51]
	v_mfma_f32_16x16x32_bf16 v[48:51], v[148:151], v[180:183], v[48:51]
	v_mfma_f32_16x16x32_bf16 v[32:35], v[148:151], v[188:191], v[32:35]
	v_mfma_f32_16x16x32_bf16 v[32:35], v[144:147], v[184:187], v[32:35]
	v_mfma_f32_16x16x32_bf16 v[16:19], v[144:147], v[192:195], v[16:19]
	v_mfma_f32_16x16x32_bf16 v[16:19], v[148:151], v[200:203], v[16:19]
	v_mfma_f32_16x16x32_bf16 v[0:3], v[148:151], v[208:211], v[0:3]
	v_mfma_f32_16x16x32_bf16 v[0:3], v[144:147], v[204:207], v[0:3]
	v_mfma_f32_16x16x32_bf16 v[52:55], v[152:155], v[160:163], v[52:55]
	v_mfma_f32_16x16x32_bf16 v[52:55], v[156:159], v[180:183], v[52:55]
	v_mfma_f32_16x16x32_bf16 v[36:39], v[156:159], v[188:191], v[36:39]
	v_mfma_f32_16x16x32_bf16 v[36:39], v[152:155], v[184:187], v[36:39]
	s_setprio 2
	s_barrier
	v_mfma_f32_16x16x32_bf16 v[20:23], v[152:155], v[192:195], v[20:23]
	v_mfma_f32_16x16x32_bf16 v[20:23], v[156:159], v[200:203], v[20:23]
	v_mfma_f32_16x16x32_bf16 v[4:7], v[156:159], v[208:211], v[4:7]
	v_mfma_f32_16x16x32_bf16 v[4:7], v[152:155], v[204:207], v[4:7]
	s_setprio 0
	s_add_i32 s53, s53, 2
	s_add_u32 s51, s51, 0x100
	s_addc_u32 s52, s52, 0
	s_cmp_gt_u32 s53, 41
	s_mov_b64 s[24:25], s[4:5]
.LBB0_1310:
	ds_read_b128 v[128:131], v197
	ds_read_b128 v[132:135], v197 offset:1024
	ds_read_b128 v[136:139], v197 offset:2048
	ds_read_b128 v[140:143], v197 offset:3072
	ds_read_b128 v[144:147], v198
	ds_read_b128 v[148:151], v198 offset:1024
	ds_read_b128 v[152:155], v198 offset:2048
	ds_read_b128 v[156:159], v198 offset:3072
	s_add_u32 s4, s24, 0x100
	s_addc_u32 s5, s25, 0
	s_cmp_eq_u32 s53, 40
	s_cselect_b32 s29, s21, s5
	s_cselect_b32 s28, s20, s4
	s_cselect_b32 s27, s23, s52
	s_cselect_b32 s26, s22, s51
	v_lshl_add_u64 v[212:213], s[24:25], 0, v[172:173]
	s_add_i32 m0, s36, 0xc000
	ds_read_b128 v[160:163], v199
	ds_read_b128 v[180:183], v199 offset:1024
	ds_read_b128 v[184:187], v199 offset:2048
	ds_read_b128 v[188:191], v199 offset:3072
	ds_read_b128 v[192:195], v199 offset:4096
	ds_read_b128 v[200:203], v199 offset:5120
	ds_read_b128 v[204:207], v199 offset:6144
	ds_read_b128 v[208:211], v199 offset:7168
	global_load_lds_dwordx4 v[212:213], off
	s_add_i32 m0, s36, 0xe000
	v_lshl_add_u64 v[212:213], s[24:25], 0, v[174:175]
	global_load_lds_dwordx4 v[212:213], off
	s_waitcnt vmcnt(8) lgkmcnt(0)
	s_barrier
	s_setprio 1
	v_mfma_f32_16x16x32_bf16 v[124:127], v[128:131], v[160:163], v[124:127]
	v_mfma_f32_16x16x32_bf16 v[124:127], v[132:135], v[180:183], v[124:127]
	v_mfma_f32_16x16x32_bf16 v[116:119], v[132:135], v[188:191], v[116:119]
	v_mfma_f32_16x16x32_bf16 v[116:119], v[128:131], v[184:187], v[116:119]
	v_mfma_f32_16x16x32_bf16 v[88:91], v[128:131], v[192:195], v[88:91]
	v_mfma_f32_16x16x32_bf16 v[88:91], v[132:135], v[200:203], v[88:91]
	v_mfma_f32_16x16x32_bf16 v[72:75], v[132:135], v[208:211], v[72:75]
	v_mfma_f32_16x16x32_bf16 v[72:75], v[128:131], v[204:207], v[72:75]
	v_mfma_f32_16x16x32_bf16 v[120:123], v[136:139], v[160:163], v[120:123]
	v_mfma_f32_16x16x32_bf16 v[120:123], v[140:143], v[180:183], v[120:123]
	v_mfma_f32_16x16x32_bf16 v[108:111], v[140:143], v[188:191], v[108:111]
	v_mfma_f32_16x16x32_bf16 v[108:111], v[136:139], v[184:187], v[108:111]
	v_mfma_f32_16x16x32_bf16 v[100:103], v[136:139], v[192:195], v[100:103]
	v_mfma_f32_16x16x32_bf16 v[100:103], v[140:143], v[200:203], v[100:103]
	v_mfma_f32_16x16x32_bf16 v[76:79], v[140:143], v[208:211], v[76:79]
	v_mfma_f32_16x16x32_bf16 v[76:79], v[136:139], v[204:207], v[76:79]
	v_mfma_f32_16x16x32_bf16 v[112:115], v[144:147], v[160:163], v[112:115]
	v_mfma_f32_16x16x32_bf16 v[112:115], v[148:151], v[180:183], v[112:115]
	v_mfma_f32_16x16x32_bf16 v[96:99], v[148:151], v[188:191], v[96:99]
	v_mfma_f32_16x16x32_bf16 v[96:99], v[144:147], v[184:187], v[96:99]
	v_mfma_f32_16x16x32_bf16 v[80:83], v[144:147], v[192:195], v[80:83]
	v_mfma_f32_16x16x32_bf16 v[80:83], v[148:151], v[200:203], v[80:83]
	v_mfma_f32_16x16x32_bf16 v[64:67], v[148:151], v[208:211], v[64:67]
	v_mfma_f32_16x16x32_bf16 v[64:67], v[144:147], v[204:207], v[64:67]
	v_mfma_f32_16x16x32_bf16 v[104:107], v[152:155], v[160:163], v[104:107]
	v_mfma_f32_16x16x32_bf16 v[104:107], v[156:159], v[180:183], v[104:107]
	v_mfma_f32_16x16x32_bf16 v[92:95], v[156:159], v[188:191], v[92:95]
	v_mfma_f32_16x16x32_bf16 v[92:95], v[152:155], v[184:187], v[92:95]
	s_setprio 2
	s_barrier
	ds_read_b128 v[160:163], v199 offset:16384
	ds_read_b128 v[180:183], v199 offset:17408
	ds_read_b128 v[184:187], v199 offset:18432
	ds_read_b128 v[188:191], v199 offset:19456
	v_mfma_f32_16x16x32_bf16 v[84:87], v[152:155], v[192:195], v[84:87]
	v_mfma_f32_16x16x32_bf16 v[84:87], v[156:159], v[200:203], v[84:87]
	v_mfma_f32_16x16x32_bf16 v[68:71], v[156:159], v[208:211], v[68:71]
	v_mfma_f32_16x16x32_bf16 v[68:71], v[152:155], v[204:207], v[68:71]
	s_setprio 2
	s_add_i32 s24, s45, s35
	v_lshl_add_u64 v[212:213], s[26:27], 0, v[166:167]
	s_mov_b32 m0, s24
	ds_read_b128 v[192:195], v199 offset:20480
	ds_read_b128 v[200:203], v199 offset:21504
	ds_read_b128 v[204:207], v199 offset:22528
	ds_read_b128 v[208:211], v199 offset:23552
	global_load_lds_dwordx4 v[212:213], off
	s_add_i32 m0, s24, 0x2000
	s_add_u32 s24, s26, 0xb0000
	v_lshl_add_u64 v[214:215], s[26:27], 0, v[170:171]
	s_addc_u32 s25, s27, 0
	s_add_i32 s54, s46, s35
	global_load_lds_dwordx4 v[214:215], off
	v_lshl_add_u64 v[216:217], s[24:25], 0, v[166:167]
	s_mov_b32 m0, s54
	v_lshl_add_u64 v[218:219], s[28:29], 0, v[168:169]
	global_load_lds_dwordx4 v[216:217], off
	s_add_i32 m0, s54, 0x2000
	v_lshl_add_u64 v[216:217], s[24:25], 0, v[170:171]
	global_load_lds_dwordx4 v[216:217], off
	s_mov_b32 m0, s36
	v_lshl_add_u64 v[216:217], s[28:29], 0, v[164:165]
	global_load_lds_dwordx4 v[216:217], off
	s_mov_b32 m0, s37
	s_nop 0
	global_load_lds_dwordx4 v[218:219], off
	s_waitcnt vmcnt(8) lgkmcnt(0)
	s_barrier
	s_setprio 1
	v_mfma_f32_16x16x32_bf16 v[56:59], v[128:131], v[160:163], v[56:59]
	v_mfma_f32_16x16x32_bf16 v[56:59], v[132:135], v[180:183], v[56:59]
	v_mfma_f32_16x16x32_bf16 v[40:43], v[132:135], v[188:191], v[40:43]
	v_mfma_f32_16x16x32_bf16 v[40:43], v[128:131], v[184:187], v[40:43]
	v_mfma_f32_16x16x32_bf16 v[24:27], v[128:131], v[192:195], v[24:27]
	v_mfma_f32_16x16x32_bf16 v[24:27], v[132:135], v[200:203], v[24:27]
	v_mfma_f32_16x16x32_bf16 v[8:11], v[132:135], v[208:211], v[8:11]
	v_mfma_f32_16x16x32_bf16 v[8:11], v[128:131], v[204:207], v[8:11]
	v_mfma_f32_16x16x32_bf16 v[60:63], v[136:139], v[160:163], v[60:63]
	v_mfma_f32_16x16x32_bf16 v[60:63], v[140:143], v[180:183], v[60:63]
	v_mfma_f32_16x16x32_bf16 v[44:47], v[140:143], v[188:191], v[44:47]
	v_mfma_f32_16x16x32_bf16 v[44:47], v[136:139], v[184:187], v[44:47]
	v_mfma_f32_16x16x32_bf16 v[28:31], v[136:139], v[192:195], v[28:31]
	v_mfma_f32_16x16x32_bf16 v[28:31], v[140:143], v[200:203], v[28:31]
	v_mfma_f32_16x16x32_bf16 v[12:15], v[140:143], v[208:211], v[12:15]
	v_mfma_f32_16x16x32_bf16 v[12:15], v[136:139], v[204:207], v[12:15]
	v_mfma_f32_16x16x32_bf16 v[48:51], v[144:147], v[160:163], v[48:51]
	v_mfma_f32_16x16x32_bf16 v[48:51], v[148:151], v[180:183], v[48:51]
	v_mfma_f32_16x16x32_bf16 v[32:35], v[148:151], v[188:191], v[32:35]
	v_mfma_f32_16x16x32_bf16 v[32:35], v[144:147], v[184:187], v[32:35]
	v_mfma_f32_16x16x32_bf16 v[16:19], v[144:147], v[192:195], v[16:19]
	v_mfma_f32_16x16x32_bf16 v[16:19], v[148:151], v[200:203], v[16:19]
	v_mfma_f32_16x16x32_bf16 v[0:3], v[148:151], v[208:211], v[0:3]
	v_mfma_f32_16x16x32_bf16 v[0:3], v[144:147], v[204:207], v[0:3]
	v_mfma_f32_16x16x32_bf16 v[52:55], v[152:155], v[160:163], v[52:55]
	v_mfma_f32_16x16x32_bf16 v[52:55], v[156:159], v[180:183], v[52:55]
	v_mfma_f32_16x16x32_bf16 v[36:39], v[156:159], v[188:191], v[36:39]
	v_mfma_f32_16x16x32_bf16 v[36:39], v[152:155], v[184:187], v[36:39]
	s_setprio 2
	s_barrier
	ds_read_b128 v[160:163], v199 offset:32768
	ds_read_b128 v[180:183], v199 offset:33792
	ds_read_b128 v[184:187], v199 offset:34816
	ds_read_b128 v[188:191], v199 offset:35840
	v_mfma_f32_16x16x32_bf16 v[20:23], v[152:155], v[192:195], v[20:23]
	v_mfma_f32_16x16x32_bf16 v[20:23], v[156:159], v[200:203], v[20:23]
	v_mfma_f32_16x16x32_bf16 v[4:7], v[156:159], v[208:211], v[4:7]
	v_mfma_f32_16x16x32_bf16 v[4:7], v[152:155], v[204:207], v[4:7]
	s_setprio 0
	s_add_i32 s54, 0, 0x18000
	s_add_i32 s55, 0, 0x1c000
	v_add_u32_e32 v140, s54, v196
	v_add_u32_e32 v156, s55, v196
	ds_read_b128 v[128:131], v140
	ds_read_b128 v[132:135], v140 offset:1024
	ds_read_b128 v[136:139], v140 offset:2048
	ds_read_b128 v[140:143], v140 offset:3072
	ds_read_b128 v[144:147], v156
	ds_read_b128 v[148:151], v156 offset:1024
	ds_read_b128 v[152:155], v156 offset:2048
	ds_read_b128 v[156:159], v156 offset:3072
	s_add_u32 s24, s28, 0xb0000
	s_addc_u32 s25, s29, 0
	s_mov_b32 m0, s38
	v_lshl_add_u64 v[220:221], s[24:25], 0, v[164:165]
	ds_read_b128 v[192:195], v199 offset:36864
	ds_read_b128 v[200:203], v199 offset:37888
	ds_read_b128 v[204:207], v199 offset:38912
	ds_read_b128 v[208:211], v199 offset:39936
	global_load_lds_dwordx4 v[220:221], off
	s_mov_b32 m0, s39
	v_lshl_add_u64 v[220:221], s[24:25], 0, v[168:169]
	global_load_lds_dwordx4 v[220:221], off
	s_waitcnt vmcnt(8) lgkmcnt(0)
	s_barrier
	s_setprio 1
	v_mfma_f32_16x16x32_bf16 v[124:127], v[128:131], v[160:163], v[124:127]
	v_mfma_f32_16x16x32_bf16 v[124:127], v[132:135], v[180:183], v[124:127]
	v_mfma_f32_16x16x32_bf16 v[116:119], v[132:135], v[188:191], v[116:119]
	v_mfma_f32_16x16x32_bf16 v[116:119], v[128:131], v[184:187], v[116:119]
	v_mfma_f32_16x16x32_bf16 v[88:91], v[128:131], v[192:195], v[88:91]
	v_mfma_f32_16x16x32_bf16 v[88:91], v[132:135], v[200:203], v[88:91]
	v_mfma_f32_16x16x32_bf16 v[72:75], v[132:135], v[208:211], v[72:75]
	v_mfma_f32_16x16x32_bf16 v[72:75], v[128:131], v[204:207], v[72:75]
	v_mfma_f32_16x16x32_bf16 v[120:123], v[136:139], v[160:163], v[120:123]
	v_mfma_f32_16x16x32_bf16 v[120:123], v[140:143], v[180:183], v[120:123]
	v_mfma_f32_16x16x32_bf16 v[108:111], v[140:143], v[188:191], v[108:111]
	v_mfma_f32_16x16x32_bf16 v[108:111], v[136:139], v[184:187], v[108:111]
	v_mfma_f32_16x16x32_bf16 v[100:103], v[136:139], v[192:195], v[100:103]
	v_mfma_f32_16x16x32_bf16 v[100:103], v[140:143], v[200:203], v[100:103]
	v_mfma_f32_16x16x32_bf16 v[76:79], v[140:143], v[208:211], v[76:79]
	v_mfma_f32_16x16x32_bf16 v[76:79], v[136:139], v[204:207], v[76:79]
	v_mfma_f32_16x16x32_bf16 v[112:115], v[144:147], v[160:163], v[112:115]
	v_mfma_f32_16x16x32_bf16 v[112:115], v[148:151], v[180:183], v[112:115]
	v_mfma_f32_16x16x32_bf16 v[96:99], v[148:151], v[188:191], v[96:99]
	v_mfma_f32_16x16x32_bf16 v[96:99], v[144:147], v[184:187], v[96:99]
	v_mfma_f32_16x16x32_bf16 v[80:83], v[144:147], v[192:195], v[80:83]
	v_mfma_f32_16x16x32_bf16 v[80:83], v[148:151], v[200:203], v[80:83]
	v_mfma_f32_16x16x32_bf16 v[64:67], v[148:151], v[208:211], v[64:67]
	v_mfma_f32_16x16x32_bf16 v[64:67], v[144:147], v[204:207], v[64:67]
	v_mfma_f32_16x16x32_bf16 v[104:107], v[152:155], v[160:163], v[104:107]
	v_mfma_f32_16x16x32_bf16 v[104:107], v[156:159], v[180:183], v[104:107]
	v_mfma_f32_16x16x32_bf16 v[92:95], v[156:159], v[188:191], v[92:95]
	v_mfma_f32_16x16x32_bf16 v[92:95], v[152:155], v[184:187], v[92:95]
	s_setprio 2
	s_barrier
	ds_read_b128 v[160:163], v199 offset:49152
	ds_read_b128 v[180:183], v199 offset:50176
	ds_read_b128 v[184:187], v199 offset:51200
	ds_read_b128 v[188:191], v199 offset:52224
	v_mfma_f32_16x16x32_bf16 v[84:87], v[152:155], v[192:195], v[84:87]
	v_mfma_f32_16x16x32_bf16 v[84:87], v[156:159], v[200:203], v[84:87]
	v_mfma_f32_16x16x32_bf16 v[68:71], v[156:159], v[208:211], v[68:71]
	v_mfma_f32_16x16x32_bf16 v[68:71], v[152:155], v[204:207], v[68:71]
	s_setprio 2
	s_add_i32 s24, s54, s35
	v_lshl_add_u64 v[212:213], v[212:213], 0, s[16:17]
	s_mov_b32 m0, s24
	ds_read_b128 v[192:195], v199 offset:53248
	ds_read_b128 v[200:203], v199 offset:54272
	ds_read_b128 v[204:207], v199 offset:55296
	ds_read_b128 v[208:211], v199 offset:56320
	global_load_lds_dwordx4 v[212:213], off
	s_add_i32 m0, s24, 0x2000
	s_add_u32 s24, s26, 0xb0080
	v_lshl_add_u64 v[212:213], v[214:215], 0, s[16:17]
	s_addc_u32 s25, s27, 0
	s_add_i32 s26, s55, s35
	global_load_lds_dwordx4 v[212:213], off
	s_mov_b32 m0, s26
	v_lshl_add_u64 v[212:213], s[24:25], 0, v[166:167]
	global_load_lds_dwordx4 v[212:213], off
	s_add_i32 m0, s26, 0x2000
	v_lshl_add_u64 v[212:213], s[24:25], 0, v[170:171]
	global_load_lds_dwordx4 v[212:213], off
	s_mov_b32 m0, s41
	v_lshl_add_u64 v[212:213], v[216:217], 0, s[16:17]
	global_load_lds_dwordx4 v[212:213], off
	s_mov_b32 m0, s42
	v_lshl_add_u64 v[212:213], v[218:219], 0, s[16:17]
	global_load_lds_dwordx4 v[212:213], off
	s_waitcnt vmcnt(8) lgkmcnt(0)
	s_barrier
	s_setprio 1
	v_mfma_f32_16x16x32_bf16 v[56:59], v[128:131], v[160:163], v[56:59]
	v_mfma_f32_16x16x32_bf16 v[56:59], v[132:135], v[180:183], v[56:59]
	v_mfma_f32_16x16x32_bf16 v[40:43], v[132:135], v[188:191], v[40:43]
	v_mfma_f32_16x16x32_bf16 v[40:43], v[128:131], v[184:187], v[40:43]
	v_mfma_f32_16x16x32_bf16 v[24:27], v[128:131], v[192:195], v[24:27]
	v_mfma_f32_16x16x32_bf16 v[24:27], v[132:135], v[200:203], v[24:27]
	v_mfma_f32_16x16x32_bf16 v[8:11], v[132:135], v[208:211], v[8:11]
	v_mfma_f32_16x16x32_bf16 v[8:11], v[128:131], v[204:207], v[8:11]
	v_mfma_f32_16x16x32_bf16 v[60:63], v[136:139], v[160:163], v[60:63]
	v_mfma_f32_16x16x32_bf16 v[60:63], v[140:143], v[180:183], v[60:63]
	v_mfma_f32_16x16x32_bf16 v[44:47], v[140:143], v[188:191], v[44:47]
	v_mfma_f32_16x16x32_bf16 v[44:47], v[136:139], v[184:187], v[44:47]
	v_mfma_f32_16x16x32_bf16 v[28:31], v[136:139], v[192:195], v[28:31]
	v_mfma_f32_16x16x32_bf16 v[28:31], v[140:143], v[200:203], v[28:31]
	v_mfma_f32_16x16x32_bf16 v[12:15], v[140:143], v[208:211], v[12:15]
	v_mfma_f32_16x16x32_bf16 v[12:15], v[136:139], v[204:207], v[12:15]
	v_mfma_f32_16x16x32_bf16 v[48:51], v[144:147], v[160:163], v[48:51]
	v_mfma_f32_16x16x32_bf16 v[48:51], v[148:151], v[180:183], v[48:51]
	v_mfma_f32_16x16x32_bf16 v[32:35], v[148:151], v[188:191], v[32:35]
	v_mfma_f32_16x16x32_bf16 v[32:35], v[144:147], v[184:187], v[32:35]
	v_mfma_f32_16x16x32_bf16 v[16:19], v[144:147], v[192:195], v[16:19]
	v_mfma_f32_16x16x32_bf16 v[16:19], v[148:151], v[200:203], v[16:19]
	v_mfma_f32_16x16x32_bf16 v[0:3], v[148:151], v[208:211], v[0:3]
	v_mfma_f32_16x16x32_bf16 v[0:3], v[144:147], v[204:207], v[0:3]
	v_mfma_f32_16x16x32_bf16 v[52:55], v[152:155], v[160:163], v[52:55]
	v_mfma_f32_16x16x32_bf16 v[52:55], v[156:159], v[180:183], v[52:55]
	v_mfma_f32_16x16x32_bf16 v[36:39], v[156:159], v[188:191], v[36:39]
	v_mfma_f32_16x16x32_bf16 v[36:39], v[152:155], v[184:187], v[36:39]
	s_setprio 2
	s_barrier
	v_mfma_f32_16x16x32_bf16 v[20:23], v[152:155], v[192:195], v[20:23]
	v_mfma_f32_16x16x32_bf16 v[20:23], v[156:159], v[200:203], v[20:23]
	v_mfma_f32_16x16x32_bf16 v[4:7], v[156:159], v[208:211], v[4:7]
	v_mfma_f32_16x16x32_bf16 v[4:7], v[152:155], v[204:207], v[4:7]
	s_setprio 0
	s_add_i32 s53, s53, 2
	s_add_u32 s51, s51, 0x100
	s_addc_u32 s52, s52, 0
	s_cmp_gt_u32 s53, 41
	s_mov_b64 s[24:25], s[4:5]
	s_cbranch_scc0 .LBB0_1310
